# mid_sgu epilogue: bias loads issued before the MFMA loop and the store-draining vmcnt(0) between the two output halves removed; MLA QK waits paired
# baseline (speedup 1.0000x reference)
.LBB0_277:
	s_lshl_b32 s11, s10, 7
	v_add_u32_e32 v4, s11, v102
	v_mad_i64_i32 v[2:3], s[14:15], v4, s55, v[76:77]
	global_load_dwordx4 v[62:65], v[2:3], off offset:1536 nt
	global_load_dwordx4 v[58:61], v[2:3], off offset:2048 nt
	v_add_u32_e32 v2, 16, v4
	v_mad_i64_i32 v[2:3], s[14:15], v2, s55, v[76:77]
	global_load_dwordx4 v[54:57], v[2:3], off offset:1536 nt
	global_load_dwordx4 v[50:53], v[2:3], off offset:2048 nt
	v_add_u32_e32 v2, 32, v4
	v_mad_i64_i32 v[2:3], s[14:15], v2, s55, v[76:77]
	global_load_dwordx4 v[46:49], v[2:3], off offset:1536 nt
	global_load_dwordx4 v[42:45], v[2:3], off offset:2048 nt
	v_add_u32_e32 v2, 48, v4
	v_mad_i64_i32 v[2:3], s[14:15], v2, s55, v[76:77]
	global_load_dwordx4 v[38:41], v[2:3], off offset:1536 nt
	global_load_dwordx4 v[34:37], v[2:3], off offset:2048 nt
	v_add_u32_e32 v2, 64, v4
	v_mad_i64_i32 v[2:3], s[14:15], v2, s55, v[76:77]
	global_load_dwordx4 v[30:33], v[2:3], off offset:1536 nt
	global_load_dwordx4 v[26:29], v[2:3], off offset:2048 nt
	v_add_u32_e32 v2, 0x50, v4
	v_mad_i64_i32 v[2:3], s[14:15], v2, s55, v[76:77]
	global_load_dwordx4 v[22:25], v[2:3], off offset:1536 nt
	global_load_dwordx4 v[18:21], v[2:3], off offset:2048 nt
	v_add_u32_e32 v2, 0x60, v4
	v_mad_i64_i32 v[2:3], s[14:15], v2, s55, v[76:77]
	global_load_dwordx4 v[14:17], v[2:3], off offset:1536 nt
	global_load_dwordx4 v[10:13], v[2:3], off offset:2048 nt
	v_add_u32_e32 v2, 0x70, v4
	v_mad_i64_i32 v[2:3], s[14:15], v2, s55, v[76:77]
	global_load_dwordx4 v[6:9], v[2:3], off offset:1536 nt
	s_nop 0
	global_load_dwordx4 v[2:5], v[2:3], off offset:2048 nt
	s_mov_b32 s5, 0
	s_waitcnt vmcnt(0)
	v_lshlrev_b32_e32 v98, 16, v62
	v_mul_f32_e32 v99, 0x3d372713, v98
	v_mul_f32_e32 v99, v99, v98
	v_fma_f32 v99, v99, v98, v98
	v_mul_f32_e32 v99, 0x3f4c422a, v99
	v_add_f32_e32 v99, v99, v99
	v_mul_f32_e32 v99, 0x3fb8aa3b, v99
	v_exp_f32_e32 v99, v99
	v_mul_f32_e32 v98, 0.5, v98
	v_and_b32_e32 v62, 0xffff0000, v62
	v_add_f32_e32 v99, 1.0, v99
	v_div_scale_f32 v100, s[14:15], v99, v99, 2.0
	v_rcp_f32_e32 v101, v100
	s_nop 0
	v_fma_f32 v115, -v100, v101, 1.0
	v_fmac_f32_e32 v101, v115, v101
	v_div_scale_f32 v115, vcc, 2.0, v99, 2.0
	v_mul_f32_e32 v116, v115, v101
	v_fma_f32 v117, -v100, v116, v115
	v_fmac_f32_e32 v116, v117, v101
	v_fma_f32 v100, -v100, v116, v115
	v_div_fmas_f32 v100, v100, v101, v116
	v_div_fixup_f32 v99, v100, v99, 2.0
	v_sub_f32_e32 v99, 1.0, v99
	v_add_f32_e32 v99, 1.0, v99
	v_mul_f32_e32 v98, v98, v99
	v_mul_f32_e32 v99, 0x3d372713, v62
	v_mul_f32_e32 v99, v99, v62
	v_fma_f32 v99, v99, v62, v62
	v_mul_f32_e32 v99, 0x3f4c422a, v99
	v_add_f32_e32 v99, v99, v99
	v_mul_f32_e32 v99, 0x3fb8aa3b, v99
	v_exp_f32_e32 v99, v99
	v_mul_f32_e32 v62, 0.5, v62
	v_add_f32_e32 v99, 1.0, v99
	v_div_scale_f32 v100, s[14:15], v99, v99, 2.0
	v_rcp_f32_e32 v101, v100
	s_nop 0
	v_fma_f32 v115, -v100, v101, 1.0
	v_fmac_f32_e32 v101, v115, v101
	v_div_scale_f32 v115, vcc, 2.0, v99, 2.0
	v_mul_f32_e32 v116, v115, v101
	v_fma_f32 v117, -v100, v116, v115
	v_fmac_f32_e32 v116, v117, v101
	v_fma_f32 v100, -v100, v116, v115
	v_div_fmas_f32 v100, v100, v101, v116
	v_div_fixup_f32 v99, v100, v99, 2.0
	v_sub_f32_e32 v99, 1.0, v99
	v_add_f32_e32 v99, 1.0, v99
	v_mul_f32_e32 v99, v62, v99
	v_lshlrev_b32_e32 v62, 16, v58
	v_mul_f32_e32 v100, 0x3d372713, v62
	v_mul_f32_e32 v100, v100, v62
	v_fma_f32 v100, v100, v62, v62
	v_mul_f32_e32 v100, 0x3f4c422a, v100
	v_add_f32_e32 v100, v100, v100
	v_mul_f32_e32 v100, 0x3fb8aa3b, v100
	v_exp_f32_e32 v100, v100
	v_mul_f32_e32 v62, 0.5, v62
	v_and_b32_e32 v58, 0xffff0000, v58
	v_cvt_pk_bf16_f32 v98, v98, v99
	v_add_f32_e32 v100, 1.0, v100
	v_div_scale_f32 v101, s[14:15], v100, v100, 2.0
	v_rcp_f32_e32 v115, v101
	s_nop 0
	v_fma_f32 v116, -v101, v115, 1.0
	v_fmac_f32_e32 v115, v116, v115
	v_div_scale_f32 v116, vcc, 2.0, v100, 2.0
	v_mul_f32_e32 v117, v116, v115
	v_fma_f32 v118, -v101, v117, v116
	v_fmac_f32_e32 v117, v118, v115
	v_fma_f32 v101, -v101, v117, v116
	v_div_fmas_f32 v101, v101, v115, v117
	v_div_fixup_f32 v100, v101, v100, 2.0
	v_sub_f32_e32 v100, 1.0, v100
	v_add_f32_e32 v100, 1.0, v100
	v_mul_f32_e32 v100, v62, v100
	v_mul_f32_e32 v62, 0x3d372713, v58
	v_mul_f32_e32 v62, v62, v58
	v_fma_f32 v62, v62, v58, v58
	v_mul_f32_e32 v62, 0x3f4c422a, v62
	v_add_f32_e32 v62, v62, v62
	v_mul_f32_e32 v62, 0x3fb8aa3b, v62
	v_exp_f32_e32 v62, v62
	v_mul_f32_e32 v58, 0.5, v58
	v_add_f32_e32 v62, 1.0, v62
	v_div_scale_f32 v101, s[14:15], v62, v62, 2.0
	v_rcp_f32_e32 v115, v101
	s_nop 0
	v_fma_f32 v116, -v101, v115, 1.0
	v_fmac_f32_e32 v115, v116, v115
	v_div_scale_f32 v116, vcc, 2.0, v62, 2.0
	v_mul_f32_e32 v117, v116, v115
	v_fma_f32 v118, -v101, v117, v116
	v_fmac_f32_e32 v117, v118, v115
	v_fma_f32 v101, -v101, v117, v116
	v_div_fmas_f32 v101, v101, v115, v117
	v_div_fixup_f32 v62, v101, v62, 2.0
	v_sub_f32_e32 v62, 1.0, v62
	v_add_f32_e32 v62, 1.0, v62
	v_mul_f32_e32 v101, v58, v62
	v_lshlrev_b32_e32 v58, 16, v63
	v_mul_f32_e32 v62, 0x3d372713, v58
	v_mul_f32_e32 v62, v62, v58
	v_fma_f32 v62, v62, v58, v58
	v_mul_f32_e32 v62, 0x3f4c422a, v62
	v_add_f32_e32 v62, v62, v62
	v_mul_f32_e32 v62, 0x3fb8aa3b, v62
	v_exp_f32_e32 v62, v62
	v_mul_f32_e32 v58, 0.5, v58
	v_add_f32_e32 v62, 1.0, v62
	v_div_scale_f32 v115, s[14:15], v62, v62, 2.0
	v_rcp_f32_e32 v116, v115
	s_nop 0
	v_fma_f32 v117, -v115, v116, 1.0
	v_fmac_f32_e32 v116, v117, v116
	v_div_scale_f32 v117, vcc, 2.0, v62, 2.0
	v_mul_f32_e32 v118, v117, v116
	v_fma_f32 v119, -v115, v118, v117
	v_fmac_f32_e32 v118, v119, v116
	v_fma_f32 v115, -v115, v118, v117
	v_div_fmas_f32 v115, v115, v116, v118
	v_div_fixup_f32 v62, v115, v62, 2.0
	v_sub_f32_e32 v62, 1.0, v62
	v_add_f32_e32 v62, 1.0, v62
	v_mul_f32_e32 v115, v58, v62
	v_and_b32_e32 v58, 0xffff0000, v63
	v_mul_f32_e32 v62, 0x3d372713, v58
	v_mul_f32_e32 v62, v62, v58
	v_fma_f32 v62, v62, v58, v58
	v_mul_f32_e32 v62, 0x3f4c422a, v62
	v_add_f32_e32 v62, v62, v62
	v_mul_f32_e32 v62, 0x3fb8aa3b, v62
	v_exp_f32_e32 v62, v62
	v_mul_f32_e32 v58, 0.5, v58
	v_add_f32_e32 v62, 1.0, v62
	v_div_scale_f32 v63, s[14:15], v62, v62, 2.0
	v_rcp_f32_e32 v116, v63
	s_nop 0
	v_fma_f32 v117, -v63, v116, 1.0
	v_fmac_f32_e32 v116, v117, v116
	v_div_scale_f32 v117, vcc, 2.0, v62, 2.0
	v_mul_f32_e32 v118, v117, v116
	v_fma_f32 v119, -v63, v118, v117
	v_fmac_f32_e32 v118, v119, v116
	v_fma_f32 v63, -v63, v118, v117
	v_div_fmas_f32 v63, v63, v116, v118
	v_div_fixup_f32 v62, v63, v62, 2.0
	v_sub_f32_e32 v62, 1.0, v62
	v_add_f32_e32 v62, 1.0, v62
	v_mul_f32_e32 v116, v58, v62
	v_lshlrev_b32_e32 v58, 16, v64
	v_mul_f32_e32 v62, 0x3d372713, v58
	v_mul_f32_e32 v62, v62, v58
	v_fma_f32 v62, v62, v58, v58
	v_mul_f32_e32 v62, 0x3f4c422a, v62
	v_add_f32_e32 v62, v62, v62
	v_mul_f32_e32 v62, 0x3fb8aa3b, v62
	v_exp_f32_e32 v62, v62
	v_mul_f32_e32 v58, 0.5, v58
	v_add_f32_e32 v62, 1.0, v62
	v_div_scale_f32 v63, s[14:15], v62, v62, 2.0
	v_rcp_f32_e32 v117, v63
	s_nop 0
	v_fma_f32 v118, -v63, v117, 1.0
	v_fmac_f32_e32 v117, v118, v117
	v_div_scale_f32 v118, vcc, 2.0, v62, 2.0
	v_mul_f32_e32 v119, v118, v117
	v_fma_f32 v120, -v63, v119, v118
	v_fmac_f32_e32 v119, v120, v117
	v_fma_f32 v63, -v63, v119, v118
	v_div_fmas_f32 v63, v63, v117, v119
	v_div_fixup_f32 v62, v63, v62, 2.0
	v_sub_f32_e32 v62, 1.0, v62
	v_add_f32_e32 v62, 1.0, v62
	v_mul_f32_e32 v117, v58, v62
	v_and_b32_e32 v58, 0xffff0000, v64
	v_mul_f32_e32 v62, 0x3d372713, v58
	v_mul_f32_e32 v62, v62, v58
	v_fma_f32 v62, v62, v58, v58
	v_mul_f32_e32 v62, 0x3f4c422a, v62
	v_add_f32_e32 v62, v62, v62
	v_mul_f32_e32 v62, 0x3fb8aa3b, v62
	v_exp_f32_e32 v62, v62
	v_mul_f32_e32 v58, 0.5, v58
	v_add_f32_e32 v62, 1.0, v62
	v_div_scale_f32 v63, s[14:15], v62, v62, 2.0
	v_rcp_f32_e32 v64, v63
	s_nop 0
	v_fma_f32 v118, -v63, v64, 1.0
	v_fmac_f32_e32 v64, v118, v64
	v_div_scale_f32 v118, vcc, 2.0, v62, 2.0
	v_mul_f32_e32 v119, v118, v64
	v_fma_f32 v120, -v63, v119, v118
	v_fmac_f32_e32 v119, v120, v64
	v_fma_f32 v63, -v63, v119, v118
	v_div_fmas_f32 v63, v63, v64, v119
	v_div_fixup_f32 v62, v63, v62, 2.0
	v_sub_f32_e32 v62, 1.0, v62
	v_add_f32_e32 v62, 1.0, v62
	v_mul_f32_e32 v64, v58, v62
	v_lshlrev_b32_e32 v58, 16, v65
	v_mul_f32_e32 v62, 0x3d372713, v58
	v_mul_f32_e32 v62, v62, v58
	v_fma_f32 v62, v62, v58, v58
	v_mul_f32_e32 v62, 0x3f4c422a, v62
	v_add_f32_e32 v62, v62, v62
	v_mul_f32_e32 v62, 0x3fb8aa3b, v62
	v_exp_f32_e32 v62, v62
	v_mul_f32_e32 v58, 0.5, v58
	v_add_f32_e32 v62, 1.0, v62
	v_div_scale_f32 v63, s[14:15], v62, v62, 2.0
	v_rcp_f32_e32 v118, v63
	s_nop 0
	v_fma_f32 v119, -v63, v118, 1.0
	v_fmac_f32_e32 v118, v119, v118
	v_div_scale_f32 v119, vcc, 2.0, v62, 2.0
	v_mul_f32_e32 v120, v119, v118
	v_fma_f32 v121, -v63, v120, v119
	v_fmac_f32_e32 v120, v121, v118
	v_fma_f32 v63, -v63, v120, v119
	v_div_fmas_f32 v63, v63, v118, v120
	v_div_fixup_f32 v62, v63, v62, 2.0
	v_sub_f32_e32 v62, 1.0, v62
	v_add_f32_e32 v62, 1.0, v62
	v_mul_f32_e32 v118, v58, v62
	v_and_b32_e32 v58, 0xffff0000, v65
	v_mul_f32_e32 v62, 0x3d372713, v58
	v_mul_f32_e32 v62, v62, v58
	v_fma_f32 v62, v62, v58, v58
	v_mul_f32_e32 v62, 0x3f4c422a, v62
	v_add_f32_e32 v62, v62, v62
	v_mul_f32_e32 v62, 0x3fb8aa3b, v62
	v_exp_f32_e32 v62, v62
	v_mul_f32_e32 v58, 0.5, v58
	v_add_f32_e32 v62, 1.0, v62
	v_div_scale_f32 v63, s[14:15], v62, v62, 2.0
	v_rcp_f32_e32 v65, v63
	s_nop 0
	v_fma_f32 v119, -v63, v65, 1.0
	v_fmac_f32_e32 v65, v119, v65
	v_div_scale_f32 v119, vcc, 2.0, v62, 2.0
	v_mul_f32_e32 v120, v119, v65
	v_fma_f32 v121, -v63, v120, v119
	v_fmac_f32_e32 v120, v121, v65
	v_fma_f32 v63, -v63, v120, v119
	v_div_fmas_f32 v63, v63, v65, v120
	v_div_fixup_f32 v62, v63, v62, 2.0
	v_sub_f32_e32 v62, 1.0, v62
	v_add_f32_e32 v62, 1.0, v62
	v_mul_f32_e32 v65, v58, v62
	v_and_b32_e32 v58, 0xffff0000, v59
	v_lshlrev_b32_e32 v59, 16, v59
	v_mul_f32_e32 v62, 0x3d372713, v59
	v_mul_f32_e32 v62, v62, v59
	v_mov_b32_e32 v63, v59
	v_fmac_f32_e32 v63, v62, v63
	v_mul_f32_e32 v62, 0x3f4c422a, v63
	v_add_f32_e32 v62, v62, v62
	v_mul_f32_e32 v62, 0x3fb8aa3b, v62
	v_exp_f32_e32 v63, v62
	v_mul_f32_e32 v62, 0x3d372713, v58
	v_mul_f32_e32 v62, v62, v58
	v_mov_b32_e32 v120, v58
	v_fmac_f32_e32 v120, v62, v120
	v_mul_f32_e32 v62, 0x3f4c422a, v120
	v_add_f32_e32 v62, v62, v62
	v_mul_f32_e32 v62, 0x3fb8aa3b, v62
	v_exp_f32_e32 v62, v62
	v_pk_mul_f32 v[58:59], v[58:59], 0.5 op_sel_hi:[1,0]
	v_mul_f32_e32 v119, v101, v101
	v_fmac_f32_e32 v119, v100, v100
	v_pk_add_f32 v[62:63], v[62:63], 1.0 op_sel_hi:[1,0]
	s_nop 0
	v_div_scale_f32 v120, s[14:15], v63, v63, 2.0
	v_rcp_f32_e32 v121, v120
	s_nop 0
	v_fma_f32 v122, -v120, v121, 1.0
	v_fmac_f32_e32 v121, v122, v121
	v_div_scale_f32 v122, vcc, 2.0, v63, 2.0
	v_mul_f32_e32 v123, v122, v121
	v_fma_f32 v124, -v120, v123, v122
	v_fmac_f32_e32 v123, v124, v121
	v_fma_f32 v120, -v120, v123, v122
	v_div_fmas_f32 v120, v120, v121, v123
	v_div_fixup_f32 v63, v120, v63, 2.0
	v_div_scale_f32 v120, s[14:15], v62, v62, 2.0
	v_rcp_f32_e32 v121, v120
	s_nop 0
	v_fma_f32 v122, -v120, v121, 1.0
	v_fmac_f32_e32 v121, v122, v121
	v_div_scale_f32 v122, vcc, 2.0, v62, 2.0
	v_mul_f32_e32 v123, v122, v121
	v_fma_f32 v124, -v120, v123, v122
	v_fmac_f32_e32 v123, v124, v121
	v_fma_f32 v120, -v120, v123, v122
	v_div_fmas_f32 v120, v120, v121, v123
	v_div_fixup_f32 v62, v120, v62, 2.0
	v_pk_add_f32 v[62:63], v[62:63], 1.0 op_sel_hi:[1,0] neg_lo:[1,0] neg_hi:[1,0]
	s_nop 0
	v_pk_add_f32 v[62:63], v[62:63], 1.0 op_sel_hi:[1,0]
	s_nop 0
	v_pk_mul_f32 v[58:59], v[58:59], v[62:63]
	s_nop 0
	v_pk_mul_f32 v[62:63], v[58:59], v[58:59]
	s_nop 0
	v_add_f32_e32 v63, v63, v119
	v_add_f32_e32 v119, v62, v63
	v_lshlrev_b32_e32 v63, 16, v60
	v_and_b32_e32 v62, 0xffff0000, v60
	v_mul_f32_e32 v60, 0x3d372713, v63
	v_mul_f32_e32 v60, v60, v63
	v_mov_b32_e32 v120, v63
	v_fmac_f32_e32 v120, v60, v120
	v_mul_f32_e32 v60, 0x3f4c422a, v120
	v_add_f32_e32 v60, v60, v60
	v_mul_f32_e32 v60, 0x3fb8aa3b, v60
	v_exp_f32_e32 v121, v60
	v_mul_f32_e32 v60, 0x3d372713, v62
	v_mul_f32_e32 v60, v60, v62
	v_mov_b32_e32 v120, v62
	v_fmac_f32_e32 v120, v60, v120
	v_mul_f32_e32 v60, 0x3f4c422a, v120
	v_add_f32_e32 v60, v60, v60
	v_mul_f32_e32 v60, 0x3fb8aa3b, v60
	v_exp_f32_e32 v120, v60
	v_pk_mul_f32 v[62:63], v[62:63], 0.5 op_sel_hi:[1,0]
	v_pk_add_f32 v[120:121], v[120:121], 1.0 op_sel_hi:[1,0]
	s_nop 0
	v_div_scale_f32 v60, s[14:15], v121, v121, 2.0
	v_rcp_f32_e32 v122, v60
	s_nop 0
	v_fma_f32 v123, -v60, v122, 1.0
	v_fmac_f32_e32 v122, v123, v122
	v_div_scale_f32 v123, vcc, 2.0, v121, 2.0
	v_mul_f32_e32 v124, v123, v122
	v_fma_f32 v125, -v60, v124, v123
	v_fmac_f32_e32 v124, v125, v122
	v_fma_f32 v60, -v60, v124, v123
	v_div_fmas_f32 v60, v60, v122, v124
	v_div_fixup_f32 v121, v60, v121, 2.0
	v_div_scale_f32 v60, s[14:15], v120, v120, 2.0
	v_rcp_f32_e32 v122, v60
	s_nop 0
	v_fma_f32 v123, -v60, v122, 1.0
	v_fmac_f32_e32 v122, v123, v122
	v_div_scale_f32 v123, vcc, 2.0, v120, 2.0
	v_mul_f32_e32 v124, v123, v122
	v_fma_f32 v125, -v60, v124, v123
	v_fmac_f32_e32 v124, v125, v122
	v_fma_f32 v60, -v60, v124, v123
	v_div_fmas_f32 v60, v60, v122, v124
	v_div_fixup_f32 v120, v60, v120, 2.0
	v_pk_add_f32 v[120:121], v[120:121], 1.0 op_sel_hi:[1,0] neg_lo:[1,0] neg_hi:[1,0]
	s_nop 0
	v_pk_add_f32 v[120:121], v[120:121], 1.0 op_sel_hi:[1,0]
	s_nop 0
	v_pk_mul_f32 v[62:63], v[62:63], v[120:121]
	s_nop 0
	v_pk_mul_f32 v[120:121], v[62:63], v[62:63]
	s_nop 0
	v_add_f32_e32 v60, v121, v119
	v_add_f32_e32 v119, v120, v60
	v_and_b32_e32 v60, 0xffff0000, v61
	v_lshlrev_b32_e32 v61, 16, v61
	v_mul_f32_e32 v120, 0x3d372713, v61
	v_mul_f32_e32 v120, v120, v61
	v_mov_b32_e32 v121, v61
	v_fmac_f32_e32 v121, v120, v121
	v_mul_f32_e32 v120, 0x3f4c422a, v121
	v_add_f32_e32 v120, v120, v120
	v_mul_f32_e32 v120, 0x3fb8aa3b, v120
	v_exp_f32_e32 v121, v120
	v_mul_f32_e32 v120, 0x3d372713, v60
	v_mul_f32_e32 v120, v120, v60
	v_mov_b32_e32 v122, v60
	v_fmac_f32_e32 v122, v120, v122
	v_mul_f32_e32 v120, 0x3f4c422a, v122
	v_add_f32_e32 v120, v120, v120
	v_mul_f32_e32 v120, 0x3fb8aa3b, v120
	v_exp_f32_e32 v120, v120
	v_pk_mul_f32 v[60:61], v[60:61], 0.5 op_sel_hi:[1,0]
	v_pk_add_f32 v[120:121], v[120:121], 1.0 op_sel_hi:[1,0]
	s_nop 0
	v_div_scale_f32 v122, s[14:15], v121, v121, 2.0
	v_rcp_f32_e32 v123, v122
	s_nop 0
	v_fma_f32 v124, -v122, v123, 1.0
	v_fmac_f32_e32 v123, v124, v123
	v_div_scale_f32 v124, vcc, 2.0, v121, 2.0
	v_mul_f32_e32 v125, v124, v123
	v_fma_f32 v126, -v122, v125, v124
	v_fmac_f32_e32 v125, v126, v123
	v_fma_f32 v122, -v122, v125, v124
	v_div_fmas_f32 v122, v122, v123, v125
	v_div_fixup_f32 v121, v122, v121, 2.0
	v_div_scale_f32 v122, s[14:15], v120, v120, 2.0
	v_rcp_f32_e32 v123, v122
	s_nop 0
	v_fma_f32 v124, -v122, v123, 1.0
	v_fmac_f32_e32 v123, v124, v123
	v_div_scale_f32 v124, vcc, 2.0, v120, 2.0
	v_mul_f32_e32 v125, v124, v123
	v_fma_f32 v126, -v122, v125, v124
	v_fmac_f32_e32 v125, v126, v123
	v_fma_f32 v122, -v122, v125, v124
	v_div_fmas_f32 v122, v122, v123, v125
	v_div_fixup_f32 v120, v122, v120, 2.0
	v_pk_add_f32 v[120:121], v[120:121], 1.0 op_sel_hi:[1,0] neg_lo:[1,0] neg_hi:[1,0]
	s_nop 0
	v_pk_add_f32 v[120:121], v[120:121], 1.0 op_sel_hi:[1,0]
	s_nop 0
	v_pk_mul_f32 v[120:121], v[60:61], v[120:121]
	s_nop 0
	v_pk_mul_f32 v[60:61], v[120:121], v[120:121]
	s_nop 0
	v_add_f32_e32 v61, v61, v119
	v_add_f32_e32 v60, v60, v61
	ds_bpermute_b32 v61, v106, v60
	s_waitcnt lgkmcnt(0)
	v_add_f32_e32 v60, v60, v61
	ds_bpermute_b32 v61, v107, v60
	s_waitcnt lgkmcnt(0)
	v_add_f32_e32 v60, v60, v61
	ds_bpermute_b32 v61, v108, v60
	s_waitcnt lgkmcnt(0)
	v_add_f32_e32 v60, v60, v61
	ds_bpermute_b32 v61, v109, v60
	s_waitcnt lgkmcnt(0)
	v_add_f32_e32 v60, v60, v61
	ds_bpermute_b32 v61, v110, v60
	s_waitcnt lgkmcnt(0)
	v_add_f32_e32 v60, v60, v61
	v_fmamk_f32 v60, v60, 0x3b800000, v243
	v_cmp_gt_f32_e32 vcc, s3, v60
	v_mul_f32_e32 v61, 0x4b800000, v60
	s_nop 0
	v_cndmask_b32_e32 v60, v60, v61, vcc
	v_rsq_f32_e32 v60, v60
	s_nop 0
	v_mul_f32_e32 v61, 0x45800000, v60
	v_cndmask_b32_e32 v119, v60, v61, vcc
	v_mul_f32_e32 v60, v100, v119
	v_mul_f32_e32 v61, v101, v119
	v_mul_f32_e32 v58, v58, v119
	v_mul_f32_e32 v60, v70, v60
	v_mul_f32_e32 v61, v71, v61
	v_mul_f32_e32 v59, v59, v119
	v_mul_f32_e32 v58, v73, v58
	v_cvt_pk_bf16_f32 v60, v60, v61
	v_cvt_pk_bf16_f32 v99, v115, v116
	v_mul_f32_e32 v59, v72, v59
	v_cvt_pk_bf16_f32 v61, v59, v58
	v_mul_f32_e32 v58, v63, v119
	v_mul_f32_e32 v58, v66, v58
	v_mul_f32_e32 v59, v62, v119
	v_cvt_pk_bf16_f32 v100, v117, v64
	v_mul_f32_e32 v59, v67, v59
	v_cvt_pk_bf16_f32 v62, v58, v59
	v_mul_f32_e32 v58, v121, v119
	v_mul_f32_e32 v58, v68, v58
	v_mul_f32_e32 v59, v120, v119
	v_cvt_pk_bf16_f32 v101, v118, v65
	v_mul_f32_e32 v59, v69, v59
	v_cvt_pk_bf16_f32 v63, v58, v59
	v_lshlrev_b32_e32 v58, 16, v54
	v_mul_f32_e32 v59, 0x3d372713, v58
	v_mul_f32_e32 v59, v59, v58
	v_fma_f32 v59, v59, v58, v58
	v_mul_f32_e32 v59, 0x3f4c422a, v59
	v_add_f32_e32 v59, v59, v59
	v_mul_f32_e32 v59, 0x3fb8aa3b, v59
	v_exp_f32_e32 v59, v59
	ds_write_b128 v111, v[98:101]
	ds_write_b128 v112, v[60:63]
	v_mul_f32_e32 v58, 0.5, v58
	v_and_b32_e32 v54, 0xffff0000, v54
	v_add_f32_e32 v59, 1.0, v59
	v_div_scale_f32 v60, s[14:15], v59, v59, 2.0
	v_rcp_f32_e32 v61, v60
	s_nop 0
	v_fma_f32 v62, -v60, v61, 1.0
	v_fmac_f32_e32 v61, v62, v61
	v_div_scale_f32 v62, vcc, 2.0, v59, 2.0
	v_mul_f32_e32 v63, v62, v61
	v_fma_f32 v64, -v60, v63, v62
	v_fmac_f32_e32 v63, v64, v61
	v_fma_f32 v60, -v60, v63, v62
	v_div_fmas_f32 v60, v60, v61, v63
	v_div_fixup_f32 v59, v60, v59, 2.0
	v_sub_f32_e32 v59, 1.0, v59
	v_add_f32_e32 v59, 1.0, v59
	v_mul_f32_e32 v58, v58, v59
	v_mul_f32_e32 v59, 0x3d372713, v54
	v_mul_f32_e32 v59, v59, v54
	v_fma_f32 v59, v59, v54, v54
	v_mul_f32_e32 v59, 0x3f4c422a, v59
	v_add_f32_e32 v59, v59, v59
	v_mul_f32_e32 v59, 0x3fb8aa3b, v59
	v_exp_f32_e32 v59, v59
	v_mul_f32_e32 v54, 0.5, v54
	v_add_f32_e32 v59, 1.0, v59
	v_div_scale_f32 v60, s[14:15], v59, v59, 2.0
	v_rcp_f32_e32 v61, v60
	s_nop 0
	v_fma_f32 v62, -v60, v61, 1.0
	v_fmac_f32_e32 v61, v62, v61
	v_div_scale_f32 v62, vcc, 2.0, v59, 2.0
	v_mul_f32_e32 v63, v62, v61
	v_fma_f32 v64, -v60, v63, v62
	v_fmac_f32_e32 v63, v64, v61
	v_fma_f32 v60, -v60, v63, v62
	v_div_fmas_f32 v60, v60, v61, v63
	v_div_fixup_f32 v59, v60, v59, 2.0
	v_sub_f32_e32 v59, 1.0, v59
	v_add_f32_e32 v59, 1.0, v59
	v_mul_f32_e32 v59, v54, v59
	v_lshlrev_b32_e32 v54, 16, v50
	v_mul_f32_e32 v60, 0x3d372713, v54
	v_mul_f32_e32 v60, v60, v54
	v_fma_f32 v60, v60, v54, v54
	v_mul_f32_e32 v60, 0x3f4c422a, v60
	v_add_f32_e32 v60, v60, v60
	v_mul_f32_e32 v60, 0x3fb8aa3b, v60
	v_exp_f32_e32 v60, v60
	v_mul_f32_e32 v54, 0.5, v54
	v_and_b32_e32 v50, 0xffff0000, v50
	v_cvt_pk_bf16_f32 v58, v58, v59
	v_add_f32_e32 v60, 1.0, v60
	v_div_scale_f32 v61, s[14:15], v60, v60, 2.0
	v_rcp_f32_e32 v62, v61
	s_nop 0
	v_fma_f32 v63, -v61, v62, 1.0
	v_fmac_f32_e32 v62, v63, v62
	v_div_scale_f32 v63, vcc, 2.0, v60, 2.0
	v_mul_f32_e32 v64, v63, v62
	v_fma_f32 v65, -v61, v64, v63
	v_fmac_f32_e32 v64, v65, v62
	v_fma_f32 v61, -v61, v64, v63
	v_div_fmas_f32 v61, v61, v62, v64
	v_div_fixup_f32 v60, v61, v60, 2.0
	v_sub_f32_e32 v60, 1.0, v60
	v_add_f32_e32 v60, 1.0, v60
	v_mul_f32_e32 v60, v54, v60
	v_mul_f32_e32 v54, 0x3d372713, v50
	v_mul_f32_e32 v54, v54, v50
	v_fma_f32 v54, v54, v50, v50
	v_mul_f32_e32 v54, 0x3f4c422a, v54
	v_add_f32_e32 v54, v54, v54
	v_mul_f32_e32 v54, 0x3fb8aa3b, v54
	v_exp_f32_e32 v54, v54
	v_mul_f32_e32 v50, 0.5, v50
	v_add_f32_e32 v54, 1.0, v54
	v_div_scale_f32 v61, s[14:15], v54, v54, 2.0
	v_rcp_f32_e32 v62, v61
	s_nop 0
	v_fma_f32 v63, -v61, v62, 1.0
	v_fmac_f32_e32 v62, v63, v62
	v_div_scale_f32 v63, vcc, 2.0, v54, 2.0
	v_mul_f32_e32 v64, v63, v62
	v_fma_f32 v65, -v61, v64, v63
	v_fmac_f32_e32 v64, v65, v62
	v_fma_f32 v61, -v61, v64, v63
	v_div_fmas_f32 v61, v61, v62, v64
	v_div_fixup_f32 v54, v61, v54, 2.0
	v_sub_f32_e32 v54, 1.0, v54
	v_add_f32_e32 v54, 1.0, v54
	v_mul_f32_e32 v61, v50, v54
	v_lshlrev_b32_e32 v50, 16, v55
	v_mul_f32_e32 v54, 0x3d372713, v50
	v_mul_f32_e32 v54, v54, v50
	v_fma_f32 v54, v54, v50, v50
	v_mul_f32_e32 v54, 0x3f4c422a, v54
	v_add_f32_e32 v54, v54, v54
	v_mul_f32_e32 v54, 0x3fb8aa3b, v54
	v_exp_f32_e32 v54, v54
	v_mul_f32_e32 v50, 0.5, v50
	v_add_f32_e32 v54, 1.0, v54
	v_div_scale_f32 v62, s[14:15], v54, v54, 2.0
	v_rcp_f32_e32 v63, v62
	s_nop 0
	v_fma_f32 v64, -v62, v63, 1.0
	v_fmac_f32_e32 v63, v64, v63
	v_div_scale_f32 v64, vcc, 2.0, v54, 2.0
	v_mul_f32_e32 v65, v64, v63
	v_fma_f32 v98, -v62, v65, v64
	v_fmac_f32_e32 v65, v98, v63
	v_fma_f32 v62, -v62, v65, v64
	v_div_fmas_f32 v62, v62, v63, v65
	v_div_fixup_f32 v54, v62, v54, 2.0
	v_sub_f32_e32 v54, 1.0, v54
	v_add_f32_e32 v54, 1.0, v54
	v_mul_f32_e32 v62, v50, v54
	v_and_b32_e32 v50, 0xffff0000, v55
	v_mul_f32_e32 v54, 0x3d372713, v50
	v_mul_f32_e32 v54, v54, v50
	v_fma_f32 v54, v54, v50, v50
	v_mul_f32_e32 v54, 0x3f4c422a, v54
	v_add_f32_e32 v54, v54, v54
	v_mul_f32_e32 v54, 0x3fb8aa3b, v54
	v_exp_f32_e32 v54, v54
	v_mul_f32_e32 v50, 0.5, v50
	v_add_f32_e32 v54, 1.0, v54
	v_div_scale_f32 v55, s[14:15], v54, v54, 2.0
	v_rcp_f32_e32 v63, v55
	s_nop 0
	v_fma_f32 v64, -v55, v63, 1.0
	v_fmac_f32_e32 v63, v64, v63
	v_div_scale_f32 v64, vcc, 2.0, v54, 2.0
	v_mul_f32_e32 v65, v64, v63
	v_fma_f32 v98, -v55, v65, v64
	v_fmac_f32_e32 v65, v98, v63
	v_fma_f32 v55, -v55, v65, v64
	v_div_fmas_f32 v55, v55, v63, v65
	v_div_fixup_f32 v54, v55, v54, 2.0
	v_sub_f32_e32 v54, 1.0, v54
	v_add_f32_e32 v54, 1.0, v54
	v_mul_f32_e32 v63, v50, v54
	v_lshlrev_b32_e32 v50, 16, v56
	v_mul_f32_e32 v54, 0x3d372713, v50
	v_mul_f32_e32 v54, v54, v50
	v_fma_f32 v54, v54, v50, v50
	v_mul_f32_e32 v54, 0x3f4c422a, v54
	v_add_f32_e32 v54, v54, v54
	v_mul_f32_e32 v54, 0x3fb8aa3b, v54
	v_exp_f32_e32 v54, v54
	v_mul_f32_e32 v50, 0.5, v50
	v_add_f32_e32 v54, 1.0, v54
	v_div_scale_f32 v55, s[14:15], v54, v54, 2.0
	v_rcp_f32_e32 v64, v55
	s_nop 0
	v_fma_f32 v65, -v55, v64, 1.0
	v_fmac_f32_e32 v64, v65, v64
	v_div_scale_f32 v65, vcc, 2.0, v54, 2.0
	v_mul_f32_e32 v98, v65, v64
	v_fma_f32 v99, -v55, v98, v65
	v_fmac_f32_e32 v98, v99, v64
	v_fma_f32 v55, -v55, v98, v65
	v_div_fmas_f32 v55, v55, v64, v98
	v_div_fixup_f32 v54, v55, v54, 2.0
	v_sub_f32_e32 v54, 1.0, v54
	v_add_f32_e32 v54, 1.0, v54
	v_mul_f32_e32 v64, v50, v54
	v_and_b32_e32 v50, 0xffff0000, v56
	v_mul_f32_e32 v54, 0x3d372713, v50
	v_mul_f32_e32 v54, v54, v50
	v_fma_f32 v54, v54, v50, v50
	v_mul_f32_e32 v54, 0x3f4c422a, v54
	v_add_f32_e32 v54, v54, v54
	v_mul_f32_e32 v54, 0x3fb8aa3b, v54
	v_exp_f32_e32 v54, v54
	v_mul_f32_e32 v50, 0.5, v50
	v_add_f32_e32 v54, 1.0, v54
	v_div_scale_f32 v55, s[14:15], v54, v54, 2.0
	v_rcp_f32_e32 v56, v55
	s_nop 0
	v_fma_f32 v65, -v55, v56, 1.0
	v_fmac_f32_e32 v56, v65, v56
	v_div_scale_f32 v65, vcc, 2.0, v54, 2.0
	v_mul_f32_e32 v98, v65, v56
	v_fma_f32 v99, -v55, v98, v65
	v_fmac_f32_e32 v98, v99, v56
	v_fma_f32 v55, -v55, v98, v65
	v_div_fmas_f32 v55, v55, v56, v98
	v_div_fixup_f32 v54, v55, v54, 2.0
	v_sub_f32_e32 v54, 1.0, v54
	v_add_f32_e32 v54, 1.0, v54
	v_mul_f32_e32 v56, v50, v54
	v_lshlrev_b32_e32 v50, 16, v57
	v_mul_f32_e32 v54, 0x3d372713, v50
	v_mul_f32_e32 v54, v54, v50
	v_fma_f32 v54, v54, v50, v50
	v_mul_f32_e32 v54, 0x3f4c422a, v54
	v_add_f32_e32 v54, v54, v54
	v_mul_f32_e32 v54, 0x3fb8aa3b, v54
	v_exp_f32_e32 v54, v54
	v_mul_f32_e32 v50, 0.5, v50
	v_add_f32_e32 v54, 1.0, v54
	v_div_scale_f32 v55, s[14:15], v54, v54, 2.0
	v_rcp_f32_e32 v65, v55
	s_nop 0
	v_fma_f32 v98, -v55, v65, 1.0
	v_fmac_f32_e32 v65, v98, v65
	v_div_scale_f32 v98, vcc, 2.0, v54, 2.0
	v_mul_f32_e32 v99, v98, v65
	v_fma_f32 v100, -v55, v99, v98
	v_fmac_f32_e32 v99, v100, v65
	v_fma_f32 v55, -v55, v99, v98
	v_div_fmas_f32 v55, v55, v65, v99
	v_div_fixup_f32 v54, v55, v54, 2.0
	v_sub_f32_e32 v54, 1.0, v54
	v_add_f32_e32 v54, 1.0, v54
	v_mul_f32_e32 v65, v50, v54
	v_and_b32_e32 v50, 0xffff0000, v57
	v_mul_f32_e32 v54, 0x3d372713, v50
	v_mul_f32_e32 v54, v54, v50
	v_fma_f32 v54, v54, v50, v50
	v_mul_f32_e32 v54, 0x3f4c422a, v54
	v_add_f32_e32 v54, v54, v54
	v_mul_f32_e32 v54, 0x3fb8aa3b, v54
	v_exp_f32_e32 v54, v54
	v_mul_f32_e32 v50, 0.5, v50
	v_add_f32_e32 v54, 1.0, v54
	v_div_scale_f32 v55, s[14:15], v54, v54, 2.0
	v_rcp_f32_e32 v57, v55
	s_nop 0
	v_fma_f32 v98, -v55, v57, 1.0
	v_fmac_f32_e32 v57, v98, v57
	v_div_scale_f32 v98, vcc, 2.0, v54, 2.0
	v_mul_f32_e32 v99, v98, v57
	v_fma_f32 v100, -v55, v99, v98
	v_fmac_f32_e32 v99, v100, v57
	v_fma_f32 v55, -v55, v99, v98
	v_div_fmas_f32 v55, v55, v57, v99
	v_div_fixup_f32 v54, v55, v54, 2.0
	v_sub_f32_e32 v54, 1.0, v54
	v_add_f32_e32 v54, 1.0, v54
	v_mul_f32_e32 v57, v50, v54
	v_and_b32_e32 v50, 0xffff0000, v51
	v_lshlrev_b32_e32 v51, 16, v51
	v_mul_f32_e32 v54, 0x3d372713, v51
	v_mul_f32_e32 v54, v54, v51
	v_mov_b32_e32 v55, v51
	v_fmac_f32_e32 v55, v54, v55
	v_mul_f32_e32 v54, 0x3f4c422a, v55
	v_add_f32_e32 v54, v54, v54
	v_mul_f32_e32 v54, 0x3fb8aa3b, v54
	v_exp_f32_e32 v55, v54
	v_mul_f32_e32 v54, 0x3d372713, v50
	v_mul_f32_e32 v54, v54, v50
	v_mov_b32_e32 v99, v50
	v_fmac_f32_e32 v99, v54, v99
	v_mul_f32_e32 v54, 0x3f4c422a, v99
	v_add_f32_e32 v54, v54, v54
	v_mul_f32_e32 v54, 0x3fb8aa3b, v54
	v_exp_f32_e32 v54, v54
	v_pk_mul_f32 v[50:51], v[50:51], 0.5 op_sel_hi:[1,0]
	v_mul_f32_e32 v98, v61, v61
	v_fmac_f32_e32 v98, v60, v60
	v_pk_add_f32 v[54:55], v[54:55], 1.0 op_sel_hi:[1,0]
	s_nop 0
	v_div_scale_f32 v99, s[14:15], v55, v55, 2.0
	v_rcp_f32_e32 v100, v99
	s_nop 0
	v_fma_f32 v101, -v99, v100, 1.0
	v_fmac_f32_e32 v100, v101, v100
	v_div_scale_f32 v101, vcc, 2.0, v55, 2.0
	v_mul_f32_e32 v115, v101, v100
	v_fma_f32 v116, -v99, v115, v101
	v_fmac_f32_e32 v115, v116, v100
	v_fma_f32 v99, -v99, v115, v101
	v_div_fmas_f32 v99, v99, v100, v115
	v_div_fixup_f32 v55, v99, v55, 2.0
	v_div_scale_f32 v99, s[14:15], v54, v54, 2.0
	v_rcp_f32_e32 v100, v99
	s_nop 0
	v_fma_f32 v101, -v99, v100, 1.0
	v_fmac_f32_e32 v100, v101, v100
	v_div_scale_f32 v101, vcc, 2.0, v54, 2.0
	v_mul_f32_e32 v115, v101, v100
	v_fma_f32 v116, -v99, v115, v101
	v_fmac_f32_e32 v115, v116, v100
	v_fma_f32 v99, -v99, v115, v101
	v_div_fmas_f32 v99, v99, v100, v115
	v_div_fixup_f32 v54, v99, v54, 2.0
	v_pk_add_f32 v[54:55], v[54:55], 1.0 op_sel_hi:[1,0] neg_lo:[1,0] neg_hi:[1,0]
	s_nop 0
	v_pk_add_f32 v[54:55], v[54:55], 1.0 op_sel_hi:[1,0]
	s_nop 0
	v_pk_mul_f32 v[50:51], v[50:51], v[54:55]
	s_nop 0
	v_pk_mul_f32 v[54:55], v[50:51], v[50:51]
	s_nop 0
	v_add_f32_e32 v55, v55, v98
	v_add_f32_e32 v100, v54, v55
	v_lshlrev_b32_e32 v55, 16, v52
	v_and_b32_e32 v54, 0xffff0000, v52
	v_mul_f32_e32 v52, 0x3d372713, v55
	v_mul_f32_e32 v52, v52, v55
	v_mov_b32_e32 v98, v55
	v_fmac_f32_e32 v98, v52, v98
	v_mul_f32_e32 v52, 0x3f4c422a, v98
	v_add_f32_e32 v52, v52, v52
	v_mul_f32_e32 v52, 0x3fb8aa3b, v52
	v_exp_f32_e32 v99, v52
	v_mul_f32_e32 v52, 0x3d372713, v54
	v_mul_f32_e32 v52, v52, v54
	v_mov_b32_e32 v98, v54
	v_fmac_f32_e32 v98, v52, v98
	v_mul_f32_e32 v52, 0x3f4c422a, v98
	v_add_f32_e32 v52, v52, v52
	v_mul_f32_e32 v52, 0x3fb8aa3b, v52
	v_exp_f32_e32 v98, v52
	v_pk_mul_f32 v[54:55], v[54:55], 0.5 op_sel_hi:[1,0]
	v_pk_add_f32 v[98:99], v[98:99], 1.0 op_sel_hi:[1,0]
	s_nop 0
	v_div_scale_f32 v52, s[14:15], v99, v99, 2.0
	v_rcp_f32_e32 v101, v52
	s_nop 0
	v_fma_f32 v115, -v52, v101, 1.0
	v_fmac_f32_e32 v101, v115, v101
	v_div_scale_f32 v115, vcc, 2.0, v99, 2.0
	v_mul_f32_e32 v116, v115, v101
	v_fma_f32 v117, -v52, v116, v115
	v_fmac_f32_e32 v116, v117, v101
	v_fma_f32 v52, -v52, v116, v115
	v_div_fmas_f32 v52, v52, v101, v116
	v_div_fixup_f32 v99, v52, v99, 2.0
	v_div_scale_f32 v52, s[14:15], v98, v98, 2.0
	v_rcp_f32_e32 v101, v52
	s_nop 0
	v_fma_f32 v115, -v52, v101, 1.0
	v_fmac_f32_e32 v101, v115, v101
	v_div_scale_f32 v115, vcc, 2.0, v98, 2.0
	v_mul_f32_e32 v116, v115, v101
	v_fma_f32 v117, -v52, v116, v115
	v_fmac_f32_e32 v116, v117, v101
	v_fma_f32 v52, -v52, v116, v115
	v_div_fmas_f32 v52, v52, v101, v116
	v_div_fixup_f32 v98, v52, v98, 2.0
	v_pk_add_f32 v[98:99], v[98:99], 1.0 op_sel_hi:[1,0] neg_lo:[1,0] neg_hi:[1,0]
	s_nop 0
	v_pk_add_f32 v[98:99], v[98:99], 1.0 op_sel_hi:[1,0]
	s_nop 0
	v_pk_mul_f32 v[54:55], v[54:55], v[98:99]
	s_nop 0
	v_pk_mul_f32 v[98:99], v[54:55], v[54:55]
	s_nop 0
	v_add_f32_e32 v52, v99, v100
	v_add_f32_e32 v100, v98, v52
	v_and_b32_e32 v52, 0xffff0000, v53
	v_lshlrev_b32_e32 v53, 16, v53
	v_mul_f32_e32 v98, 0x3d372713, v53
	v_mul_f32_e32 v98, v98, v53
	v_mov_b32_e32 v99, v53
	v_fmac_f32_e32 v99, v98, v99
	v_mul_f32_e32 v98, 0x3f4c422a, v99
	v_add_f32_e32 v98, v98, v98
	v_mul_f32_e32 v98, 0x3fb8aa3b, v98
	v_exp_f32_e32 v99, v98
	v_mul_f32_e32 v98, 0x3d372713, v52
	v_mul_f32_e32 v98, v98, v52
	v_mov_b32_e32 v101, v52
	v_fmac_f32_e32 v101, v98, v101
	v_mul_f32_e32 v98, 0x3f4c422a, v101
	v_add_f32_e32 v98, v98, v98
	v_mul_f32_e32 v98, 0x3fb8aa3b, v98
	v_exp_f32_e32 v98, v98
	v_pk_mul_f32 v[52:53], v[52:53], 0.5 op_sel_hi:[1,0]
	v_pk_add_f32 v[98:99], v[98:99], 1.0 op_sel_hi:[1,0]
	s_nop 0
	v_div_scale_f32 v101, s[14:15], v99, v99, 2.0
	v_rcp_f32_e32 v115, v101
	s_nop 0
	v_fma_f32 v116, -v101, v115, 1.0
	v_fmac_f32_e32 v115, v116, v115
	v_div_scale_f32 v116, vcc, 2.0, v99, 2.0
	v_mul_f32_e32 v117, v116, v115
	v_fma_f32 v118, -v101, v117, v116
	v_fmac_f32_e32 v117, v118, v115
	v_fma_f32 v101, -v101, v117, v116
	v_div_fmas_f32 v101, v101, v115, v117
	v_div_fixup_f32 v99, v101, v99, 2.0
	v_div_scale_f32 v101, s[14:15], v98, v98, 2.0
	v_rcp_f32_e32 v115, v101
	s_nop 0
	v_fma_f32 v116, -v101, v115, 1.0
	v_fmac_f32_e32 v115, v116, v115
	v_div_scale_f32 v116, vcc, 2.0, v98, 2.0
	v_mul_f32_e32 v117, v116, v115
	v_fma_f32 v118, -v101, v117, v116
	v_fmac_f32_e32 v117, v118, v115
	v_fma_f32 v101, -v101, v117, v116
	v_div_fmas_f32 v101, v101, v115, v117
	v_div_fixup_f32 v98, v101, v98, 2.0
	v_pk_add_f32 v[98:99], v[98:99], 1.0 op_sel_hi:[1,0] neg_lo:[1,0] neg_hi:[1,0]
	s_nop 0
	v_pk_add_f32 v[98:99], v[98:99], 1.0 op_sel_hi:[1,0]
	s_nop 0
	v_pk_mul_f32 v[98:99], v[52:53], v[98:99]
	s_nop 0
	v_pk_mul_f32 v[52:53], v[98:99], v[98:99]
	s_nop 0
	v_add_f32_e32 v53, v53, v100
	v_add_f32_e32 v52, v52, v53
	ds_bpermute_b32 v53, v106, v52
	s_waitcnt lgkmcnt(0)
	v_add_f32_e32 v52, v52, v53
	ds_bpermute_b32 v53, v107, v52
	s_waitcnt lgkmcnt(0)
	v_add_f32_e32 v52, v52, v53
	ds_bpermute_b32 v53, v108, v52
	s_waitcnt lgkmcnt(0)
	v_add_f32_e32 v52, v52, v53
	ds_bpermute_b32 v53, v109, v52
	s_waitcnt lgkmcnt(0)
	v_add_f32_e32 v52, v52, v53
	ds_bpermute_b32 v53, v110, v52
	s_waitcnt lgkmcnt(0)
	v_add_f32_e32 v52, v52, v53
	v_fmamk_f32 v52, v52, 0x3b800000, v243
	v_cmp_gt_f32_e32 vcc, s3, v52
	v_mul_f32_e32 v53, 0x4b800000, v52
	s_nop 0
	v_cndmask_b32_e32 v52, v52, v53, vcc
	v_rsq_f32_e32 v52, v52
	s_nop 0
	v_mul_f32_e32 v53, 0x45800000, v52
	v_cndmask_b32_e32 v100, v52, v53, vcc
	v_mul_f32_e32 v52, v60, v100
	v_mul_f32_e32 v53, v61, v100
	v_mul_f32_e32 v50, v50, v100
	v_mul_f32_e32 v52, v70, v52
	v_mul_f32_e32 v53, v71, v53
	v_mul_f32_e32 v51, v51, v100
	v_mul_f32_e32 v50, v73, v50
	v_cvt_pk_bf16_f32 v52, v52, v53
	v_cvt_pk_bf16_f32 v59, v62, v63
	v_mul_f32_e32 v51, v72, v51
	v_cvt_pk_bf16_f32 v53, v51, v50
	v_mul_f32_e32 v50, v55, v100
	v_mul_f32_e32 v50, v66, v50
	v_mul_f32_e32 v51, v54, v100
	v_cvt_pk_bf16_f32 v60, v64, v56
	v_mul_f32_e32 v51, v67, v51
	v_cvt_pk_bf16_f32 v54, v50, v51
	v_mul_f32_e32 v50, v99, v100
	v_mul_f32_e32 v50, v68, v50
	v_mul_f32_e32 v51, v98, v100
	v_cvt_pk_bf16_f32 v61, v65, v57
	v_mul_f32_e32 v51, v69, v51
	v_cvt_pk_bf16_f32 v55, v50, v51
	v_lshlrev_b32_e32 v50, 16, v46
	v_mul_f32_e32 v51, 0x3d372713, v50
	v_mul_f32_e32 v51, v51, v50
	v_fma_f32 v51, v51, v50, v50
	v_mul_f32_e32 v51, 0x3f4c422a, v51
	v_add_f32_e32 v51, v51, v51
	v_mul_f32_e32 v51, 0x3fb8aa3b, v51
	v_exp_f32_e32 v51, v51
	ds_write_b128 v111, v[58:61] offset:8704
	ds_write_b128 v112, v[52:55] offset:8704
	v_mul_f32_e32 v50, 0.5, v50
	v_and_b32_e32 v46, 0xffff0000, v46
	v_add_f32_e32 v51, 1.0, v51
	v_div_scale_f32 v52, s[14:15], v51, v51, 2.0
	v_rcp_f32_e32 v53, v52
	v_mov_b64_e32 v[98:99], v[80:81]
	v_mov_b64_e32 v[100:101], v[78:79]
	v_fma_f32 v54, -v52, v53, 1.0
	v_fmac_f32_e32 v53, v54, v53
	v_div_scale_f32 v54, vcc, 2.0, v51, 2.0
	v_mul_f32_e32 v55, v54, v53
	v_fma_f32 v56, -v52, v55, v54
	v_fmac_f32_e32 v55, v56, v53
	v_fma_f32 v52, -v52, v55, v54
	v_div_fmas_f32 v52, v52, v53, v55
	v_div_fixup_f32 v51, v52, v51, 2.0
	v_sub_f32_e32 v51, 1.0, v51
	v_add_f32_e32 v51, 1.0, v51
	v_mul_f32_e32 v50, v50, v51
	v_mul_f32_e32 v51, 0x3d372713, v46
	v_mul_f32_e32 v51, v51, v46
	v_fma_f32 v51, v51, v46, v46
	v_mul_f32_e32 v51, 0x3f4c422a, v51
	v_add_f32_e32 v51, v51, v51
	v_mul_f32_e32 v51, 0x3fb8aa3b, v51
	v_exp_f32_e32 v51, v51
	v_mul_f32_e32 v46, 0.5, v46
	v_add_f32_e32 v51, 1.0, v51
	v_div_scale_f32 v52, s[14:15], v51, v51, 2.0
	v_rcp_f32_e32 v53, v52
	s_nop 0
	v_fma_f32 v54, -v52, v53, 1.0
	v_fmac_f32_e32 v53, v54, v53
	v_div_scale_f32 v54, vcc, 2.0, v51, 2.0
	v_mul_f32_e32 v55, v54, v53
	v_fma_f32 v56, -v52, v55, v54
	v_fmac_f32_e32 v55, v56, v53
	v_fma_f32 v52, -v52, v55, v54
	v_div_fmas_f32 v52, v52, v53, v55
	v_div_fixup_f32 v51, v52, v51, 2.0
	v_sub_f32_e32 v51, 1.0, v51
	v_add_f32_e32 v51, 1.0, v51
	v_mul_f32_e32 v51, v46, v51
	v_lshlrev_b32_e32 v46, 16, v42
	v_mul_f32_e32 v52, 0x3d372713, v46
	v_mul_f32_e32 v52, v52, v46
	v_fma_f32 v52, v52, v46, v46
	v_mul_f32_e32 v52, 0x3f4c422a, v52
	v_add_f32_e32 v52, v52, v52
	v_mul_f32_e32 v52, 0x3fb8aa3b, v52
	v_exp_f32_e32 v52, v52
	v_mul_f32_e32 v46, 0.5, v46
	v_and_b32_e32 v42, 0xffff0000, v42
	v_cvt_pk_bf16_f32 v50, v50, v51
	v_add_f32_e32 v52, 1.0, v52
	v_div_scale_f32 v53, s[14:15], v52, v52, 2.0
	v_rcp_f32_e32 v54, v53
	s_nop 0
	v_fma_f32 v55, -v53, v54, 1.0
	v_fmac_f32_e32 v54, v55, v54
	v_div_scale_f32 v55, vcc, 2.0, v52, 2.0
	v_mul_f32_e32 v56, v55, v54
	v_fma_f32 v57, -v53, v56, v55
	v_fmac_f32_e32 v56, v57, v54
	v_fma_f32 v53, -v53, v56, v55
	v_div_fmas_f32 v53, v53, v54, v56
	v_div_fixup_f32 v52, v53, v52, 2.0
	v_sub_f32_e32 v52, 1.0, v52
	v_add_f32_e32 v52, 1.0, v52
	v_mul_f32_e32 v52, v46, v52
	v_mul_f32_e32 v46, 0x3d372713, v42
	v_mul_f32_e32 v46, v46, v42
	v_fma_f32 v46, v46, v42, v42
	v_mul_f32_e32 v46, 0x3f4c422a, v46
	v_add_f32_e32 v46, v46, v46
	v_mul_f32_e32 v46, 0x3fb8aa3b, v46
	v_exp_f32_e32 v46, v46
	v_mul_f32_e32 v42, 0.5, v42
	v_add_f32_e32 v46, 1.0, v46
	v_div_scale_f32 v53, s[14:15], v46, v46, 2.0
	v_rcp_f32_e32 v54, v53
	s_nop 0
	v_fma_f32 v55, -v53, v54, 1.0
	v_fmac_f32_e32 v54, v55, v54
	v_div_scale_f32 v55, vcc, 2.0, v46, 2.0
	v_mul_f32_e32 v56, v55, v54
	v_fma_f32 v57, -v53, v56, v55
	v_fmac_f32_e32 v56, v57, v54
	v_fma_f32 v53, -v53, v56, v55
	v_div_fmas_f32 v53, v53, v54, v56
	v_div_fixup_f32 v46, v53, v46, 2.0
	v_sub_f32_e32 v46, 1.0, v46
	v_add_f32_e32 v46, 1.0, v46
	v_mul_f32_e32 v53, v42, v46
	v_lshlrev_b32_e32 v42, 16, v47
	v_mul_f32_e32 v46, 0x3d372713, v42
	v_mul_f32_e32 v46, v46, v42
	v_fma_f32 v46, v46, v42, v42
	v_mul_f32_e32 v46, 0x3f4c422a, v46
	v_add_f32_e32 v46, v46, v46
	v_mul_f32_e32 v46, 0x3fb8aa3b, v46
	v_exp_f32_e32 v46, v46
	v_mul_f32_e32 v42, 0.5, v42
	v_add_f32_e32 v46, 1.0, v46
	v_div_scale_f32 v54, s[14:15], v46, v46, 2.0
	v_rcp_f32_e32 v55, v54
	s_nop 0
	v_fma_f32 v56, -v54, v55, 1.0
	v_fmac_f32_e32 v55, v56, v55
	v_div_scale_f32 v56, vcc, 2.0, v46, 2.0
	v_mul_f32_e32 v57, v56, v55
	v_fma_f32 v58, -v54, v57, v56
	v_fmac_f32_e32 v57, v58, v55
	v_fma_f32 v54, -v54, v57, v56
	v_div_fmas_f32 v54, v54, v55, v57
	v_div_fixup_f32 v46, v54, v46, 2.0
	v_sub_f32_e32 v46, 1.0, v46
	v_add_f32_e32 v46, 1.0, v46
	v_mul_f32_e32 v54, v42, v46
	v_and_b32_e32 v42, 0xffff0000, v47
	v_mul_f32_e32 v46, 0x3d372713, v42
	v_mul_f32_e32 v46, v46, v42
	v_fma_f32 v46, v46, v42, v42
	v_mul_f32_e32 v46, 0x3f4c422a, v46
	v_add_f32_e32 v46, v46, v46
	v_mul_f32_e32 v46, 0x3fb8aa3b, v46
	v_exp_f32_e32 v46, v46
	v_mul_f32_e32 v42, 0.5, v42
	v_add_f32_e32 v46, 1.0, v46
	v_div_scale_f32 v47, s[14:15], v46, v46, 2.0
	v_rcp_f32_e32 v55, v47
	s_nop 0
	v_fma_f32 v56, -v47, v55, 1.0
	v_fmac_f32_e32 v55, v56, v55
	v_div_scale_f32 v56, vcc, 2.0, v46, 2.0
	v_mul_f32_e32 v57, v56, v55
	v_fma_f32 v58, -v47, v57, v56
	v_fmac_f32_e32 v57, v58, v55
	v_fma_f32 v47, -v47, v57, v56
	v_div_fmas_f32 v47, v47, v55, v57
	v_div_fixup_f32 v46, v47, v46, 2.0
	v_sub_f32_e32 v46, 1.0, v46
	v_add_f32_e32 v46, 1.0, v46
	v_mul_f32_e32 v55, v42, v46
	v_lshlrev_b32_e32 v42, 16, v48
	v_mul_f32_e32 v46, 0x3d372713, v42
	v_mul_f32_e32 v46, v46, v42
	v_fma_f32 v46, v46, v42, v42
	v_mul_f32_e32 v46, 0x3f4c422a, v46
	v_add_f32_e32 v46, v46, v46
	v_mul_f32_e32 v46, 0x3fb8aa3b, v46
	v_exp_f32_e32 v46, v46
	v_mul_f32_e32 v42, 0.5, v42
	v_add_f32_e32 v46, 1.0, v46
	v_div_scale_f32 v47, s[14:15], v46, v46, 2.0
	v_rcp_f32_e32 v56, v47
	s_nop 0
	v_fma_f32 v57, -v47, v56, 1.0
	v_fmac_f32_e32 v56, v57, v56
	v_div_scale_f32 v57, vcc, 2.0, v46, 2.0
	v_mul_f32_e32 v58, v57, v56
	v_fma_f32 v59, -v47, v58, v57
	v_fmac_f32_e32 v58, v59, v56
	v_fma_f32 v47, -v47, v58, v57
	v_div_fmas_f32 v47, v47, v56, v58
	v_div_fixup_f32 v46, v47, v46, 2.0
	v_sub_f32_e32 v46, 1.0, v46
	v_add_f32_e32 v46, 1.0, v46
	v_mul_f32_e32 v56, v42, v46
	v_and_b32_e32 v42, 0xffff0000, v48
	v_mul_f32_e32 v46, 0x3d372713, v42
	v_mul_f32_e32 v46, v46, v42
	v_fma_f32 v46, v46, v42, v42
	v_mul_f32_e32 v46, 0x3f4c422a, v46
	v_add_f32_e32 v46, v46, v46
	v_mul_f32_e32 v46, 0x3fb8aa3b, v46
	v_exp_f32_e32 v46, v46
	v_mul_f32_e32 v42, 0.5, v42
	v_add_f32_e32 v46, 1.0, v46
	v_div_scale_f32 v47, s[14:15], v46, v46, 2.0
	v_rcp_f32_e32 v48, v47
	s_nop 0
	v_fma_f32 v57, -v47, v48, 1.0
	v_fmac_f32_e32 v48, v57, v48
	v_div_scale_f32 v57, vcc, 2.0, v46, 2.0
	v_mul_f32_e32 v58, v57, v48
	v_fma_f32 v59, -v47, v58, v57
	v_fmac_f32_e32 v58, v59, v48
	v_fma_f32 v47, -v47, v58, v57
	v_div_fmas_f32 v47, v47, v48, v58
	v_div_fixup_f32 v46, v47, v46, 2.0
	v_sub_f32_e32 v46, 1.0, v46
	v_add_f32_e32 v46, 1.0, v46
	v_mul_f32_e32 v48, v42, v46
	v_lshlrev_b32_e32 v42, 16, v49
	v_mul_f32_e32 v46, 0x3d372713, v42
	v_mul_f32_e32 v46, v46, v42
	v_fma_f32 v46, v46, v42, v42
	v_mul_f32_e32 v46, 0x3f4c422a, v46
	v_add_f32_e32 v46, v46, v46
	v_mul_f32_e32 v46, 0x3fb8aa3b, v46
	v_exp_f32_e32 v46, v46
	v_mul_f32_e32 v42, 0.5, v42
	v_add_f32_e32 v46, 1.0, v46
	v_div_scale_f32 v47, s[14:15], v46, v46, 2.0
	v_rcp_f32_e32 v57, v47
	s_nop 0
	v_fma_f32 v58, -v47, v57, 1.0
	v_fmac_f32_e32 v57, v58, v57
	v_div_scale_f32 v58, vcc, 2.0, v46, 2.0
	v_mul_f32_e32 v59, v58, v57
	v_fma_f32 v60, -v47, v59, v58
	v_fmac_f32_e32 v59, v60, v57
	v_fma_f32 v47, -v47, v59, v58
	v_div_fmas_f32 v47, v47, v57, v59
	v_div_fixup_f32 v46, v47, v46, 2.0
	v_sub_f32_e32 v46, 1.0, v46
	v_add_f32_e32 v46, 1.0, v46
	v_mul_f32_e32 v57, v42, v46
	v_and_b32_e32 v42, 0xffff0000, v49
	v_mul_f32_e32 v46, 0x3d372713, v42
	v_mul_f32_e32 v46, v46, v42
	v_fma_f32 v46, v46, v42, v42
	v_mul_f32_e32 v46, 0x3f4c422a, v46
	v_add_f32_e32 v46, v46, v46
	v_mul_f32_e32 v46, 0x3fb8aa3b, v46
	v_exp_f32_e32 v46, v46
	v_mul_f32_e32 v42, 0.5, v42
	v_add_f32_e32 v46, 1.0, v46
	v_div_scale_f32 v47, s[14:15], v46, v46, 2.0
	v_rcp_f32_e32 v49, v47
	s_nop 0
	v_fma_f32 v58, -v47, v49, 1.0
	v_fmac_f32_e32 v49, v58, v49
	v_div_scale_f32 v58, vcc, 2.0, v46, 2.0
	v_mul_f32_e32 v59, v58, v49
	v_fma_f32 v60, -v47, v59, v58
	v_fmac_f32_e32 v59, v60, v49
	v_fma_f32 v47, -v47, v59, v58
	v_div_fmas_f32 v47, v47, v49, v59
	v_div_fixup_f32 v46, v47, v46, 2.0
	v_sub_f32_e32 v46, 1.0, v46
	v_add_f32_e32 v46, 1.0, v46
	v_mul_f32_e32 v49, v42, v46
	v_and_b32_e32 v42, 0xffff0000, v43
	v_lshlrev_b32_e32 v43, 16, v43
	v_mul_f32_e32 v46, 0x3d372713, v43
	v_mul_f32_e32 v46, v46, v43
	v_mov_b32_e32 v47, v43
	v_fmac_f32_e32 v47, v46, v47
	v_mul_f32_e32 v46, 0x3f4c422a, v47
	v_add_f32_e32 v46, v46, v46
	v_mul_f32_e32 v46, 0x3fb8aa3b, v46
	v_exp_f32_e32 v47, v46
	v_mul_f32_e32 v46, 0x3d372713, v42
	v_mul_f32_e32 v46, v46, v42
	v_mov_b32_e32 v59, v42
	v_fmac_f32_e32 v59, v46, v59
	v_mul_f32_e32 v46, 0x3f4c422a, v59
	v_add_f32_e32 v46, v46, v46
	v_mul_f32_e32 v46, 0x3fb8aa3b, v46
	v_exp_f32_e32 v46, v46
	v_pk_mul_f32 v[42:43], v[42:43], 0.5 op_sel_hi:[1,0]
	v_mul_f32_e32 v58, v53, v53
	v_fmac_f32_e32 v58, v52, v52
	v_pk_add_f32 v[46:47], v[46:47], 1.0 op_sel_hi:[1,0]
	s_nop 0
	v_div_scale_f32 v59, s[14:15], v47, v47, 2.0
	v_rcp_f32_e32 v60, v59
	s_nop 0
	v_fma_f32 v61, -v59, v60, 1.0
	v_fmac_f32_e32 v60, v61, v60
	v_div_scale_f32 v61, vcc, 2.0, v47, 2.0
	v_mul_f32_e32 v62, v61, v60
	v_fma_f32 v63, -v59, v62, v61
	v_fmac_f32_e32 v62, v63, v60
	v_fma_f32 v59, -v59, v62, v61
	v_div_fmas_f32 v59, v59, v60, v62
	v_div_fixup_f32 v47, v59, v47, 2.0
	v_div_scale_f32 v59, s[14:15], v46, v46, 2.0
	v_rcp_f32_e32 v60, v59
	s_nop 0
	v_fma_f32 v61, -v59, v60, 1.0
	v_fmac_f32_e32 v60, v61, v60
	v_div_scale_f32 v61, vcc, 2.0, v46, 2.0
	v_mul_f32_e32 v62, v61, v60
	v_fma_f32 v63, -v59, v62, v61
	v_fmac_f32_e32 v62, v63, v60
	v_fma_f32 v59, -v59, v62, v61
	v_div_fmas_f32 v59, v59, v60, v62
	v_div_fixup_f32 v46, v59, v46, 2.0
	v_pk_add_f32 v[46:47], v[46:47], 1.0 op_sel_hi:[1,0] neg_lo:[1,0] neg_hi:[1,0]
	s_nop 0
	v_pk_add_f32 v[46:47], v[46:47], 1.0 op_sel_hi:[1,0]
	s_nop 0
	v_pk_mul_f32 v[42:43], v[42:43], v[46:47]
	s_nop 0
	v_pk_mul_f32 v[46:47], v[42:43], v[42:43]
	s_nop 0
	v_add_f32_e32 v47, v47, v58
	v_add_f32_e32 v60, v46, v47
	v_lshlrev_b32_e32 v47, 16, v44
	v_and_b32_e32 v46, 0xffff0000, v44
	v_mul_f32_e32 v44, 0x3d372713, v47
	v_mul_f32_e32 v44, v44, v47
	v_mov_b32_e32 v58, v47
	v_fmac_f32_e32 v58, v44, v58
	v_mul_f32_e32 v44, 0x3f4c422a, v58
	v_add_f32_e32 v44, v44, v44
	v_mul_f32_e32 v44, 0x3fb8aa3b, v44
	v_exp_f32_e32 v59, v44
	v_mul_f32_e32 v44, 0x3d372713, v46
	v_mul_f32_e32 v44, v44, v46
	v_mov_b32_e32 v58, v46
	v_fmac_f32_e32 v58, v44, v58
	v_mul_f32_e32 v44, 0x3f4c422a, v58
	v_add_f32_e32 v44, v44, v44
	v_mul_f32_e32 v44, 0x3fb8aa3b, v44
	v_exp_f32_e32 v58, v44
	v_pk_mul_f32 v[46:47], v[46:47], 0.5 op_sel_hi:[1,0]
	v_pk_add_f32 v[58:59], v[58:59], 1.0 op_sel_hi:[1,0]
	s_nop 0
	v_div_scale_f32 v44, s[14:15], v59, v59, 2.0
	v_rcp_f32_e32 v61, v44
	s_nop 0
	v_fma_f32 v62, -v44, v61, 1.0
	v_fmac_f32_e32 v61, v62, v61
	v_div_scale_f32 v62, vcc, 2.0, v59, 2.0
	v_mul_f32_e32 v63, v62, v61
	v_fma_f32 v64, -v44, v63, v62
	v_fmac_f32_e32 v63, v64, v61
	v_fma_f32 v44, -v44, v63, v62
	v_div_fmas_f32 v44, v44, v61, v63
	v_div_fixup_f32 v59, v44, v59, 2.0
	v_div_scale_f32 v44, s[14:15], v58, v58, 2.0
	v_rcp_f32_e32 v61, v44
	s_nop 0
	v_fma_f32 v62, -v44, v61, 1.0
	v_fmac_f32_e32 v61, v62, v61
	v_div_scale_f32 v62, vcc, 2.0, v58, 2.0
	v_mul_f32_e32 v63, v62, v61
	v_fma_f32 v64, -v44, v63, v62
	v_fmac_f32_e32 v63, v64, v61
	v_fma_f32 v44, -v44, v63, v62
	v_div_fmas_f32 v44, v44, v61, v63
	v_div_fixup_f32 v58, v44, v58, 2.0
	v_pk_add_f32 v[58:59], v[58:59], 1.0 op_sel_hi:[1,0] neg_lo:[1,0] neg_hi:[1,0]
	s_nop 0
	v_pk_add_f32 v[58:59], v[58:59], 1.0 op_sel_hi:[1,0]
	s_nop 0
	v_pk_mul_f32 v[46:47], v[46:47], v[58:59]
	s_nop 0
	v_pk_mul_f32 v[58:59], v[46:47], v[46:47]
	s_nop 0
	v_add_f32_e32 v44, v59, v60
	v_add_f32_e32 v60, v58, v44
	v_and_b32_e32 v44, 0xffff0000, v45
	v_lshlrev_b32_e32 v45, 16, v45
	v_mul_f32_e32 v58, 0x3d372713, v45
	v_mul_f32_e32 v58, v58, v45
	v_mov_b32_e32 v59, v45
	v_fmac_f32_e32 v59, v58, v59
	v_mul_f32_e32 v58, 0x3f4c422a, v59
	v_add_f32_e32 v58, v58, v58
	v_mul_f32_e32 v58, 0x3fb8aa3b, v58
	v_exp_f32_e32 v59, v58
	v_mul_f32_e32 v58, 0x3d372713, v44
	v_mul_f32_e32 v58, v58, v44
	v_mov_b32_e32 v61, v44
	v_fmac_f32_e32 v61, v58, v61
	v_mul_f32_e32 v58, 0x3f4c422a, v61
	v_add_f32_e32 v58, v58, v58
	v_mul_f32_e32 v58, 0x3fb8aa3b, v58
	v_exp_f32_e32 v58, v58
	v_pk_mul_f32 v[44:45], v[44:45], 0.5 op_sel_hi:[1,0]
	v_pk_add_f32 v[58:59], v[58:59], 1.0 op_sel_hi:[1,0]
	s_nop 0
	v_div_scale_f32 v61, s[14:15], v59, v59, 2.0
	v_rcp_f32_e32 v62, v61
	s_nop 0
	v_fma_f32 v63, -v61, v62, 1.0
	v_fmac_f32_e32 v62, v63, v62
	v_div_scale_f32 v63, vcc, 2.0, v59, 2.0
	v_mul_f32_e32 v64, v63, v62
	v_fma_f32 v65, -v61, v64, v63
	v_fmac_f32_e32 v64, v65, v62
	v_fma_f32 v61, -v61, v64, v63
	v_div_fmas_f32 v61, v61, v62, v64
	v_div_fixup_f32 v59, v61, v59, 2.0
	v_div_scale_f32 v61, s[14:15], v58, v58, 2.0
	v_rcp_f32_e32 v62, v61
	s_nop 0
	v_fma_f32 v63, -v61, v62, 1.0
	v_fmac_f32_e32 v62, v63, v62
	v_div_scale_f32 v63, vcc, 2.0, v58, 2.0
	v_mul_f32_e32 v64, v63, v62
	v_fma_f32 v65, -v61, v64, v63
	v_fmac_f32_e32 v64, v65, v62
	v_fma_f32 v61, -v61, v64, v63
	v_div_fmas_f32 v61, v61, v62, v64
	v_div_fixup_f32 v58, v61, v58, 2.0
	v_pk_add_f32 v[58:59], v[58:59], 1.0 op_sel_hi:[1,0] neg_lo:[1,0] neg_hi:[1,0]
	s_nop 0
	v_pk_add_f32 v[58:59], v[58:59], 1.0 op_sel_hi:[1,0]
	s_nop 0
	v_pk_mul_f32 v[58:59], v[44:45], v[58:59]
	s_nop 0
	v_pk_mul_f32 v[44:45], v[58:59], v[58:59]
	s_nop 0
	v_add_f32_e32 v45, v45, v60
	v_add_f32_e32 v44, v44, v45
	ds_bpermute_b32 v45, v106, v44
	s_waitcnt lgkmcnt(0)
	v_add_f32_e32 v44, v44, v45
	ds_bpermute_b32 v45, v107, v44
	s_waitcnt lgkmcnt(0)
	v_add_f32_e32 v44, v44, v45
	ds_bpermute_b32 v45, v108, v44
	s_waitcnt lgkmcnt(0)
	v_add_f32_e32 v44, v44, v45
	ds_bpermute_b32 v45, v109, v44
	s_waitcnt lgkmcnt(0)
	v_add_f32_e32 v44, v44, v45
	ds_bpermute_b32 v45, v110, v44
	s_waitcnt lgkmcnt(0)
	v_add_f32_e32 v44, v44, v45
	v_fmamk_f32 v44, v44, 0x3b800000, v243
	v_cmp_gt_f32_e32 vcc, s3, v44
	v_mul_f32_e32 v45, 0x4b800000, v44
	s_nop 0
	v_cndmask_b32_e32 v44, v44, v45, vcc
	v_rsq_f32_e32 v44, v44
	s_nop 0
	v_mul_f32_e32 v45, 0x45800000, v44
	v_cndmask_b32_e32 v60, v44, v45, vcc
	v_mul_f32_e32 v44, v52, v60
	v_mul_f32_e32 v45, v53, v60
	v_mul_f32_e32 v42, v42, v60
	v_mul_f32_e32 v44, v70, v44
	v_mul_f32_e32 v45, v71, v45
	v_mul_f32_e32 v43, v43, v60
	v_mul_f32_e32 v42, v73, v42
	v_cvt_pk_bf16_f32 v44, v44, v45
	v_cvt_pk_bf16_f32 v51, v54, v55
	v_mul_f32_e32 v43, v72, v43
	v_cvt_pk_bf16_f32 v45, v43, v42
	v_mul_f32_e32 v42, v47, v60
	v_mul_f32_e32 v42, v66, v42
	v_mul_f32_e32 v43, v46, v60
	v_cvt_pk_bf16_f32 v52, v56, v48
	v_mul_f32_e32 v43, v67, v43
	v_cvt_pk_bf16_f32 v46, v42, v43
	v_mul_f32_e32 v42, v59, v60
	v_mul_f32_e32 v42, v68, v42
	v_mul_f32_e32 v43, v58, v60
	v_cvt_pk_bf16_f32 v53, v57, v49
	v_mul_f32_e32 v43, v69, v43
	v_cvt_pk_bf16_f32 v47, v42, v43
	v_lshlrev_b32_e32 v42, 16, v38
	v_mul_f32_e32 v43, 0x3d372713, v42
	v_mul_f32_e32 v43, v43, v42
	v_fma_f32 v43, v43, v42, v42
	v_mul_f32_e32 v43, 0x3f4c422a, v43
	v_add_f32_e32 v43, v43, v43
	v_mul_f32_e32 v43, 0x3fb8aa3b, v43
	v_exp_f32_e32 v43, v43
	ds_write_b128 v111, v[50:53] offset:17408
	ds_write_b128 v112, v[44:47] offset:17408
	v_mul_f32_e32 v42, 0.5, v42
	v_and_b32_e32 v38, 0xffff0000, v38
	v_add_f32_e32 v43, 1.0, v43
	v_div_scale_f32 v44, s[14:15], v43, v43, 2.0
	v_rcp_f32_e32 v45, v44
	s_nop 0
	v_fma_f32 v46, -v44, v45, 1.0
	v_fmac_f32_e32 v45, v46, v45
	v_div_scale_f32 v46, vcc, 2.0, v43, 2.0
	v_mul_f32_e32 v47, v46, v45
	v_fma_f32 v48, -v44, v47, v46
	v_fmac_f32_e32 v47, v48, v45
	v_fma_f32 v44, -v44, v47, v46
	v_div_fmas_f32 v44, v44, v45, v47
	v_div_fixup_f32 v43, v44, v43, 2.0
	v_sub_f32_e32 v43, 1.0, v43
	v_add_f32_e32 v43, 1.0, v43
	v_mul_f32_e32 v42, v42, v43
	v_mul_f32_e32 v43, 0x3d372713, v38
	v_mul_f32_e32 v43, v43, v38
	v_fma_f32 v43, v43, v38, v38
	v_mul_f32_e32 v43, 0x3f4c422a, v43
	v_add_f32_e32 v43, v43, v43
	v_mul_f32_e32 v43, 0x3fb8aa3b, v43
	v_exp_f32_e32 v43, v43
	v_mul_f32_e32 v38, 0.5, v38
	v_add_f32_e32 v43, 1.0, v43
	v_div_scale_f32 v44, s[14:15], v43, v43, 2.0
	v_rcp_f32_e32 v45, v44
	s_nop 0
	v_fma_f32 v46, -v44, v45, 1.0
	v_fmac_f32_e32 v45, v46, v45
	v_div_scale_f32 v46, vcc, 2.0, v43, 2.0
	v_mul_f32_e32 v47, v46, v45
	v_fma_f32 v48, -v44, v47, v46
	v_fmac_f32_e32 v47, v48, v45
	v_fma_f32 v44, -v44, v47, v46
	v_div_fmas_f32 v44, v44, v45, v47
	v_div_fixup_f32 v43, v44, v43, 2.0
	v_sub_f32_e32 v43, 1.0, v43
	v_add_f32_e32 v43, 1.0, v43
	v_mul_f32_e32 v43, v38, v43
	v_lshlrev_b32_e32 v38, 16, v34
	v_mul_f32_e32 v44, 0x3d372713, v38
	v_mul_f32_e32 v44, v44, v38
	v_fma_f32 v44, v44, v38, v38
	v_mul_f32_e32 v44, 0x3f4c422a, v44
	v_add_f32_e32 v44, v44, v44
	v_mul_f32_e32 v44, 0x3fb8aa3b, v44
	v_exp_f32_e32 v44, v44
	v_mul_f32_e32 v38, 0.5, v38
	v_and_b32_e32 v34, 0xffff0000, v34
	v_cvt_pk_bf16_f32 v42, v42, v43
	v_add_f32_e32 v44, 1.0, v44
	v_div_scale_f32 v45, s[14:15], v44, v44, 2.0
	v_rcp_f32_e32 v46, v45
	s_nop 0
	v_fma_f32 v47, -v45, v46, 1.0
	v_fmac_f32_e32 v46, v47, v46
	v_div_scale_f32 v47, vcc, 2.0, v44, 2.0
	v_mul_f32_e32 v48, v47, v46
	v_fma_f32 v49, -v45, v48, v47
	v_fmac_f32_e32 v48, v49, v46
	v_fma_f32 v45, -v45, v48, v47
	v_div_fmas_f32 v45, v45, v46, v48
	v_div_fixup_f32 v44, v45, v44, 2.0
	v_sub_f32_e32 v44, 1.0, v44
	v_add_f32_e32 v44, 1.0, v44
	v_mul_f32_e32 v44, v38, v44
	v_mul_f32_e32 v38, 0x3d372713, v34
	v_mul_f32_e32 v38, v38, v34
	v_fma_f32 v38, v38, v34, v34
	v_mul_f32_e32 v38, 0x3f4c422a, v38
	v_add_f32_e32 v38, v38, v38
	v_mul_f32_e32 v38, 0x3fb8aa3b, v38
	v_exp_f32_e32 v38, v38
	v_mul_f32_e32 v34, 0.5, v34
	v_add_f32_e32 v38, 1.0, v38
	v_div_scale_f32 v45, s[14:15], v38, v38, 2.0
	v_rcp_f32_e32 v46, v45
	s_nop 0
	v_fma_f32 v47, -v45, v46, 1.0
	v_fmac_f32_e32 v46, v47, v46
	v_div_scale_f32 v47, vcc, 2.0, v38, 2.0
	v_mul_f32_e32 v48, v47, v46
	v_fma_f32 v49, -v45, v48, v47
	v_fmac_f32_e32 v48, v49, v46
	v_fma_f32 v45, -v45, v48, v47
	v_div_fmas_f32 v45, v45, v46, v48
	v_div_fixup_f32 v38, v45, v38, 2.0
	v_sub_f32_e32 v38, 1.0, v38
	v_add_f32_e32 v38, 1.0, v38
	v_mul_f32_e32 v45, v34, v38
	v_lshlrev_b32_e32 v34, 16, v39
	v_mul_f32_e32 v38, 0x3d372713, v34
	v_mul_f32_e32 v38, v38, v34
	v_fma_f32 v38, v38, v34, v34
	v_mul_f32_e32 v38, 0x3f4c422a, v38
	v_add_f32_e32 v38, v38, v38
	v_mul_f32_e32 v38, 0x3fb8aa3b, v38
	v_exp_f32_e32 v38, v38
	v_mul_f32_e32 v34, 0.5, v34
	v_add_f32_e32 v38, 1.0, v38
	v_div_scale_f32 v46, s[14:15], v38, v38, 2.0
	v_rcp_f32_e32 v47, v46
	s_nop 0
	v_fma_f32 v48, -v46, v47, 1.0
	v_fmac_f32_e32 v47, v48, v47
	v_div_scale_f32 v48, vcc, 2.0, v38, 2.0
	v_mul_f32_e32 v49, v48, v47
	v_fma_f32 v50, -v46, v49, v48
	v_fmac_f32_e32 v49, v50, v47
	v_fma_f32 v46, -v46, v49, v48
	v_div_fmas_f32 v46, v46, v47, v49
	v_div_fixup_f32 v38, v46, v38, 2.0
	v_sub_f32_e32 v38, 1.0, v38
	v_add_f32_e32 v38, 1.0, v38
	v_mul_f32_e32 v46, v34, v38
	v_and_b32_e32 v34, 0xffff0000, v39
	v_mul_f32_e32 v38, 0x3d372713, v34
	v_mul_f32_e32 v38, v38, v34
	v_fma_f32 v38, v38, v34, v34
	v_mul_f32_e32 v38, 0x3f4c422a, v38
	v_add_f32_e32 v38, v38, v38
	v_mul_f32_e32 v38, 0x3fb8aa3b, v38
	v_exp_f32_e32 v38, v38
	v_mul_f32_e32 v34, 0.5, v34
	v_add_f32_e32 v38, 1.0, v38
	v_div_scale_f32 v39, s[14:15], v38, v38, 2.0
	v_rcp_f32_e32 v47, v39
	s_nop 0
	v_fma_f32 v48, -v39, v47, 1.0
	v_fmac_f32_e32 v47, v48, v47
	v_div_scale_f32 v48, vcc, 2.0, v38, 2.0
	v_mul_f32_e32 v49, v48, v47
	v_fma_f32 v50, -v39, v49, v48
	v_fmac_f32_e32 v49, v50, v47
	v_fma_f32 v39, -v39, v49, v48
	v_div_fmas_f32 v39, v39, v47, v49
	v_div_fixup_f32 v38, v39, v38, 2.0
	v_sub_f32_e32 v38, 1.0, v38
	v_add_f32_e32 v38, 1.0, v38
	v_mul_f32_e32 v47, v34, v38
	v_lshlrev_b32_e32 v34, 16, v40
	v_mul_f32_e32 v38, 0x3d372713, v34
	v_mul_f32_e32 v38, v38, v34
	v_fma_f32 v38, v38, v34, v34
	v_mul_f32_e32 v38, 0x3f4c422a, v38
	v_add_f32_e32 v38, v38, v38
	v_mul_f32_e32 v38, 0x3fb8aa3b, v38
	v_exp_f32_e32 v38, v38
	v_mul_f32_e32 v34, 0.5, v34
	v_add_f32_e32 v38, 1.0, v38
	v_div_scale_f32 v39, s[14:15], v38, v38, 2.0
	v_rcp_f32_e32 v48, v39
	s_nop 0
	v_fma_f32 v49, -v39, v48, 1.0
	v_fmac_f32_e32 v48, v49, v48
	v_div_scale_f32 v49, vcc, 2.0, v38, 2.0
	v_mul_f32_e32 v50, v49, v48
	v_fma_f32 v51, -v39, v50, v49
	v_fmac_f32_e32 v50, v51, v48
	v_fma_f32 v39, -v39, v50, v49
	v_div_fmas_f32 v39, v39, v48, v50
	v_div_fixup_f32 v38, v39, v38, 2.0
	v_sub_f32_e32 v38, 1.0, v38
	v_add_f32_e32 v38, 1.0, v38
	v_mul_f32_e32 v48, v34, v38
	v_and_b32_e32 v34, 0xffff0000, v40
	v_mul_f32_e32 v38, 0x3d372713, v34
	v_mul_f32_e32 v38, v38, v34
	v_fma_f32 v38, v38, v34, v34
	v_mul_f32_e32 v38, 0x3f4c422a, v38
	v_add_f32_e32 v38, v38, v38
	v_mul_f32_e32 v38, 0x3fb8aa3b, v38
	v_exp_f32_e32 v38, v38
	v_mul_f32_e32 v34, 0.5, v34
	v_add_f32_e32 v38, 1.0, v38
	v_div_scale_f32 v39, s[14:15], v38, v38, 2.0
	v_rcp_f32_e32 v40, v39
	s_nop 0
	v_fma_f32 v49, -v39, v40, 1.0
	v_fmac_f32_e32 v40, v49, v40
	v_div_scale_f32 v49, vcc, 2.0, v38, 2.0
	v_mul_f32_e32 v50, v49, v40
	v_fma_f32 v51, -v39, v50, v49
	v_fmac_f32_e32 v50, v51, v40
	v_fma_f32 v39, -v39, v50, v49
	v_div_fmas_f32 v39, v39, v40, v50
	v_div_fixup_f32 v38, v39, v38, 2.0
	v_sub_f32_e32 v38, 1.0, v38
	v_add_f32_e32 v38, 1.0, v38
	v_mul_f32_e32 v40, v34, v38
	v_lshlrev_b32_e32 v34, 16, v41
	v_mul_f32_e32 v38, 0x3d372713, v34
	v_mul_f32_e32 v38, v38, v34
	v_fma_f32 v38, v38, v34, v34
	v_mul_f32_e32 v38, 0x3f4c422a, v38
	v_add_f32_e32 v38, v38, v38
	v_mul_f32_e32 v38, 0x3fb8aa3b, v38
	v_exp_f32_e32 v38, v38
	v_mul_f32_e32 v34, 0.5, v34
	v_add_f32_e32 v38, 1.0, v38
	v_div_scale_f32 v39, s[14:15], v38, v38, 2.0
	v_rcp_f32_e32 v49, v39
	s_nop 0
	v_fma_f32 v50, -v39, v49, 1.0
	v_fmac_f32_e32 v49, v50, v49
	v_div_scale_f32 v50, vcc, 2.0, v38, 2.0
	v_mul_f32_e32 v51, v50, v49
	v_fma_f32 v52, -v39, v51, v50
	v_fmac_f32_e32 v51, v52, v49
	v_fma_f32 v39, -v39, v51, v50
	v_div_fmas_f32 v39, v39, v49, v51
	v_div_fixup_f32 v38, v39, v38, 2.0
	v_sub_f32_e32 v38, 1.0, v38
	v_add_f32_e32 v38, 1.0, v38
	v_mul_f32_e32 v49, v34, v38
	v_and_b32_e32 v34, 0xffff0000, v41
	v_mul_f32_e32 v38, 0x3d372713, v34
	v_mul_f32_e32 v38, v38, v34
	v_fma_f32 v38, v38, v34, v34
	v_mul_f32_e32 v38, 0x3f4c422a, v38
	v_add_f32_e32 v38, v38, v38
	v_mul_f32_e32 v38, 0x3fb8aa3b, v38
	v_exp_f32_e32 v38, v38
	v_mul_f32_e32 v34, 0.5, v34
	v_add_f32_e32 v38, 1.0, v38
	v_div_scale_f32 v39, s[14:15], v38, v38, 2.0
	v_rcp_f32_e32 v41, v39
	s_nop 0
	v_fma_f32 v50, -v39, v41, 1.0
	v_fmac_f32_e32 v41, v50, v41
	v_div_scale_f32 v50, vcc, 2.0, v38, 2.0
	v_mul_f32_e32 v51, v50, v41
	v_fma_f32 v52, -v39, v51, v50
	v_fmac_f32_e32 v51, v52, v41
	v_fma_f32 v39, -v39, v51, v50
	v_div_fmas_f32 v39, v39, v41, v51
	v_div_fixup_f32 v38, v39, v38, 2.0
	v_sub_f32_e32 v38, 1.0, v38
	v_add_f32_e32 v38, 1.0, v38
	v_mul_f32_e32 v41, v34, v38
	v_and_b32_e32 v34, 0xffff0000, v35
	v_lshlrev_b32_e32 v35, 16, v35
	v_mul_f32_e32 v38, 0x3d372713, v35
	v_mul_f32_e32 v38, v38, v35
	v_mov_b32_e32 v39, v35
	v_fmac_f32_e32 v39, v38, v39
	v_mul_f32_e32 v38, 0x3f4c422a, v39
	v_add_f32_e32 v38, v38, v38
	v_mul_f32_e32 v38, 0x3fb8aa3b, v38
	v_exp_f32_e32 v39, v38
	v_mul_f32_e32 v38, 0x3d372713, v34
	v_mul_f32_e32 v38, v38, v34
	v_mov_b32_e32 v51, v34
	v_fmac_f32_e32 v51, v38, v51
	v_mul_f32_e32 v38, 0x3f4c422a, v51
	v_add_f32_e32 v38, v38, v38
	v_mul_f32_e32 v38, 0x3fb8aa3b, v38
	v_exp_f32_e32 v38, v38
	v_pk_mul_f32 v[34:35], v[34:35], 0.5 op_sel_hi:[1,0]
	v_mul_f32_e32 v50, v45, v45
	v_fmac_f32_e32 v50, v44, v44
	v_pk_add_f32 v[38:39], v[38:39], 1.0 op_sel_hi:[1,0]
	s_nop 0
	v_div_scale_f32 v51, s[14:15], v39, v39, 2.0
	v_rcp_f32_e32 v52, v51
	s_nop 0
	v_fma_f32 v53, -v51, v52, 1.0
	v_fmac_f32_e32 v52, v53, v52
	v_div_scale_f32 v53, vcc, 2.0, v39, 2.0
	v_mul_f32_e32 v54, v53, v52
	v_fma_f32 v55, -v51, v54, v53
	v_fmac_f32_e32 v54, v55, v52
	v_fma_f32 v51, -v51, v54, v53
	v_div_fmas_f32 v51, v51, v52, v54
	v_div_fixup_f32 v39, v51, v39, 2.0
	v_div_scale_f32 v51, s[14:15], v38, v38, 2.0
	v_rcp_f32_e32 v52, v51
	s_nop 0
	v_fma_f32 v53, -v51, v52, 1.0
	v_fmac_f32_e32 v52, v53, v52
	v_div_scale_f32 v53, vcc, 2.0, v38, 2.0
	v_mul_f32_e32 v54, v53, v52
	v_fma_f32 v55, -v51, v54, v53
	v_fmac_f32_e32 v54, v55, v52
	v_fma_f32 v51, -v51, v54, v53
	v_div_fmas_f32 v51, v51, v52, v54
	v_div_fixup_f32 v38, v51, v38, 2.0
	v_pk_add_f32 v[38:39], v[38:39], 1.0 op_sel_hi:[1,0] neg_lo:[1,0] neg_hi:[1,0]
	s_nop 0
	v_pk_add_f32 v[38:39], v[38:39], 1.0 op_sel_hi:[1,0]
	s_nop 0
	v_pk_mul_f32 v[34:35], v[34:35], v[38:39]
	s_nop 0
	v_pk_mul_f32 v[38:39], v[34:35], v[34:35]
	s_nop 0
	v_add_f32_e32 v39, v39, v50
	v_add_f32_e32 v52, v38, v39
	v_lshlrev_b32_e32 v39, 16, v36
	v_and_b32_e32 v38, 0xffff0000, v36
	v_mul_f32_e32 v36, 0x3d372713, v39
	v_mul_f32_e32 v36, v36, v39
	v_mov_b32_e32 v50, v39
	v_fmac_f32_e32 v50, v36, v50
	v_mul_f32_e32 v36, 0x3f4c422a, v50
	v_add_f32_e32 v36, v36, v36
	v_mul_f32_e32 v36, 0x3fb8aa3b, v36
	v_exp_f32_e32 v51, v36
	v_mul_f32_e32 v36, 0x3d372713, v38
	v_mul_f32_e32 v36, v36, v38
	v_mov_b32_e32 v50, v38
	v_fmac_f32_e32 v50, v36, v50
	v_mul_f32_e32 v36, 0x3f4c422a, v50
	v_add_f32_e32 v36, v36, v36
	v_mul_f32_e32 v36, 0x3fb8aa3b, v36
	v_exp_f32_e32 v50, v36
	v_pk_mul_f32 v[38:39], v[38:39], 0.5 op_sel_hi:[1,0]
	v_pk_add_f32 v[50:51], v[50:51], 1.0 op_sel_hi:[1,0]
	s_nop 0
	v_div_scale_f32 v36, s[14:15], v51, v51, 2.0
	v_rcp_f32_e32 v53, v36
	s_nop 0
	v_fma_f32 v54, -v36, v53, 1.0
	v_fmac_f32_e32 v53, v54, v53
	v_div_scale_f32 v54, vcc, 2.0, v51, 2.0
	v_mul_f32_e32 v55, v54, v53
	v_fma_f32 v56, -v36, v55, v54
	v_fmac_f32_e32 v55, v56, v53
	v_fma_f32 v36, -v36, v55, v54
	v_div_fmas_f32 v36, v36, v53, v55
	v_div_fixup_f32 v51, v36, v51, 2.0
	v_div_scale_f32 v36, s[14:15], v50, v50, 2.0
	v_rcp_f32_e32 v53, v36
	s_nop 0
	v_fma_f32 v54, -v36, v53, 1.0
	v_fmac_f32_e32 v53, v54, v53
	v_div_scale_f32 v54, vcc, 2.0, v50, 2.0
	v_mul_f32_e32 v55, v54, v53
	v_fma_f32 v56, -v36, v55, v54
	v_fmac_f32_e32 v55, v56, v53
	v_fma_f32 v36, -v36, v55, v54
	v_div_fmas_f32 v36, v36, v53, v55
	v_div_fixup_f32 v50, v36, v50, 2.0
	v_pk_add_f32 v[50:51], v[50:51], 1.0 op_sel_hi:[1,0] neg_lo:[1,0] neg_hi:[1,0]
	s_nop 0
	v_pk_add_f32 v[50:51], v[50:51], 1.0 op_sel_hi:[1,0]
	s_nop 0
	v_pk_mul_f32 v[38:39], v[38:39], v[50:51]
	s_nop 0
	v_pk_mul_f32 v[50:51], v[38:39], v[38:39]
	s_nop 0
	v_add_f32_e32 v36, v51, v52
	v_add_f32_e32 v52, v50, v36
	v_and_b32_e32 v36, 0xffff0000, v37
	v_lshlrev_b32_e32 v37, 16, v37
	v_mul_f32_e32 v50, 0x3d372713, v37
	v_mul_f32_e32 v50, v50, v37
	v_mov_b32_e32 v51, v37
	v_fmac_f32_e32 v51, v50, v51
	v_mul_f32_e32 v50, 0x3f4c422a, v51
	v_add_f32_e32 v50, v50, v50
	v_mul_f32_e32 v50, 0x3fb8aa3b, v50
	v_exp_f32_e32 v51, v50
	v_mul_f32_e32 v50, 0x3d372713, v36
	v_mul_f32_e32 v50, v50, v36
	v_mov_b32_e32 v53, v36
	v_fmac_f32_e32 v53, v50, v53
	v_mul_f32_e32 v50, 0x3f4c422a, v53
	v_add_f32_e32 v50, v50, v50
	v_mul_f32_e32 v50, 0x3fb8aa3b, v50
	v_exp_f32_e32 v50, v50
	v_pk_mul_f32 v[36:37], v[36:37], 0.5 op_sel_hi:[1,0]
	v_pk_add_f32 v[50:51], v[50:51], 1.0 op_sel_hi:[1,0]
	s_nop 0
	v_div_scale_f32 v53, s[14:15], v51, v51, 2.0
	v_rcp_f32_e32 v54, v53
	s_nop 0
	v_fma_f32 v55, -v53, v54, 1.0
	v_fmac_f32_e32 v54, v55, v54
	v_div_scale_f32 v55, vcc, 2.0, v51, 2.0
	v_mul_f32_e32 v56, v55, v54
	v_fma_f32 v57, -v53, v56, v55
	v_fmac_f32_e32 v56, v57, v54
	v_fma_f32 v53, -v53, v56, v55
	v_div_fmas_f32 v53, v53, v54, v56
	v_div_fixup_f32 v51, v53, v51, 2.0
	v_div_scale_f32 v53, s[14:15], v50, v50, 2.0
	v_rcp_f32_e32 v54, v53
	s_nop 0
	v_fma_f32 v55, -v53, v54, 1.0
	v_fmac_f32_e32 v54, v55, v54
	v_div_scale_f32 v55, vcc, 2.0, v50, 2.0
	v_mul_f32_e32 v56, v55, v54
	v_fma_f32 v57, -v53, v56, v55
	v_fmac_f32_e32 v56, v57, v54
	v_fma_f32 v53, -v53, v56, v55
	v_div_fmas_f32 v53, v53, v54, v56
	v_div_fixup_f32 v50, v53, v50, 2.0
	v_pk_add_f32 v[50:51], v[50:51], 1.0 op_sel_hi:[1,0] neg_lo:[1,0] neg_hi:[1,0]
	s_nop 0
	v_pk_add_f32 v[50:51], v[50:51], 1.0 op_sel_hi:[1,0]
	s_nop 0
	v_pk_mul_f32 v[50:51], v[36:37], v[50:51]
	s_nop 0
	v_pk_mul_f32 v[36:37], v[50:51], v[50:51]
	s_nop 0
	v_add_f32_e32 v37, v37, v52
	v_add_f32_e32 v36, v36, v37
	ds_bpermute_b32 v37, v106, v36
	s_waitcnt lgkmcnt(0)
	v_add_f32_e32 v36, v36, v37
	ds_bpermute_b32 v37, v107, v36
	s_waitcnt lgkmcnt(0)
	v_add_f32_e32 v36, v36, v37
	ds_bpermute_b32 v37, v108, v36
	s_waitcnt lgkmcnt(0)
	v_add_f32_e32 v36, v36, v37
	ds_bpermute_b32 v37, v109, v36
	s_waitcnt lgkmcnt(0)
	v_add_f32_e32 v36, v36, v37
	ds_bpermute_b32 v37, v110, v36
	s_waitcnt lgkmcnt(0)
	v_add_f32_e32 v36, v36, v37
	v_fmamk_f32 v36, v36, 0x3b800000, v243
	v_cmp_gt_f32_e32 vcc, s3, v36
	v_mul_f32_e32 v37, 0x4b800000, v36
	s_nop 0
	v_cndmask_b32_e32 v36, v36, v37, vcc
	v_rsq_f32_e32 v36, v36
	s_nop 0
	v_mul_f32_e32 v37, 0x45800000, v36
	v_cndmask_b32_e32 v52, v36, v37, vcc
	v_mul_f32_e32 v36, v44, v52
	v_mul_f32_e32 v37, v45, v52
	v_mul_f32_e32 v34, v34, v52
	v_mul_f32_e32 v36, v70, v36
	v_mul_f32_e32 v37, v71, v37
	v_mul_f32_e32 v35, v35, v52
	v_mul_f32_e32 v34, v73, v34
	v_cvt_pk_bf16_f32 v36, v36, v37
	v_cvt_pk_bf16_f32 v43, v46, v47
	v_mul_f32_e32 v35, v72, v35
	v_cvt_pk_bf16_f32 v37, v35, v34
	v_mul_f32_e32 v34, v39, v52
	v_mul_f32_e32 v34, v66, v34
	v_mul_f32_e32 v35, v38, v52
	v_cvt_pk_bf16_f32 v44, v48, v40
	v_mul_f32_e32 v35, v67, v35
	v_cvt_pk_bf16_f32 v38, v34, v35
	v_mul_f32_e32 v34, v51, v52
	v_mul_f32_e32 v34, v68, v34
	v_mul_f32_e32 v35, v50, v52
	v_cvt_pk_bf16_f32 v45, v49, v41
	v_mul_f32_e32 v35, v69, v35
	v_cvt_pk_bf16_f32 v39, v34, v35
	v_lshlrev_b32_e32 v34, 16, v30
	v_mul_f32_e32 v35, 0x3d372713, v34
	v_mul_f32_e32 v35, v35, v34
	v_fma_f32 v35, v35, v34, v34
	v_mul_f32_e32 v35, 0x3f4c422a, v35
	v_add_f32_e32 v35, v35, v35
	v_mul_f32_e32 v35, 0x3fb8aa3b, v35
	v_exp_f32_e32 v35, v35
	ds_write_b128 v111, v[42:45] offset:26112
	ds_write_b128 v112, v[36:39] offset:26112
	v_mul_f32_e32 v34, 0.5, v34
	v_and_b32_e32 v30, 0xffff0000, v30
	v_add_f32_e32 v35, 1.0, v35
	v_div_scale_f32 v36, s[14:15], v35, v35, 2.0
	v_rcp_f32_e32 v37, v36
	s_nop 0
	v_fma_f32 v38, -v36, v37, 1.0
	v_fmac_f32_e32 v37, v38, v37
	v_div_scale_f32 v38, vcc, 2.0, v35, 2.0
	v_mul_f32_e32 v39, v38, v37
	v_fma_f32 v40, -v36, v39, v38
	v_fmac_f32_e32 v39, v40, v37
	v_fma_f32 v36, -v36, v39, v38
	v_div_fmas_f32 v36, v36, v37, v39
	v_div_fixup_f32 v35, v36, v35, 2.0
	v_sub_f32_e32 v35, 1.0, v35
	v_add_f32_e32 v35, 1.0, v35
	v_mul_f32_e32 v34, v34, v35
	v_mul_f32_e32 v35, 0x3d372713, v30
	v_mul_f32_e32 v35, v35, v30
	v_fma_f32 v35, v35, v30, v30
	v_mul_f32_e32 v35, 0x3f4c422a, v35
	v_add_f32_e32 v35, v35, v35
	v_mul_f32_e32 v35, 0x3fb8aa3b, v35
	v_exp_f32_e32 v35, v35
	v_mul_f32_e32 v30, 0.5, v30
	v_add_f32_e32 v35, 1.0, v35
	v_div_scale_f32 v36, s[14:15], v35, v35, 2.0
	v_rcp_f32_e32 v37, v36
	s_nop 0
	v_fma_f32 v38, -v36, v37, 1.0
	v_fmac_f32_e32 v37, v38, v37
	v_div_scale_f32 v38, vcc, 2.0, v35, 2.0
	v_mul_f32_e32 v39, v38, v37
	v_fma_f32 v40, -v36, v39, v38
	v_fmac_f32_e32 v39, v40, v37
	v_fma_f32 v36, -v36, v39, v38
	v_div_fmas_f32 v36, v36, v37, v39
	v_div_fixup_f32 v35, v36, v35, 2.0
	v_sub_f32_e32 v35, 1.0, v35
	v_add_f32_e32 v35, 1.0, v35
	v_mul_f32_e32 v35, v30, v35
	v_lshlrev_b32_e32 v30, 16, v26
	v_mul_f32_e32 v36, 0x3d372713, v30
	v_mul_f32_e32 v36, v36, v30
	v_fma_f32 v36, v36, v30, v30
	v_mul_f32_e32 v36, 0x3f4c422a, v36
	v_add_f32_e32 v36, v36, v36
	v_mul_f32_e32 v36, 0x3fb8aa3b, v36
	v_exp_f32_e32 v36, v36
	v_mul_f32_e32 v30, 0.5, v30
	v_and_b32_e32 v26, 0xffff0000, v26
	v_cvt_pk_bf16_f32 v34, v34, v35
	v_add_f32_e32 v36, 1.0, v36
	v_div_scale_f32 v37, s[14:15], v36, v36, 2.0
	v_rcp_f32_e32 v38, v37
	s_nop 0
	v_fma_f32 v39, -v37, v38, 1.0
	v_fmac_f32_e32 v38, v39, v38
	v_div_scale_f32 v39, vcc, 2.0, v36, 2.0
	v_mul_f32_e32 v40, v39, v38
	v_fma_f32 v41, -v37, v40, v39
	v_fmac_f32_e32 v40, v41, v38
	v_fma_f32 v37, -v37, v40, v39
	v_div_fmas_f32 v37, v37, v38, v40
	v_div_fixup_f32 v36, v37, v36, 2.0
	v_sub_f32_e32 v36, 1.0, v36
	v_add_f32_e32 v36, 1.0, v36
	v_mul_f32_e32 v36, v30, v36
	v_mul_f32_e32 v30, 0x3d372713, v26
	v_mul_f32_e32 v30, v30, v26
	v_fma_f32 v30, v30, v26, v26
	v_mul_f32_e32 v30, 0x3f4c422a, v30
	v_add_f32_e32 v30, v30, v30
	v_mul_f32_e32 v30, 0x3fb8aa3b, v30
	v_exp_f32_e32 v30, v30
	v_mul_f32_e32 v26, 0.5, v26
	v_add_f32_e32 v30, 1.0, v30
	v_div_scale_f32 v37, s[14:15], v30, v30, 2.0
	v_rcp_f32_e32 v38, v37
	s_nop 0
	v_fma_f32 v39, -v37, v38, 1.0
	v_fmac_f32_e32 v38, v39, v38
	v_div_scale_f32 v39, vcc, 2.0, v30, 2.0
	v_mul_f32_e32 v40, v39, v38
	v_fma_f32 v41, -v37, v40, v39
	v_fmac_f32_e32 v40, v41, v38
	v_fma_f32 v37, -v37, v40, v39
	v_div_fmas_f32 v37, v37, v38, v40
	v_div_fixup_f32 v30, v37, v30, 2.0
	v_sub_f32_e32 v30, 1.0, v30
	v_add_f32_e32 v30, 1.0, v30
	v_mul_f32_e32 v37, v26, v30
	v_lshlrev_b32_e32 v26, 16, v31
	v_mul_f32_e32 v30, 0x3d372713, v26
	v_mul_f32_e32 v30, v30, v26
	v_fma_f32 v30, v30, v26, v26
	v_mul_f32_e32 v30, 0x3f4c422a, v30
	v_add_f32_e32 v30, v30, v30
	v_mul_f32_e32 v30, 0x3fb8aa3b, v30
	v_exp_f32_e32 v30, v30
	v_mul_f32_e32 v26, 0.5, v26
	v_add_f32_e32 v30, 1.0, v30
	v_div_scale_f32 v38, s[14:15], v30, v30, 2.0
	v_rcp_f32_e32 v39, v38
	s_nop 0
	v_fma_f32 v40, -v38, v39, 1.0
	v_fmac_f32_e32 v39, v40, v39
	v_div_scale_f32 v40, vcc, 2.0, v30, 2.0
	v_mul_f32_e32 v41, v40, v39
	v_fma_f32 v42, -v38, v41, v40
	v_fmac_f32_e32 v41, v42, v39
	v_fma_f32 v38, -v38, v41, v40
	v_div_fmas_f32 v38, v38, v39, v41
	v_div_fixup_f32 v30, v38, v30, 2.0
	v_sub_f32_e32 v30, 1.0, v30
	v_add_f32_e32 v30, 1.0, v30
	v_mul_f32_e32 v38, v26, v30
	v_and_b32_e32 v26, 0xffff0000, v31
	v_mul_f32_e32 v30, 0x3d372713, v26
	v_mul_f32_e32 v30, v30, v26
	v_fma_f32 v30, v30, v26, v26
	v_mul_f32_e32 v30, 0x3f4c422a, v30
	v_add_f32_e32 v30, v30, v30
	v_mul_f32_e32 v30, 0x3fb8aa3b, v30
	v_exp_f32_e32 v30, v30
	v_mul_f32_e32 v26, 0.5, v26
	v_add_f32_e32 v30, 1.0, v30
	v_div_scale_f32 v31, s[14:15], v30, v30, 2.0
	v_rcp_f32_e32 v39, v31
	s_nop 0
	v_fma_f32 v40, -v31, v39, 1.0
	v_fmac_f32_e32 v39, v40, v39
	v_div_scale_f32 v40, vcc, 2.0, v30, 2.0
	v_mul_f32_e32 v41, v40, v39
	v_fma_f32 v42, -v31, v41, v40
	v_fmac_f32_e32 v41, v42, v39
	v_fma_f32 v31, -v31, v41, v40
	v_div_fmas_f32 v31, v31, v39, v41
	v_div_fixup_f32 v30, v31, v30, 2.0
	v_sub_f32_e32 v30, 1.0, v30
	v_add_f32_e32 v30, 1.0, v30
	v_mul_f32_e32 v39, v26, v30
	v_lshlrev_b32_e32 v26, 16, v32
	v_mul_f32_e32 v30, 0x3d372713, v26
	v_mul_f32_e32 v30, v30, v26
	v_fma_f32 v30, v30, v26, v26
	v_mul_f32_e32 v30, 0x3f4c422a, v30
	v_add_f32_e32 v30, v30, v30
	v_mul_f32_e32 v30, 0x3fb8aa3b, v30
	v_exp_f32_e32 v30, v30
	v_mul_f32_e32 v26, 0.5, v26
	v_add_f32_e32 v30, 1.0, v30
	v_div_scale_f32 v31, s[14:15], v30, v30, 2.0
	v_rcp_f32_e32 v40, v31
	s_nop 0
	v_fma_f32 v41, -v31, v40, 1.0
	v_fmac_f32_e32 v40, v41, v40
	v_div_scale_f32 v41, vcc, 2.0, v30, 2.0
	v_mul_f32_e32 v42, v41, v40
	v_fma_f32 v43, -v31, v42, v41
	v_fmac_f32_e32 v42, v43, v40
	v_fma_f32 v31, -v31, v42, v41
	v_div_fmas_f32 v31, v31, v40, v42
	v_div_fixup_f32 v30, v31, v30, 2.0
	v_sub_f32_e32 v30, 1.0, v30
	v_add_f32_e32 v30, 1.0, v30
	v_mul_f32_e32 v40, v26, v30
	v_and_b32_e32 v26, 0xffff0000, v32
	v_mul_f32_e32 v30, 0x3d372713, v26
	v_mul_f32_e32 v30, v30, v26
	v_fma_f32 v30, v30, v26, v26
	v_mul_f32_e32 v30, 0x3f4c422a, v30
	v_add_f32_e32 v30, v30, v30
	v_mul_f32_e32 v30, 0x3fb8aa3b, v30
	v_exp_f32_e32 v30, v30
	v_mul_f32_e32 v26, 0.5, v26
	v_add_f32_e32 v30, 1.0, v30
	v_div_scale_f32 v31, s[14:15], v30, v30, 2.0
	v_rcp_f32_e32 v32, v31
	s_nop 0
	v_fma_f32 v41, -v31, v32, 1.0
	v_fmac_f32_e32 v32, v41, v32
	v_div_scale_f32 v41, vcc, 2.0, v30, 2.0
	v_mul_f32_e32 v42, v41, v32
	v_fma_f32 v43, -v31, v42, v41
	v_fmac_f32_e32 v42, v43, v32
	v_fma_f32 v31, -v31, v42, v41
	v_div_fmas_f32 v31, v31, v32, v42
	v_div_fixup_f32 v30, v31, v30, 2.0
	v_sub_f32_e32 v30, 1.0, v30
	v_add_f32_e32 v30, 1.0, v30
	v_mul_f32_e32 v32, v26, v30
	v_lshlrev_b32_e32 v26, 16, v33
	v_mul_f32_e32 v30, 0x3d372713, v26
	v_mul_f32_e32 v30, v30, v26
	v_fma_f32 v30, v30, v26, v26
	v_mul_f32_e32 v30, 0x3f4c422a, v30
	v_add_f32_e32 v30, v30, v30
	v_mul_f32_e32 v30, 0x3fb8aa3b, v30
	v_exp_f32_e32 v30, v30
	v_mul_f32_e32 v26, 0.5, v26
	v_add_f32_e32 v30, 1.0, v30
	v_div_scale_f32 v31, s[14:15], v30, v30, 2.0
	v_rcp_f32_e32 v41, v31
	s_nop 0
	v_fma_f32 v42, -v31, v41, 1.0
	v_fmac_f32_e32 v41, v42, v41
	v_div_scale_f32 v42, vcc, 2.0, v30, 2.0
	v_mul_f32_e32 v43, v42, v41
	v_fma_f32 v44, -v31, v43, v42
	v_fmac_f32_e32 v43, v44, v41
	v_fma_f32 v31, -v31, v43, v42
	v_div_fmas_f32 v31, v31, v41, v43
	v_div_fixup_f32 v30, v31, v30, 2.0
	v_sub_f32_e32 v30, 1.0, v30
	v_add_f32_e32 v30, 1.0, v30
	v_mul_f32_e32 v41, v26, v30
	v_and_b32_e32 v26, 0xffff0000, v33
	v_mul_f32_e32 v30, 0x3d372713, v26
	v_mul_f32_e32 v30, v30, v26
	v_fma_f32 v30, v30, v26, v26
	v_mul_f32_e32 v30, 0x3f4c422a, v30
	v_add_f32_e32 v30, v30, v30
	v_mul_f32_e32 v30, 0x3fb8aa3b, v30
	v_exp_f32_e32 v30, v30
	v_mul_f32_e32 v26, 0.5, v26
	v_add_f32_e32 v30, 1.0, v30
	v_div_scale_f32 v31, s[14:15], v30, v30, 2.0
	v_rcp_f32_e32 v33, v31
	s_nop 0
	v_fma_f32 v42, -v31, v33, 1.0
	v_fmac_f32_e32 v33, v42, v33
	v_div_scale_f32 v42, vcc, 2.0, v30, 2.0
	v_mul_f32_e32 v43, v42, v33
	v_fma_f32 v44, -v31, v43, v42
	v_fmac_f32_e32 v43, v44, v33
	v_fma_f32 v31, -v31, v43, v42
	v_div_fmas_f32 v31, v31, v33, v43
	v_div_fixup_f32 v30, v31, v30, 2.0
	v_sub_f32_e32 v30, 1.0, v30
	v_add_f32_e32 v30, 1.0, v30
	v_mul_f32_e32 v33, v26, v30
	v_and_b32_e32 v26, 0xffff0000, v27
	v_lshlrev_b32_e32 v27, 16, v27
	v_mul_f32_e32 v30, 0x3d372713, v27
	v_mul_f32_e32 v30, v30, v27
	v_mov_b32_e32 v31, v27
	v_fmac_f32_e32 v31, v30, v31
	v_mul_f32_e32 v30, 0x3f4c422a, v31
	v_add_f32_e32 v30, v30, v30
	v_mul_f32_e32 v30, 0x3fb8aa3b, v30
	v_exp_f32_e32 v31, v30
	v_mul_f32_e32 v30, 0x3d372713, v26
	v_mul_f32_e32 v30, v30, v26
	v_mov_b32_e32 v43, v26
	v_fmac_f32_e32 v43, v30, v43
	v_mul_f32_e32 v30, 0x3f4c422a, v43
	v_add_f32_e32 v30, v30, v30
	v_mul_f32_e32 v30, 0x3fb8aa3b, v30
	v_exp_f32_e32 v30, v30
	v_pk_mul_f32 v[26:27], v[26:27], 0.5 op_sel_hi:[1,0]
	v_mul_f32_e32 v42, v37, v37
	v_fmac_f32_e32 v42, v36, v36
	v_pk_add_f32 v[30:31], v[30:31], 1.0 op_sel_hi:[1,0]
	s_nop 0
	v_div_scale_f32 v43, s[14:15], v31, v31, 2.0
	v_rcp_f32_e32 v44, v43
	s_nop 0
	v_fma_f32 v45, -v43, v44, 1.0
	v_fmac_f32_e32 v44, v45, v44
	v_div_scale_f32 v45, vcc, 2.0, v31, 2.0
	v_mul_f32_e32 v46, v45, v44
	v_fma_f32 v47, -v43, v46, v45
	v_fmac_f32_e32 v46, v47, v44
	v_fma_f32 v43, -v43, v46, v45
	v_div_fmas_f32 v43, v43, v44, v46
	v_div_fixup_f32 v31, v43, v31, 2.0
	v_div_scale_f32 v43, s[14:15], v30, v30, 2.0
	v_rcp_f32_e32 v44, v43
	s_nop 0
	v_fma_f32 v45, -v43, v44, 1.0
	v_fmac_f32_e32 v44, v45, v44
	v_div_scale_f32 v45, vcc, 2.0, v30, 2.0
	v_mul_f32_e32 v46, v45, v44
	v_fma_f32 v47, -v43, v46, v45
	v_fmac_f32_e32 v46, v47, v44
	v_fma_f32 v43, -v43, v46, v45
	v_div_fmas_f32 v43, v43, v44, v46
	v_div_fixup_f32 v30, v43, v30, 2.0
	v_pk_add_f32 v[30:31], v[30:31], 1.0 op_sel_hi:[1,0] neg_lo:[1,0] neg_hi:[1,0]
	s_nop 0
	v_pk_add_f32 v[30:31], v[30:31], 1.0 op_sel_hi:[1,0]
	s_nop 0
	v_pk_mul_f32 v[26:27], v[26:27], v[30:31]
	s_nop 0
	v_pk_mul_f32 v[30:31], v[26:27], v[26:27]
	s_nop 0
	v_add_f32_e32 v31, v31, v42
	v_add_f32_e32 v44, v30, v31
	v_lshlrev_b32_e32 v31, 16, v28
	v_and_b32_e32 v30, 0xffff0000, v28
	v_mul_f32_e32 v28, 0x3d372713, v31
	v_mul_f32_e32 v28, v28, v31
	v_mov_b32_e32 v42, v31
	v_fmac_f32_e32 v42, v28, v42
	v_mul_f32_e32 v28, 0x3f4c422a, v42
	v_add_f32_e32 v28, v28, v28
	v_mul_f32_e32 v28, 0x3fb8aa3b, v28
	v_exp_f32_e32 v43, v28
	v_mul_f32_e32 v28, 0x3d372713, v30
	v_mul_f32_e32 v28, v28, v30
	v_mov_b32_e32 v42, v30
	v_fmac_f32_e32 v42, v28, v42
	v_mul_f32_e32 v28, 0x3f4c422a, v42
	v_add_f32_e32 v28, v28, v28
	v_mul_f32_e32 v28, 0x3fb8aa3b, v28
	v_exp_f32_e32 v42, v28
	v_pk_mul_f32 v[30:31], v[30:31], 0.5 op_sel_hi:[1,0]
	v_pk_add_f32 v[42:43], v[42:43], 1.0 op_sel_hi:[1,0]
	s_nop 0
	v_div_scale_f32 v28, s[14:15], v43, v43, 2.0
	v_rcp_f32_e32 v45, v28
	s_nop 0
	v_fma_f32 v46, -v28, v45, 1.0
	v_fmac_f32_e32 v45, v46, v45
	v_div_scale_f32 v46, vcc, 2.0, v43, 2.0
	v_mul_f32_e32 v47, v46, v45
	v_fma_f32 v48, -v28, v47, v46
	v_fmac_f32_e32 v47, v48, v45
	v_fma_f32 v28, -v28, v47, v46
	v_div_fmas_f32 v28, v28, v45, v47
	v_div_fixup_f32 v43, v28, v43, 2.0
	v_div_scale_f32 v28, s[14:15], v42, v42, 2.0
	v_rcp_f32_e32 v45, v28
	s_nop 0
	v_fma_f32 v46, -v28, v45, 1.0
	v_fmac_f32_e32 v45, v46, v45
	v_div_scale_f32 v46, vcc, 2.0, v42, 2.0
	v_mul_f32_e32 v47, v46, v45
	v_fma_f32 v48, -v28, v47, v46
	v_fmac_f32_e32 v47, v48, v45
	v_fma_f32 v28, -v28, v47, v46
	v_div_fmas_f32 v28, v28, v45, v47
	v_div_fixup_f32 v42, v28, v42, 2.0
	v_pk_add_f32 v[42:43], v[42:43], 1.0 op_sel_hi:[1,0] neg_lo:[1,0] neg_hi:[1,0]
	s_nop 0
	v_pk_add_f32 v[42:43], v[42:43], 1.0 op_sel_hi:[1,0]
	s_nop 0
	v_pk_mul_f32 v[30:31], v[30:31], v[42:43]
	s_nop 0
	v_pk_mul_f32 v[42:43], v[30:31], v[30:31]
	s_nop 0
	v_add_f32_e32 v28, v43, v44
	v_add_f32_e32 v44, v42, v28
	v_and_b32_e32 v28, 0xffff0000, v29
	v_lshlrev_b32_e32 v29, 16, v29
	v_mul_f32_e32 v42, 0x3d372713, v29
	v_mul_f32_e32 v42, v42, v29
	v_mov_b32_e32 v43, v29
	v_fmac_f32_e32 v43, v42, v43
	v_mul_f32_e32 v42, 0x3f4c422a, v43
	v_add_f32_e32 v42, v42, v42
	v_mul_f32_e32 v42, 0x3fb8aa3b, v42
	v_exp_f32_e32 v43, v42
	v_mul_f32_e32 v42, 0x3d372713, v28
	v_mul_f32_e32 v42, v42, v28
	v_mov_b32_e32 v45, v28
	v_fmac_f32_e32 v45, v42, v45
	v_mul_f32_e32 v42, 0x3f4c422a, v45
	v_add_f32_e32 v42, v42, v42
	v_mul_f32_e32 v42, 0x3fb8aa3b, v42
	v_exp_f32_e32 v42, v42
	v_pk_mul_f32 v[28:29], v[28:29], 0.5 op_sel_hi:[1,0]
	v_pk_add_f32 v[42:43], v[42:43], 1.0 op_sel_hi:[1,0]
	s_nop 0
	v_div_scale_f32 v45, s[14:15], v43, v43, 2.0
	v_rcp_f32_e32 v46, v45
	s_nop 0
	v_fma_f32 v47, -v45, v46, 1.0
	v_fmac_f32_e32 v46, v47, v46
	v_div_scale_f32 v47, vcc, 2.0, v43, 2.0
	v_mul_f32_e32 v48, v47, v46
	v_fma_f32 v49, -v45, v48, v47
	v_fmac_f32_e32 v48, v49, v46
	v_fma_f32 v45, -v45, v48, v47
	v_div_fmas_f32 v45, v45, v46, v48
	v_div_fixup_f32 v43, v45, v43, 2.0
	v_div_scale_f32 v45, s[14:15], v42, v42, 2.0
	v_rcp_f32_e32 v46, v45
	s_nop 0
	v_fma_f32 v47, -v45, v46, 1.0
	v_fmac_f32_e32 v46, v47, v46
	v_div_scale_f32 v47, vcc, 2.0, v42, 2.0
	v_mul_f32_e32 v48, v47, v46
	v_fma_f32 v49, -v45, v48, v47
	v_fmac_f32_e32 v48, v49, v46
	v_fma_f32 v45, -v45, v48, v47
	v_div_fmas_f32 v45, v45, v46, v48
	v_div_fixup_f32 v42, v45, v42, 2.0
	v_pk_add_f32 v[42:43], v[42:43], 1.0 op_sel_hi:[1,0] neg_lo:[1,0] neg_hi:[1,0]
	s_nop 0
	v_pk_add_f32 v[42:43], v[42:43], 1.0 op_sel_hi:[1,0]
	s_nop 0
	v_pk_mul_f32 v[42:43], v[28:29], v[42:43]
	s_nop 0
	v_pk_mul_f32 v[28:29], v[42:43], v[42:43]
	s_nop 0
	v_add_f32_e32 v29, v29, v44
	v_add_f32_e32 v28, v28, v29
	ds_bpermute_b32 v29, v106, v28
	s_waitcnt lgkmcnt(0)
	v_add_f32_e32 v28, v28, v29
	ds_bpermute_b32 v29, v107, v28
	s_waitcnt lgkmcnt(0)
	v_add_f32_e32 v28, v28, v29
	ds_bpermute_b32 v29, v108, v28
	s_waitcnt lgkmcnt(0)
	v_add_f32_e32 v28, v28, v29
	ds_bpermute_b32 v29, v109, v28
	s_waitcnt lgkmcnt(0)
	v_add_f32_e32 v28, v28, v29
	ds_bpermute_b32 v29, v110, v28
	s_waitcnt lgkmcnt(0)
	v_add_f32_e32 v28, v28, v29
	v_fmamk_f32 v28, v28, 0x3b800000, v243
	v_cmp_gt_f32_e32 vcc, s3, v28
	v_mul_f32_e32 v29, 0x4b800000, v28
	s_nop 0
	v_cndmask_b32_e32 v28, v28, v29, vcc
	v_rsq_f32_e32 v28, v28
	s_nop 0
	v_mul_f32_e32 v29, 0x45800000, v28
	v_cndmask_b32_e32 v44, v28, v29, vcc
	v_mul_f32_e32 v28, v36, v44
	v_mul_f32_e32 v29, v37, v44
	v_mul_f32_e32 v26, v26, v44
	v_mul_f32_e32 v28, v70, v28
	v_mul_f32_e32 v29, v71, v29
	v_mul_f32_e32 v27, v27, v44
	v_mul_f32_e32 v26, v73, v26
	v_cvt_pk_bf16_f32 v28, v28, v29
	v_cvt_pk_bf16_f32 v35, v38, v39
	v_mul_f32_e32 v27, v72, v27
	v_cvt_pk_bf16_f32 v29, v27, v26
	v_mul_f32_e32 v26, v31, v44
	v_mul_f32_e32 v26, v66, v26
	v_mul_f32_e32 v27, v30, v44
	v_cvt_pk_bf16_f32 v36, v40, v32
	v_mul_f32_e32 v27, v67, v27
	v_cvt_pk_bf16_f32 v30, v26, v27
	v_mul_f32_e32 v26, v43, v44
	v_mul_f32_e32 v26, v68, v26
	v_mul_f32_e32 v27, v42, v44
	v_cvt_pk_bf16_f32 v37, v41, v33
	v_mul_f32_e32 v27, v69, v27
	v_cvt_pk_bf16_f32 v31, v26, v27
	v_lshlrev_b32_e32 v26, 16, v22
	v_mul_f32_e32 v27, 0x3d372713, v26
	v_mul_f32_e32 v27, v27, v26
	v_fma_f32 v27, v27, v26, v26
	v_mul_f32_e32 v27, 0x3f4c422a, v27
	v_add_f32_e32 v27, v27, v27
	v_mul_f32_e32 v27, 0x3fb8aa3b, v27
	v_exp_f32_e32 v27, v27
	ds_write_b128 v111, v[34:37] offset:34816
	ds_write_b128 v112, v[28:31] offset:34816
	v_mul_f32_e32 v26, 0.5, v26
	v_and_b32_e32 v22, 0xffff0000, v22
	v_add_f32_e32 v27, 1.0, v27
	v_div_scale_f32 v28, s[14:15], v27, v27, 2.0
	v_rcp_f32_e32 v29, v28
	s_nop 0
	v_fma_f32 v30, -v28, v29, 1.0
	v_fmac_f32_e32 v29, v30, v29
	v_div_scale_f32 v30, vcc, 2.0, v27, 2.0
	v_mul_f32_e32 v31, v30, v29
	v_fma_f32 v32, -v28, v31, v30
	v_fmac_f32_e32 v31, v32, v29
	v_fma_f32 v28, -v28, v31, v30
	v_div_fmas_f32 v28, v28, v29, v31
	v_div_fixup_f32 v27, v28, v27, 2.0
	v_sub_f32_e32 v27, 1.0, v27
	v_add_f32_e32 v27, 1.0, v27
	v_mul_f32_e32 v26, v26, v27
	v_mul_f32_e32 v27, 0x3d372713, v22
	v_mul_f32_e32 v27, v27, v22
	v_fma_f32 v27, v27, v22, v22
	v_mul_f32_e32 v27, 0x3f4c422a, v27
	v_add_f32_e32 v27, v27, v27
	v_mul_f32_e32 v27, 0x3fb8aa3b, v27
	v_exp_f32_e32 v27, v27
	v_mul_f32_e32 v22, 0.5, v22
	v_add_f32_e32 v27, 1.0, v27
	v_div_scale_f32 v28, s[14:15], v27, v27, 2.0
	v_rcp_f32_e32 v29, v28
	s_nop 0
	v_fma_f32 v30, -v28, v29, 1.0
	v_fmac_f32_e32 v29, v30, v29
	v_div_scale_f32 v30, vcc, 2.0, v27, 2.0
	v_mul_f32_e32 v31, v30, v29
	v_fma_f32 v32, -v28, v31, v30
	v_fmac_f32_e32 v31, v32, v29
	v_fma_f32 v28, -v28, v31, v30
	v_div_fmas_f32 v28, v28, v29, v31
	v_div_fixup_f32 v27, v28, v27, 2.0
	v_sub_f32_e32 v27, 1.0, v27
	v_add_f32_e32 v27, 1.0, v27
	v_mul_f32_e32 v27, v22, v27
	v_lshlrev_b32_e32 v22, 16, v18
	v_mul_f32_e32 v28, 0x3d372713, v22
	v_mul_f32_e32 v28, v28, v22
	v_fma_f32 v28, v28, v22, v22
	v_mul_f32_e32 v28, 0x3f4c422a, v28
	v_add_f32_e32 v28, v28, v28
	v_mul_f32_e32 v28, 0x3fb8aa3b, v28
	v_exp_f32_e32 v28, v28
	v_mul_f32_e32 v22, 0.5, v22
	v_and_b32_e32 v18, 0xffff0000, v18
	v_cvt_pk_bf16_f32 v26, v26, v27
	v_add_f32_e32 v28, 1.0, v28
	v_div_scale_f32 v29, s[14:15], v28, v28, 2.0
	v_rcp_f32_e32 v30, v29
	s_nop 0
	v_fma_f32 v31, -v29, v30, 1.0
	v_fmac_f32_e32 v30, v31, v30
	v_div_scale_f32 v31, vcc, 2.0, v28, 2.0
	v_mul_f32_e32 v32, v31, v30
	v_fma_f32 v33, -v29, v32, v31
	v_fmac_f32_e32 v32, v33, v30
	v_fma_f32 v29, -v29, v32, v31
	v_div_fmas_f32 v29, v29, v30, v32
	v_div_fixup_f32 v28, v29, v28, 2.0
	v_sub_f32_e32 v28, 1.0, v28
	v_add_f32_e32 v28, 1.0, v28
	v_mul_f32_e32 v28, v22, v28
	v_mul_f32_e32 v22, 0x3d372713, v18
	v_mul_f32_e32 v22, v22, v18
	v_fma_f32 v22, v22, v18, v18
	v_mul_f32_e32 v22, 0x3f4c422a, v22
	v_add_f32_e32 v22, v22, v22
	v_mul_f32_e32 v22, 0x3fb8aa3b, v22
	v_exp_f32_e32 v22, v22
	v_mul_f32_e32 v18, 0.5, v18
	v_add_f32_e32 v22, 1.0, v22
	v_div_scale_f32 v29, s[14:15], v22, v22, 2.0
	v_rcp_f32_e32 v30, v29
	s_nop 0
	v_fma_f32 v31, -v29, v30, 1.0
	v_fmac_f32_e32 v30, v31, v30
	v_div_scale_f32 v31, vcc, 2.0, v22, 2.0
	v_mul_f32_e32 v32, v31, v30
	v_fma_f32 v33, -v29, v32, v31
	v_fmac_f32_e32 v32, v33, v30
	v_fma_f32 v29, -v29, v32, v31
	v_div_fmas_f32 v29, v29, v30, v32
	v_div_fixup_f32 v22, v29, v22, 2.0
	v_sub_f32_e32 v22, 1.0, v22
	v_add_f32_e32 v22, 1.0, v22
	v_mul_f32_e32 v29, v18, v22
	v_lshlrev_b32_e32 v18, 16, v23
	v_mul_f32_e32 v22, 0x3d372713, v18
	v_mul_f32_e32 v22, v22, v18
	v_fma_f32 v22, v22, v18, v18
	v_mul_f32_e32 v22, 0x3f4c422a, v22
	v_add_f32_e32 v22, v22, v22
	v_mul_f32_e32 v22, 0x3fb8aa3b, v22
	v_exp_f32_e32 v22, v22
	v_mul_f32_e32 v18, 0.5, v18
	v_add_f32_e32 v22, 1.0, v22
	v_div_scale_f32 v30, s[14:15], v22, v22, 2.0
	v_rcp_f32_e32 v31, v30
	s_nop 0
	v_fma_f32 v32, -v30, v31, 1.0
	v_fmac_f32_e32 v31, v32, v31
	v_div_scale_f32 v32, vcc, 2.0, v22, 2.0
	v_mul_f32_e32 v33, v32, v31
	v_fma_f32 v34, -v30, v33, v32
	v_fmac_f32_e32 v33, v34, v31
	v_fma_f32 v30, -v30, v33, v32
	v_div_fmas_f32 v30, v30, v31, v33
	v_div_fixup_f32 v22, v30, v22, 2.0
	v_sub_f32_e32 v22, 1.0, v22
	v_add_f32_e32 v22, 1.0, v22
	v_mul_f32_e32 v30, v18, v22
	v_and_b32_e32 v18, 0xffff0000, v23
	v_mul_f32_e32 v22, 0x3d372713, v18
	v_mul_f32_e32 v22, v22, v18
	v_fma_f32 v22, v22, v18, v18
	v_mul_f32_e32 v22, 0x3f4c422a, v22
	v_add_f32_e32 v22, v22, v22
	v_mul_f32_e32 v22, 0x3fb8aa3b, v22
	v_exp_f32_e32 v22, v22
	v_mul_f32_e32 v18, 0.5, v18
	v_add_f32_e32 v22, 1.0, v22
	v_div_scale_f32 v23, s[14:15], v22, v22, 2.0
	v_rcp_f32_e32 v31, v23
	s_nop 0
	v_fma_f32 v32, -v23, v31, 1.0
	v_fmac_f32_e32 v31, v32, v31
	v_div_scale_f32 v32, vcc, 2.0, v22, 2.0
	v_mul_f32_e32 v33, v32, v31
	v_fma_f32 v34, -v23, v33, v32
	v_fmac_f32_e32 v33, v34, v31
	v_fma_f32 v23, -v23, v33, v32
	v_div_fmas_f32 v23, v23, v31, v33
	v_div_fixup_f32 v22, v23, v22, 2.0
	v_sub_f32_e32 v22, 1.0, v22
	v_add_f32_e32 v22, 1.0, v22
	v_mul_f32_e32 v31, v18, v22
	v_lshlrev_b32_e32 v18, 16, v24
	v_mul_f32_e32 v22, 0x3d372713, v18
	v_mul_f32_e32 v22, v22, v18
	v_fma_f32 v22, v22, v18, v18
	v_mul_f32_e32 v22, 0x3f4c422a, v22
	v_add_f32_e32 v22, v22, v22
	v_mul_f32_e32 v22, 0x3fb8aa3b, v22
	v_exp_f32_e32 v22, v22
	v_mul_f32_e32 v18, 0.5, v18
	v_add_f32_e32 v22, 1.0, v22
	v_div_scale_f32 v23, s[14:15], v22, v22, 2.0
	v_rcp_f32_e32 v32, v23
	s_nop 0
	v_fma_f32 v33, -v23, v32, 1.0
	v_fmac_f32_e32 v32, v33, v32
	v_div_scale_f32 v33, vcc, 2.0, v22, 2.0
	v_mul_f32_e32 v34, v33, v32
	v_fma_f32 v35, -v23, v34, v33
	v_fmac_f32_e32 v34, v35, v32
	v_fma_f32 v23, -v23, v34, v33
	v_div_fmas_f32 v23, v23, v32, v34
	v_div_fixup_f32 v22, v23, v22, 2.0
	v_sub_f32_e32 v22, 1.0, v22
	v_add_f32_e32 v22, 1.0, v22
	v_mul_f32_e32 v32, v18, v22
	v_and_b32_e32 v18, 0xffff0000, v24
	v_mul_f32_e32 v22, 0x3d372713, v18
	v_mul_f32_e32 v22, v22, v18
	v_fma_f32 v22, v22, v18, v18
	v_mul_f32_e32 v22, 0x3f4c422a, v22
	v_add_f32_e32 v22, v22, v22
	v_mul_f32_e32 v22, 0x3fb8aa3b, v22
	v_exp_f32_e32 v22, v22
	v_mul_f32_e32 v18, 0.5, v18
	v_add_f32_e32 v22, 1.0, v22
	v_div_scale_f32 v23, s[14:15], v22, v22, 2.0
	v_rcp_f32_e32 v24, v23
	s_nop 0
	v_fma_f32 v33, -v23, v24, 1.0
	v_fmac_f32_e32 v24, v33, v24
	v_div_scale_f32 v33, vcc, 2.0, v22, 2.0
	v_mul_f32_e32 v34, v33, v24
	v_fma_f32 v35, -v23, v34, v33
	v_fmac_f32_e32 v34, v35, v24
	v_fma_f32 v23, -v23, v34, v33
	v_div_fmas_f32 v23, v23, v24, v34
	v_div_fixup_f32 v22, v23, v22, 2.0
	v_sub_f32_e32 v22, 1.0, v22
	v_add_f32_e32 v22, 1.0, v22
	v_mul_f32_e32 v24, v18, v22
	v_lshlrev_b32_e32 v18, 16, v25
	v_mul_f32_e32 v22, 0x3d372713, v18
	v_mul_f32_e32 v22, v22, v18
	v_fma_f32 v22, v22, v18, v18
	v_mul_f32_e32 v22, 0x3f4c422a, v22
	v_add_f32_e32 v22, v22, v22
	v_mul_f32_e32 v22, 0x3fb8aa3b, v22
	v_exp_f32_e32 v22, v22
	v_mul_f32_e32 v18, 0.5, v18
	v_add_f32_e32 v22, 1.0, v22
	v_div_scale_f32 v23, s[14:15], v22, v22, 2.0
	v_rcp_f32_e32 v33, v23
	s_nop 0
	v_fma_f32 v34, -v23, v33, 1.0
	v_fmac_f32_e32 v33, v34, v33
	v_div_scale_f32 v34, vcc, 2.0, v22, 2.0
	v_mul_f32_e32 v35, v34, v33
	v_fma_f32 v36, -v23, v35, v34
	v_fmac_f32_e32 v35, v36, v33
	v_fma_f32 v23, -v23, v35, v34
	v_div_fmas_f32 v23, v23, v33, v35
	v_div_fixup_f32 v22, v23, v22, 2.0
	v_sub_f32_e32 v22, 1.0, v22
	v_add_f32_e32 v22, 1.0, v22
	v_mul_f32_e32 v33, v18, v22
	v_and_b32_e32 v18, 0xffff0000, v25
	v_mul_f32_e32 v22, 0x3d372713, v18
	v_mul_f32_e32 v22, v22, v18
	v_fma_f32 v22, v22, v18, v18
	v_mul_f32_e32 v22, 0x3f4c422a, v22
	v_add_f32_e32 v22, v22, v22
	v_mul_f32_e32 v22, 0x3fb8aa3b, v22
	v_exp_f32_e32 v22, v22
	v_mul_f32_e32 v18, 0.5, v18
	v_add_f32_e32 v22, 1.0, v22
	v_div_scale_f32 v23, s[14:15], v22, v22, 2.0
	v_rcp_f32_e32 v25, v23
	s_nop 0
	v_fma_f32 v34, -v23, v25, 1.0
	v_fmac_f32_e32 v25, v34, v25
	v_div_scale_f32 v34, vcc, 2.0, v22, 2.0
	v_mul_f32_e32 v35, v34, v25
	v_fma_f32 v36, -v23, v35, v34
	v_fmac_f32_e32 v35, v36, v25
	v_fma_f32 v23, -v23, v35, v34
	v_div_fmas_f32 v23, v23, v25, v35
	v_div_fixup_f32 v22, v23, v22, 2.0
	v_sub_f32_e32 v22, 1.0, v22
	v_add_f32_e32 v22, 1.0, v22
	v_mul_f32_e32 v25, v18, v22
	v_and_b32_e32 v18, 0xffff0000, v19
	v_lshlrev_b32_e32 v19, 16, v19
	v_mul_f32_e32 v22, 0x3d372713, v19
	v_mul_f32_e32 v22, v22, v19
	v_mov_b32_e32 v23, v19
	v_fmac_f32_e32 v23, v22, v23
	v_mul_f32_e32 v22, 0x3f4c422a, v23
	v_add_f32_e32 v22, v22, v22
	v_mul_f32_e32 v22, 0x3fb8aa3b, v22
	v_exp_f32_e32 v23, v22
	v_mul_f32_e32 v22, 0x3d372713, v18
	v_mul_f32_e32 v22, v22, v18
	v_mov_b32_e32 v35, v18
	v_fmac_f32_e32 v35, v22, v35
	v_mul_f32_e32 v22, 0x3f4c422a, v35
	v_add_f32_e32 v22, v22, v22
	v_mul_f32_e32 v22, 0x3fb8aa3b, v22
	v_exp_f32_e32 v22, v22
	v_pk_mul_f32 v[18:19], v[18:19], 0.5 op_sel_hi:[1,0]
	v_mul_f32_e32 v34, v29, v29
	v_fmac_f32_e32 v34, v28, v28
	v_pk_add_f32 v[22:23], v[22:23], 1.0 op_sel_hi:[1,0]
	s_nop 0
	v_div_scale_f32 v35, s[14:15], v23, v23, 2.0
	v_rcp_f32_e32 v36, v35
	s_nop 0
	v_fma_f32 v37, -v35, v36, 1.0
	v_fmac_f32_e32 v36, v37, v36
	v_div_scale_f32 v37, vcc, 2.0, v23, 2.0
	v_mul_f32_e32 v38, v37, v36
	v_fma_f32 v39, -v35, v38, v37
	v_fmac_f32_e32 v38, v39, v36
	v_fma_f32 v35, -v35, v38, v37
	v_div_fmas_f32 v35, v35, v36, v38
	v_div_fixup_f32 v23, v35, v23, 2.0
	v_div_scale_f32 v35, s[14:15], v22, v22, 2.0
	v_rcp_f32_e32 v36, v35
	s_nop 0
	v_fma_f32 v37, -v35, v36, 1.0
	v_fmac_f32_e32 v36, v37, v36
	v_div_scale_f32 v37, vcc, 2.0, v22, 2.0
	v_mul_f32_e32 v38, v37, v36
	v_fma_f32 v39, -v35, v38, v37
	v_fmac_f32_e32 v38, v39, v36
	v_fma_f32 v35, -v35, v38, v37
	v_div_fmas_f32 v35, v35, v36, v38
	v_div_fixup_f32 v22, v35, v22, 2.0
	v_pk_add_f32 v[22:23], v[22:23], 1.0 op_sel_hi:[1,0] neg_lo:[1,0] neg_hi:[1,0]
	s_nop 0
	v_pk_add_f32 v[22:23], v[22:23], 1.0 op_sel_hi:[1,0]
	s_nop 0
	v_pk_mul_f32 v[18:19], v[18:19], v[22:23]
	s_nop 0
	v_pk_mul_f32 v[22:23], v[18:19], v[18:19]
	s_nop 0
	v_add_f32_e32 v23, v23, v34
	v_add_f32_e32 v36, v22, v23
	v_lshlrev_b32_e32 v23, 16, v20
	v_and_b32_e32 v22, 0xffff0000, v20
	v_mul_f32_e32 v20, 0x3d372713, v23
	v_mul_f32_e32 v20, v20, v23
	v_mov_b32_e32 v34, v23
	v_fmac_f32_e32 v34, v20, v34
	v_mul_f32_e32 v20, 0x3f4c422a, v34
	v_add_f32_e32 v20, v20, v20
	v_mul_f32_e32 v20, 0x3fb8aa3b, v20
	v_exp_f32_e32 v35, v20
	v_mul_f32_e32 v20, 0x3d372713, v22
	v_mul_f32_e32 v20, v20, v22
	v_mov_b32_e32 v34, v22
	v_fmac_f32_e32 v34, v20, v34
	v_mul_f32_e32 v20, 0x3f4c422a, v34
	v_add_f32_e32 v20, v20, v20
	v_mul_f32_e32 v20, 0x3fb8aa3b, v20
	v_exp_f32_e32 v34, v20
	v_pk_mul_f32 v[22:23], v[22:23], 0.5 op_sel_hi:[1,0]
	v_pk_add_f32 v[34:35], v[34:35], 1.0 op_sel_hi:[1,0]
	s_nop 0
	v_div_scale_f32 v20, s[14:15], v35, v35, 2.0
	v_rcp_f32_e32 v37, v20
	s_nop 0
	v_fma_f32 v38, -v20, v37, 1.0
	v_fmac_f32_e32 v37, v38, v37
	v_div_scale_f32 v38, vcc, 2.0, v35, 2.0
	v_mul_f32_e32 v39, v38, v37
	v_fma_f32 v40, -v20, v39, v38
	v_fmac_f32_e32 v39, v40, v37
	v_fma_f32 v20, -v20, v39, v38
	v_div_fmas_f32 v20, v20, v37, v39
	v_div_fixup_f32 v35, v20, v35, 2.0
	v_div_scale_f32 v20, s[14:15], v34, v34, 2.0
	v_rcp_f32_e32 v37, v20
	s_nop 0
	v_fma_f32 v38, -v20, v37, 1.0
	v_fmac_f32_e32 v37, v38, v37
	v_div_scale_f32 v38, vcc, 2.0, v34, 2.0
	v_mul_f32_e32 v39, v38, v37
	v_fma_f32 v40, -v20, v39, v38
	v_fmac_f32_e32 v39, v40, v37
	v_fma_f32 v20, -v20, v39, v38
	v_div_fmas_f32 v20, v20, v37, v39
	v_div_fixup_f32 v34, v20, v34, 2.0
	v_pk_add_f32 v[34:35], v[34:35], 1.0 op_sel_hi:[1,0] neg_lo:[1,0] neg_hi:[1,0]
	s_nop 0
	v_pk_add_f32 v[34:35], v[34:35], 1.0 op_sel_hi:[1,0]
	s_nop 0
	v_pk_mul_f32 v[22:23], v[22:23], v[34:35]
	s_nop 0
	v_pk_mul_f32 v[34:35], v[22:23], v[22:23]
	s_nop 0
	v_add_f32_e32 v20, v35, v36
	v_add_f32_e32 v36, v34, v20
	v_and_b32_e32 v20, 0xffff0000, v21
	v_lshlrev_b32_e32 v21, 16, v21
	v_mul_f32_e32 v34, 0x3d372713, v21
	v_mul_f32_e32 v34, v34, v21
	v_mov_b32_e32 v35, v21
	v_fmac_f32_e32 v35, v34, v35
	v_mul_f32_e32 v34, 0x3f4c422a, v35
	v_add_f32_e32 v34, v34, v34
	v_mul_f32_e32 v34, 0x3fb8aa3b, v34
	v_exp_f32_e32 v35, v34
	v_mul_f32_e32 v34, 0x3d372713, v20
	v_mul_f32_e32 v34, v34, v20
	v_mov_b32_e32 v37, v20
	v_fmac_f32_e32 v37, v34, v37
	v_mul_f32_e32 v34, 0x3f4c422a, v37
	v_add_f32_e32 v34, v34, v34
	v_mul_f32_e32 v34, 0x3fb8aa3b, v34
	v_exp_f32_e32 v34, v34
	v_pk_mul_f32 v[20:21], v[20:21], 0.5 op_sel_hi:[1,0]
	v_pk_add_f32 v[34:35], v[34:35], 1.0 op_sel_hi:[1,0]
	s_nop 0
	v_div_scale_f32 v37, s[14:15], v35, v35, 2.0
	v_rcp_f32_e32 v38, v37
	s_nop 0
	v_fma_f32 v39, -v37, v38, 1.0
	v_fmac_f32_e32 v38, v39, v38
	v_div_scale_f32 v39, vcc, 2.0, v35, 2.0
	v_mul_f32_e32 v40, v39, v38
	v_fma_f32 v41, -v37, v40, v39
	v_fmac_f32_e32 v40, v41, v38
	v_fma_f32 v37, -v37, v40, v39
	v_div_fmas_f32 v37, v37, v38, v40
	v_div_fixup_f32 v35, v37, v35, 2.0
	v_div_scale_f32 v37, s[14:15], v34, v34, 2.0
	v_rcp_f32_e32 v38, v37
	s_nop 0
	v_fma_f32 v39, -v37, v38, 1.0
	v_fmac_f32_e32 v38, v39, v38
	v_div_scale_f32 v39, vcc, 2.0, v34, 2.0
	v_mul_f32_e32 v40, v39, v38
	v_fma_f32 v41, -v37, v40, v39
	v_fmac_f32_e32 v40, v41, v38
	v_fma_f32 v37, -v37, v40, v39
	v_div_fmas_f32 v37, v37, v38, v40
	v_div_fixup_f32 v34, v37, v34, 2.0
	v_pk_add_f32 v[34:35], v[34:35], 1.0 op_sel_hi:[1,0] neg_lo:[1,0] neg_hi:[1,0]
	s_nop 0
	v_pk_add_f32 v[34:35], v[34:35], 1.0 op_sel_hi:[1,0]
	s_nop 0
	v_pk_mul_f32 v[34:35], v[20:21], v[34:35]
	s_nop 0
	v_pk_mul_f32 v[20:21], v[34:35], v[34:35]
	s_nop 0
	v_add_f32_e32 v21, v21, v36
	v_add_f32_e32 v20, v20, v21
	ds_bpermute_b32 v21, v106, v20
	s_waitcnt lgkmcnt(0)
	v_add_f32_e32 v20, v20, v21
	ds_bpermute_b32 v21, v107, v20
	s_waitcnt lgkmcnt(0)
	v_add_f32_e32 v20, v20, v21
	ds_bpermute_b32 v21, v108, v20
	s_waitcnt lgkmcnt(0)
	v_add_f32_e32 v20, v20, v21
	ds_bpermute_b32 v21, v109, v20
	s_waitcnt lgkmcnt(0)
	v_add_f32_e32 v20, v20, v21
	ds_bpermute_b32 v21, v110, v20
	s_waitcnt lgkmcnt(0)
	v_add_f32_e32 v20, v20, v21
	v_fmamk_f32 v20, v20, 0x3b800000, v243
	v_cmp_gt_f32_e32 vcc, s3, v20
	v_mul_f32_e32 v21, 0x4b800000, v20
	s_nop 0
	v_cndmask_b32_e32 v20, v20, v21, vcc
	v_rsq_f32_e32 v20, v20
	s_nop 0
	v_mul_f32_e32 v21, 0x45800000, v20
	v_cndmask_b32_e32 v36, v20, v21, vcc
	v_mul_f32_e32 v20, v28, v36
	v_mul_f32_e32 v21, v29, v36
	v_mul_f32_e32 v18, v18, v36
	v_mul_f32_e32 v20, v70, v20
	v_mul_f32_e32 v21, v71, v21
	v_mul_f32_e32 v19, v19, v36
	v_mul_f32_e32 v18, v73, v18
	v_cvt_pk_bf16_f32 v20, v20, v21
	v_cvt_pk_bf16_f32 v27, v30, v31
	v_mul_f32_e32 v19, v72, v19
	v_cvt_pk_bf16_f32 v21, v19, v18
	v_mul_f32_e32 v18, v23, v36
	v_mul_f32_e32 v18, v66, v18
	v_mul_f32_e32 v19, v22, v36
	v_cvt_pk_bf16_f32 v28, v32, v24
	v_mul_f32_e32 v19, v67, v19
	v_cvt_pk_bf16_f32 v22, v18, v19
	v_mul_f32_e32 v18, v35, v36
	v_mul_f32_e32 v18, v68, v18
	v_mul_f32_e32 v19, v34, v36
	v_cvt_pk_bf16_f32 v29, v33, v25
	v_mul_f32_e32 v19, v69, v19
	v_cvt_pk_bf16_f32 v23, v18, v19
	v_lshlrev_b32_e32 v18, 16, v14
	v_mul_f32_e32 v19, 0x3d372713, v18
	v_mul_f32_e32 v19, v19, v18
	v_fma_f32 v19, v19, v18, v18
	v_mul_f32_e32 v19, 0x3f4c422a, v19
	v_add_f32_e32 v19, v19, v19
	v_mul_f32_e32 v19, 0x3fb8aa3b, v19
	v_exp_f32_e32 v19, v19
	ds_write_b128 v111, v[26:29] offset:43520
	ds_write_b128 v112, v[20:23] offset:43520
	v_mul_f32_e32 v18, 0.5, v18
	v_and_b32_e32 v14, 0xffff0000, v14
	v_add_f32_e32 v19, 1.0, v19
	v_div_scale_f32 v20, s[14:15], v19, v19, 2.0
	v_rcp_f32_e32 v21, v20
	s_nop 0
	v_fma_f32 v22, -v20, v21, 1.0
	v_fmac_f32_e32 v21, v22, v21
	v_div_scale_f32 v22, vcc, 2.0, v19, 2.0
	v_mul_f32_e32 v23, v22, v21
	v_fma_f32 v24, -v20, v23, v22
	v_fmac_f32_e32 v23, v24, v21
	v_fma_f32 v20, -v20, v23, v22
	v_div_fmas_f32 v20, v20, v21, v23
	v_div_fixup_f32 v19, v20, v19, 2.0
	v_sub_f32_e32 v19, 1.0, v19
	v_add_f32_e32 v19, 1.0, v19
	v_mul_f32_e32 v18, v18, v19
	v_mul_f32_e32 v19, 0x3d372713, v14
	v_mul_f32_e32 v19, v19, v14
	v_fma_f32 v19, v19, v14, v14
	v_mul_f32_e32 v19, 0x3f4c422a, v19
	v_add_f32_e32 v19, v19, v19
	v_mul_f32_e32 v19, 0x3fb8aa3b, v19
	v_exp_f32_e32 v19, v19
	v_mul_f32_e32 v14, 0.5, v14
	v_add_f32_e32 v19, 1.0, v19
	v_div_scale_f32 v20, s[14:15], v19, v19, 2.0
	v_rcp_f32_e32 v21, v20
	s_nop 0
	v_fma_f32 v22, -v20, v21, 1.0
	v_fmac_f32_e32 v21, v22, v21
	v_div_scale_f32 v22, vcc, 2.0, v19, 2.0
	v_mul_f32_e32 v23, v22, v21
	v_fma_f32 v24, -v20, v23, v22
	v_fmac_f32_e32 v23, v24, v21
	v_fma_f32 v20, -v20, v23, v22
	v_div_fmas_f32 v20, v20, v21, v23
	v_div_fixup_f32 v19, v20, v19, 2.0
	v_sub_f32_e32 v19, 1.0, v19
	v_add_f32_e32 v19, 1.0, v19
	v_mul_f32_e32 v19, v14, v19
	v_lshlrev_b32_e32 v14, 16, v10
	v_mul_f32_e32 v20, 0x3d372713, v14
	v_mul_f32_e32 v20, v20, v14
	v_fma_f32 v20, v20, v14, v14
	v_mul_f32_e32 v20, 0x3f4c422a, v20
	v_add_f32_e32 v20, v20, v20
	v_mul_f32_e32 v20, 0x3fb8aa3b, v20
	v_exp_f32_e32 v20, v20
	v_mul_f32_e32 v14, 0.5, v14
	v_and_b32_e32 v10, 0xffff0000, v10
	v_cvt_pk_bf16_f32 v18, v18, v19
	v_add_f32_e32 v20, 1.0, v20
	v_div_scale_f32 v21, s[14:15], v20, v20, 2.0
	v_rcp_f32_e32 v22, v21
	s_nop 0
	v_fma_f32 v23, -v21, v22, 1.0
	v_fmac_f32_e32 v22, v23, v22
	v_div_scale_f32 v23, vcc, 2.0, v20, 2.0
	v_mul_f32_e32 v24, v23, v22
	v_fma_f32 v25, -v21, v24, v23
	v_fmac_f32_e32 v24, v25, v22
	v_fma_f32 v21, -v21, v24, v23
	v_div_fmas_f32 v21, v21, v22, v24
	v_div_fixup_f32 v20, v21, v20, 2.0
	v_sub_f32_e32 v20, 1.0, v20
	v_add_f32_e32 v20, 1.0, v20
	v_mul_f32_e32 v20, v14, v20
	v_mul_f32_e32 v14, 0x3d372713, v10
	v_mul_f32_e32 v14, v14, v10
	v_fma_f32 v14, v14, v10, v10
	v_mul_f32_e32 v14, 0x3f4c422a, v14
	v_add_f32_e32 v14, v14, v14
	v_mul_f32_e32 v14, 0x3fb8aa3b, v14
	v_exp_f32_e32 v14, v14
	v_mul_f32_e32 v10, 0.5, v10
	v_add_f32_e32 v14, 1.0, v14
	v_div_scale_f32 v21, s[14:15], v14, v14, 2.0
	v_rcp_f32_e32 v22, v21
	s_nop 0
	v_fma_f32 v23, -v21, v22, 1.0
	v_fmac_f32_e32 v22, v23, v22
	v_div_scale_f32 v23, vcc, 2.0, v14, 2.0
	v_mul_f32_e32 v24, v23, v22
	v_fma_f32 v25, -v21, v24, v23
	v_fmac_f32_e32 v24, v25, v22
	v_fma_f32 v21, -v21, v24, v23
	v_div_fmas_f32 v21, v21, v22, v24
	v_div_fixup_f32 v14, v21, v14, 2.0
	v_sub_f32_e32 v14, 1.0, v14
	v_add_f32_e32 v14, 1.0, v14
	v_mul_f32_e32 v21, v10, v14
	v_lshlrev_b32_e32 v10, 16, v15
	v_mul_f32_e32 v14, 0x3d372713, v10
	v_mul_f32_e32 v14, v14, v10
	v_fma_f32 v14, v14, v10, v10
	v_mul_f32_e32 v14, 0x3f4c422a, v14
	v_add_f32_e32 v14, v14, v14
	v_mul_f32_e32 v14, 0x3fb8aa3b, v14
	v_exp_f32_e32 v14, v14
	v_mul_f32_e32 v10, 0.5, v10
	v_add_f32_e32 v14, 1.0, v14
	v_div_scale_f32 v22, s[14:15], v14, v14, 2.0
	v_rcp_f32_e32 v23, v22
	s_nop 0
	v_fma_f32 v24, -v22, v23, 1.0
	v_fmac_f32_e32 v23, v24, v23
	v_div_scale_f32 v24, vcc, 2.0, v14, 2.0
	v_mul_f32_e32 v25, v24, v23
	v_fma_f32 v26, -v22, v25, v24
	v_fmac_f32_e32 v25, v26, v23
	v_fma_f32 v22, -v22, v25, v24
	v_div_fmas_f32 v22, v22, v23, v25
	v_div_fixup_f32 v14, v22, v14, 2.0
	v_sub_f32_e32 v14, 1.0, v14
	v_add_f32_e32 v14, 1.0, v14
	v_mul_f32_e32 v22, v10, v14
	v_and_b32_e32 v10, 0xffff0000, v15
	v_mul_f32_e32 v14, 0x3d372713, v10
	v_mul_f32_e32 v14, v14, v10
	v_fma_f32 v14, v14, v10, v10
	v_mul_f32_e32 v14, 0x3f4c422a, v14
	v_add_f32_e32 v14, v14, v14
	v_mul_f32_e32 v14, 0x3fb8aa3b, v14
	v_exp_f32_e32 v14, v14
	v_mul_f32_e32 v10, 0.5, v10
	v_add_f32_e32 v14, 1.0, v14
	v_div_scale_f32 v15, s[14:15], v14, v14, 2.0
	v_rcp_f32_e32 v23, v15
	s_nop 0
	v_fma_f32 v24, -v15, v23, 1.0
	v_fmac_f32_e32 v23, v24, v23
	v_div_scale_f32 v24, vcc, 2.0, v14, 2.0
	v_mul_f32_e32 v25, v24, v23
	v_fma_f32 v26, -v15, v25, v24
	v_fmac_f32_e32 v25, v26, v23
	v_fma_f32 v15, -v15, v25, v24
	v_div_fmas_f32 v15, v15, v23, v25
	v_div_fixup_f32 v14, v15, v14, 2.0
	v_sub_f32_e32 v14, 1.0, v14
	v_add_f32_e32 v14, 1.0, v14
	v_mul_f32_e32 v23, v10, v14
	v_lshlrev_b32_e32 v10, 16, v16
	v_mul_f32_e32 v14, 0x3d372713, v10
	v_mul_f32_e32 v14, v14, v10
	v_fma_f32 v14, v14, v10, v10
	v_mul_f32_e32 v14, 0x3f4c422a, v14
	v_add_f32_e32 v14, v14, v14
	v_mul_f32_e32 v14, 0x3fb8aa3b, v14
	v_exp_f32_e32 v14, v14
	v_mul_f32_e32 v10, 0.5, v10
	v_add_f32_e32 v14, 1.0, v14
	v_div_scale_f32 v15, s[14:15], v14, v14, 2.0
	v_rcp_f32_e32 v24, v15
	s_nop 0
	v_fma_f32 v25, -v15, v24, 1.0
	v_fmac_f32_e32 v24, v25, v24
	v_div_scale_f32 v25, vcc, 2.0, v14, 2.0
	v_mul_f32_e32 v26, v25, v24
	v_fma_f32 v27, -v15, v26, v25
	v_fmac_f32_e32 v26, v27, v24
	v_fma_f32 v15, -v15, v26, v25
	v_div_fmas_f32 v15, v15, v24, v26
	v_div_fixup_f32 v14, v15, v14, 2.0
	v_sub_f32_e32 v14, 1.0, v14
	v_add_f32_e32 v14, 1.0, v14
	v_mul_f32_e32 v24, v10, v14
	v_and_b32_e32 v10, 0xffff0000, v16
	v_mul_f32_e32 v14, 0x3d372713, v10
	v_mul_f32_e32 v14, v14, v10
	v_fma_f32 v14, v14, v10, v10
	v_mul_f32_e32 v14, 0x3f4c422a, v14
	v_add_f32_e32 v14, v14, v14
	v_mul_f32_e32 v14, 0x3fb8aa3b, v14
	v_exp_f32_e32 v14, v14
	v_mul_f32_e32 v10, 0.5, v10
	v_add_f32_e32 v14, 1.0, v14
	v_div_scale_f32 v15, s[14:15], v14, v14, 2.0
	v_rcp_f32_e32 v16, v15
	s_nop 0
	v_fma_f32 v25, -v15, v16, 1.0
	v_fmac_f32_e32 v16, v25, v16
	v_div_scale_f32 v25, vcc, 2.0, v14, 2.0
	v_mul_f32_e32 v26, v25, v16
	v_fma_f32 v27, -v15, v26, v25
	v_fmac_f32_e32 v26, v27, v16
	v_fma_f32 v15, -v15, v26, v25
	v_div_fmas_f32 v15, v15, v16, v26
	v_div_fixup_f32 v14, v15, v14, 2.0
	v_sub_f32_e32 v14, 1.0, v14
	v_add_f32_e32 v14, 1.0, v14
	v_mul_f32_e32 v16, v10, v14
	v_lshlrev_b32_e32 v10, 16, v17
	v_mul_f32_e32 v14, 0x3d372713, v10
	v_mul_f32_e32 v14, v14, v10
	v_fma_f32 v14, v14, v10, v10
	v_mul_f32_e32 v14, 0x3f4c422a, v14
	v_add_f32_e32 v14, v14, v14
	v_mul_f32_e32 v14, 0x3fb8aa3b, v14
	v_exp_f32_e32 v14, v14
	v_mul_f32_e32 v10, 0.5, v10
	v_add_f32_e32 v14, 1.0, v14
	v_div_scale_f32 v15, s[14:15], v14, v14, 2.0
	v_rcp_f32_e32 v25, v15
	s_nop 0
	v_fma_f32 v26, -v15, v25, 1.0
	v_fmac_f32_e32 v25, v26, v25
	v_div_scale_f32 v26, vcc, 2.0, v14, 2.0
	v_mul_f32_e32 v27, v26, v25
	v_fma_f32 v28, -v15, v27, v26
	v_fmac_f32_e32 v27, v28, v25
	v_fma_f32 v15, -v15, v27, v26
	v_div_fmas_f32 v15, v15, v25, v27
	v_div_fixup_f32 v14, v15, v14, 2.0
	v_sub_f32_e32 v14, 1.0, v14
	v_add_f32_e32 v14, 1.0, v14
	v_mul_f32_e32 v25, v10, v14
	v_and_b32_e32 v10, 0xffff0000, v17
	v_mul_f32_e32 v14, 0x3d372713, v10
	v_mul_f32_e32 v14, v14, v10
	v_fma_f32 v14, v14, v10, v10
	v_mul_f32_e32 v14, 0x3f4c422a, v14
	v_add_f32_e32 v14, v14, v14
	v_mul_f32_e32 v14, 0x3fb8aa3b, v14
	v_exp_f32_e32 v14, v14
	v_mul_f32_e32 v10, 0.5, v10
	v_add_f32_e32 v14, 1.0, v14
	v_div_scale_f32 v15, s[14:15], v14, v14, 2.0
	v_rcp_f32_e32 v17, v15
	s_nop 0
	v_fma_f32 v26, -v15, v17, 1.0
	v_fmac_f32_e32 v17, v26, v17
	v_div_scale_f32 v26, vcc, 2.0, v14, 2.0
	v_mul_f32_e32 v27, v26, v17
	v_fma_f32 v28, -v15, v27, v26
	v_fmac_f32_e32 v27, v28, v17
	v_fma_f32 v15, -v15, v27, v26
	v_div_fmas_f32 v15, v15, v17, v27
	v_div_fixup_f32 v14, v15, v14, 2.0
	v_sub_f32_e32 v14, 1.0, v14
	v_add_f32_e32 v14, 1.0, v14
	v_mul_f32_e32 v17, v10, v14
	v_and_b32_e32 v10, 0xffff0000, v11
	v_lshlrev_b32_e32 v11, 16, v11
	v_mul_f32_e32 v14, 0x3d372713, v11
	v_mul_f32_e32 v14, v14, v11
	v_mov_b32_e32 v15, v11
	v_fmac_f32_e32 v15, v14, v15
	v_mul_f32_e32 v14, 0x3f4c422a, v15
	v_add_f32_e32 v14, v14, v14
	v_mul_f32_e32 v14, 0x3fb8aa3b, v14
	v_exp_f32_e32 v15, v14
	v_mul_f32_e32 v14, 0x3d372713, v10
	v_mul_f32_e32 v14, v14, v10
	v_mov_b32_e32 v27, v10
	v_fmac_f32_e32 v27, v14, v27
	v_mul_f32_e32 v14, 0x3f4c422a, v27
	v_add_f32_e32 v14, v14, v14
	v_mul_f32_e32 v14, 0x3fb8aa3b, v14
	v_exp_f32_e32 v14, v14
	v_pk_mul_f32 v[10:11], v[10:11], 0.5 op_sel_hi:[1,0]
	v_mul_f32_e32 v26, v21, v21
	v_fmac_f32_e32 v26, v20, v20
	v_pk_add_f32 v[14:15], v[14:15], 1.0 op_sel_hi:[1,0]
	s_nop 0
	v_div_scale_f32 v27, s[14:15], v15, v15, 2.0
	v_rcp_f32_e32 v28, v27
	s_nop 0
	v_fma_f32 v29, -v27, v28, 1.0
	v_fmac_f32_e32 v28, v29, v28
	v_div_scale_f32 v29, vcc, 2.0, v15, 2.0
	v_mul_f32_e32 v30, v29, v28
	v_fma_f32 v31, -v27, v30, v29
	v_fmac_f32_e32 v30, v31, v28
	v_fma_f32 v27, -v27, v30, v29
	v_div_fmas_f32 v27, v27, v28, v30
	v_div_fixup_f32 v15, v27, v15, 2.0
	v_div_scale_f32 v27, s[14:15], v14, v14, 2.0
	v_rcp_f32_e32 v28, v27
	s_nop 0
	v_fma_f32 v29, -v27, v28, 1.0
	v_fmac_f32_e32 v28, v29, v28
	v_div_scale_f32 v29, vcc, 2.0, v14, 2.0
	v_mul_f32_e32 v30, v29, v28
	v_fma_f32 v31, -v27, v30, v29
	v_fmac_f32_e32 v30, v31, v28
	v_fma_f32 v27, -v27, v30, v29
	v_div_fmas_f32 v27, v27, v28, v30
	v_div_fixup_f32 v14, v27, v14, 2.0
	v_pk_add_f32 v[14:15], v[14:15], 1.0 op_sel_hi:[1,0] neg_lo:[1,0] neg_hi:[1,0]
	s_nop 0
	v_pk_add_f32 v[14:15], v[14:15], 1.0 op_sel_hi:[1,0]
	s_nop 0
	v_pk_mul_f32 v[10:11], v[10:11], v[14:15]
	s_nop 0
	v_pk_mul_f32 v[14:15], v[10:11], v[10:11]
	s_nop 0
	v_add_f32_e32 v15, v15, v26
	v_add_f32_e32 v28, v14, v15
	v_lshlrev_b32_e32 v15, 16, v12
	v_and_b32_e32 v14, 0xffff0000, v12
	v_mul_f32_e32 v12, 0x3d372713, v15
	v_mul_f32_e32 v12, v12, v15
	v_mov_b32_e32 v26, v15
	v_fmac_f32_e32 v26, v12, v26
	v_mul_f32_e32 v12, 0x3f4c422a, v26
	v_add_f32_e32 v12, v12, v12
	v_mul_f32_e32 v12, 0x3fb8aa3b, v12
	v_exp_f32_e32 v27, v12
	v_mul_f32_e32 v12, 0x3d372713, v14
	v_mul_f32_e32 v12, v12, v14
	v_mov_b32_e32 v26, v14
	v_fmac_f32_e32 v26, v12, v26
	v_mul_f32_e32 v12, 0x3f4c422a, v26
	v_add_f32_e32 v12, v12, v12
	v_mul_f32_e32 v12, 0x3fb8aa3b, v12
	v_exp_f32_e32 v26, v12
	v_pk_mul_f32 v[14:15], v[14:15], 0.5 op_sel_hi:[1,0]
	v_pk_add_f32 v[26:27], v[26:27], 1.0 op_sel_hi:[1,0]
	s_nop 0
	v_div_scale_f32 v12, s[14:15], v27, v27, 2.0
	v_rcp_f32_e32 v29, v12
	s_nop 0
	v_fma_f32 v30, -v12, v29, 1.0
	v_fmac_f32_e32 v29, v30, v29
	v_div_scale_f32 v30, vcc, 2.0, v27, 2.0
	v_mul_f32_e32 v31, v30, v29
	v_fma_f32 v32, -v12, v31, v30
	v_fmac_f32_e32 v31, v32, v29
	v_fma_f32 v12, -v12, v31, v30
	v_div_fmas_f32 v12, v12, v29, v31
	v_div_fixup_f32 v27, v12, v27, 2.0
	v_div_scale_f32 v12, s[14:15], v26, v26, 2.0
	v_rcp_f32_e32 v29, v12
	s_nop 0
	v_fma_f32 v30, -v12, v29, 1.0
	v_fmac_f32_e32 v29, v30, v29
	v_div_scale_f32 v30, vcc, 2.0, v26, 2.0
	v_mul_f32_e32 v31, v30, v29
	v_fma_f32 v32, -v12, v31, v30
	v_fmac_f32_e32 v31, v32, v29
	v_fma_f32 v12, -v12, v31, v30
	v_div_fmas_f32 v12, v12, v29, v31
	v_div_fixup_f32 v26, v12, v26, 2.0
	v_pk_add_f32 v[26:27], v[26:27], 1.0 op_sel_hi:[1,0] neg_lo:[1,0] neg_hi:[1,0]
	s_nop 0
	v_pk_add_f32 v[26:27], v[26:27], 1.0 op_sel_hi:[1,0]
	s_nop 0
	v_pk_mul_f32 v[14:15], v[14:15], v[26:27]
	s_nop 0
	v_pk_mul_f32 v[26:27], v[14:15], v[14:15]
	s_nop 0
	v_add_f32_e32 v12, v27, v28
	v_add_f32_e32 v28, v26, v12
	v_and_b32_e32 v12, 0xffff0000, v13
	v_lshlrev_b32_e32 v13, 16, v13
	v_mul_f32_e32 v26, 0x3d372713, v13
	v_mul_f32_e32 v26, v26, v13
	v_mov_b32_e32 v27, v13
	v_fmac_f32_e32 v27, v26, v27
	v_mul_f32_e32 v26, 0x3f4c422a, v27
	v_add_f32_e32 v26, v26, v26
	v_mul_f32_e32 v26, 0x3fb8aa3b, v26
	v_exp_f32_e32 v27, v26
	v_mul_f32_e32 v26, 0x3d372713, v12
	v_mul_f32_e32 v26, v26, v12
	v_mov_b32_e32 v29, v12
	v_fmac_f32_e32 v29, v26, v29
	v_mul_f32_e32 v26, 0x3f4c422a, v29
	v_add_f32_e32 v26, v26, v26
	v_mul_f32_e32 v26, 0x3fb8aa3b, v26
	v_exp_f32_e32 v26, v26
	v_pk_mul_f32 v[12:13], v[12:13], 0.5 op_sel_hi:[1,0]
	v_pk_add_f32 v[26:27], v[26:27], 1.0 op_sel_hi:[1,0]
	s_nop 0
	v_div_scale_f32 v29, s[14:15], v27, v27, 2.0
	v_rcp_f32_e32 v30, v29
	s_nop 0
	v_fma_f32 v31, -v29, v30, 1.0
	v_fmac_f32_e32 v30, v31, v30
	v_div_scale_f32 v31, vcc, 2.0, v27, 2.0
	v_mul_f32_e32 v32, v31, v30
	v_fma_f32 v33, -v29, v32, v31
	v_fmac_f32_e32 v32, v33, v30
	v_fma_f32 v29, -v29, v32, v31
	v_div_fmas_f32 v29, v29, v30, v32
	v_div_fixup_f32 v27, v29, v27, 2.0
	v_div_scale_f32 v29, s[14:15], v26, v26, 2.0
	v_rcp_f32_e32 v30, v29
	s_nop 0
	v_fma_f32 v31, -v29, v30, 1.0
	v_fmac_f32_e32 v30, v31, v30
	v_div_scale_f32 v31, vcc, 2.0, v26, 2.0
	v_mul_f32_e32 v32, v31, v30
	v_fma_f32 v33, -v29, v32, v31
	v_fmac_f32_e32 v32, v33, v30
	v_fma_f32 v29, -v29, v32, v31
	v_div_fmas_f32 v29, v29, v30, v32
	v_div_fixup_f32 v26, v29, v26, 2.0
	v_pk_add_f32 v[26:27], v[26:27], 1.0 op_sel_hi:[1,0] neg_lo:[1,0] neg_hi:[1,0]
	s_nop 0
	v_pk_add_f32 v[26:27], v[26:27], 1.0 op_sel_hi:[1,0]
	s_nop 0
	v_pk_mul_f32 v[26:27], v[12:13], v[26:27]
	s_nop 0
	v_pk_mul_f32 v[12:13], v[26:27], v[26:27]
	s_nop 0
	v_add_f32_e32 v13, v13, v28
	v_add_f32_e32 v12, v12, v13
	ds_bpermute_b32 v13, v106, v12
	s_waitcnt lgkmcnt(0)
	v_add_f32_e32 v12, v12, v13
	ds_bpermute_b32 v13, v107, v12
	s_waitcnt lgkmcnt(0)
	v_add_f32_e32 v12, v12, v13
	ds_bpermute_b32 v13, v108, v12
	s_waitcnt lgkmcnt(0)
	v_add_f32_e32 v12, v12, v13
	ds_bpermute_b32 v13, v109, v12
	s_waitcnt lgkmcnt(0)
	v_add_f32_e32 v12, v12, v13
	ds_bpermute_b32 v13, v110, v12
	s_waitcnt lgkmcnt(0)
	v_add_f32_e32 v12, v12, v13
	v_fmamk_f32 v12, v12, 0x3b800000, v243
	v_cmp_gt_f32_e32 vcc, s3, v12
	v_mul_f32_e32 v13, 0x4b800000, v12
	s_nop 0
	v_cndmask_b32_e32 v12, v12, v13, vcc
	v_rsq_f32_e32 v12, v12
	s_nop 0
	v_mul_f32_e32 v13, 0x45800000, v12
	v_cndmask_b32_e32 v28, v12, v13, vcc
	v_mul_f32_e32 v12, v20, v28
	v_mul_f32_e32 v13, v21, v28
	v_mul_f32_e32 v10, v10, v28
	v_mul_f32_e32 v12, v70, v12
	v_mul_f32_e32 v13, v71, v13
	v_mul_f32_e32 v11, v11, v28
	v_mul_f32_e32 v10, v73, v10
	v_cvt_pk_bf16_f32 v12, v12, v13
	v_cvt_pk_bf16_f32 v19, v22, v23
	v_mul_f32_e32 v11, v72, v11
	v_cvt_pk_bf16_f32 v13, v11, v10
	v_mul_f32_e32 v10, v15, v28
	v_mul_f32_e32 v10, v66, v10
	v_mul_f32_e32 v11, v14, v28
	v_cvt_pk_bf16_f32 v20, v24, v16
	v_mul_f32_e32 v11, v67, v11
	v_cvt_pk_bf16_f32 v14, v10, v11
	v_mul_f32_e32 v10, v27, v28
	v_mul_f32_e32 v10, v68, v10
	v_mul_f32_e32 v11, v26, v28
	v_cvt_pk_bf16_f32 v21, v25, v17
	v_mul_f32_e32 v11, v69, v11
	v_cvt_pk_bf16_f32 v15, v10, v11
	v_lshlrev_b32_e32 v10, 16, v6
	v_mul_f32_e32 v11, 0x3d372713, v10
	v_mul_f32_e32 v11, v11, v10
	v_fma_f32 v11, v11, v10, v10
	v_mul_f32_e32 v11, 0x3f4c422a, v11
	v_add_f32_e32 v11, v11, v11
	v_mul_f32_e32 v11, 0x3fb8aa3b, v11
	v_exp_f32_e32 v11, v11
	ds_write_b128 v111, v[18:21] offset:52224
	ds_write_b128 v112, v[12:15] offset:52224
	v_mul_f32_e32 v10, 0.5, v10
	v_and_b32_e32 v6, 0xffff0000, v6
	v_add_f32_e32 v11, 1.0, v11
	v_div_scale_f32 v12, s[14:15], v11, v11, 2.0
	v_rcp_f32_e32 v13, v12
	s_nop 0
	v_fma_f32 v14, -v12, v13, 1.0
	v_fmac_f32_e32 v13, v14, v13
	v_div_scale_f32 v14, vcc, 2.0, v11, 2.0
	v_mul_f32_e32 v15, v14, v13
	v_fma_f32 v16, -v12, v15, v14
	v_fmac_f32_e32 v15, v16, v13
	v_fma_f32 v12, -v12, v15, v14
	v_div_fmas_f32 v12, v12, v13, v15
	v_div_fixup_f32 v11, v12, v11, 2.0
	v_sub_f32_e32 v11, 1.0, v11
	v_add_f32_e32 v11, 1.0, v11
	v_mul_f32_e32 v10, v10, v11
	v_mul_f32_e32 v11, 0x3d372713, v6
	v_mul_f32_e32 v11, v11, v6
	v_fma_f32 v11, v11, v6, v6
	v_mul_f32_e32 v11, 0x3f4c422a, v11
	v_add_f32_e32 v11, v11, v11
	v_mul_f32_e32 v11, 0x3fb8aa3b, v11
	v_exp_f32_e32 v11, v11
	v_mul_f32_e32 v6, 0.5, v6
	v_add_f32_e32 v11, 1.0, v11
	v_div_scale_f32 v12, s[14:15], v11, v11, 2.0
	v_rcp_f32_e32 v13, v12
	s_nop 0
	v_fma_f32 v14, -v12, v13, 1.0
	v_fmac_f32_e32 v13, v14, v13
	v_div_scale_f32 v14, vcc, 2.0, v11, 2.0
	v_mul_f32_e32 v15, v14, v13
	v_fma_f32 v16, -v12, v15, v14
	v_fmac_f32_e32 v15, v16, v13
	v_fma_f32 v12, -v12, v15, v14
	v_div_fmas_f32 v12, v12, v13, v15
	v_div_fixup_f32 v11, v12, v11, 2.0
	v_sub_f32_e32 v11, 1.0, v11
	v_add_f32_e32 v11, 1.0, v11
	v_mul_f32_e32 v11, v6, v11
	v_lshlrev_b32_e32 v6, 16, v2
	v_mul_f32_e32 v12, 0x3d372713, v6
	v_mul_f32_e32 v12, v12, v6
	v_fma_f32 v12, v12, v6, v6
	v_mul_f32_e32 v12, 0x3f4c422a, v12
	v_add_f32_e32 v12, v12, v12
	v_mul_f32_e32 v12, 0x3fb8aa3b, v12
	v_exp_f32_e32 v12, v12
	v_mul_f32_e32 v6, 0.5, v6
	v_and_b32_e32 v2, 0xffff0000, v2
	v_cvt_pk_bf16_f32 v10, v10, v11
	v_add_f32_e32 v12, 1.0, v12
	v_div_scale_f32 v13, s[14:15], v12, v12, 2.0
	v_rcp_f32_e32 v14, v13
	s_nop 0
	v_fma_f32 v15, -v13, v14, 1.0
	v_fmac_f32_e32 v14, v15, v14
	v_div_scale_f32 v15, vcc, 2.0, v12, 2.0
	v_mul_f32_e32 v16, v15, v14
	v_fma_f32 v17, -v13, v16, v15
	v_fmac_f32_e32 v16, v17, v14
	v_fma_f32 v13, -v13, v16, v15
	v_div_fmas_f32 v13, v13, v14, v16
	v_div_fixup_f32 v12, v13, v12, 2.0
	v_sub_f32_e32 v12, 1.0, v12
	v_add_f32_e32 v12, 1.0, v12
	v_mul_f32_e32 v12, v6, v12
	v_mul_f32_e32 v6, 0x3d372713, v2
	v_mul_f32_e32 v6, v6, v2
	v_fma_f32 v6, v6, v2, v2
	v_mul_f32_e32 v6, 0x3f4c422a, v6
	v_add_f32_e32 v6, v6, v6
	v_mul_f32_e32 v6, 0x3fb8aa3b, v6
	v_exp_f32_e32 v6, v6
	v_mul_f32_e32 v2, 0.5, v2
	v_add_f32_e32 v6, 1.0, v6
	v_div_scale_f32 v13, s[14:15], v6, v6, 2.0
	v_rcp_f32_e32 v14, v13
	s_nop 0
	v_fma_f32 v15, -v13, v14, 1.0
	v_fmac_f32_e32 v14, v15, v14
	v_div_scale_f32 v15, vcc, 2.0, v6, 2.0
	v_mul_f32_e32 v16, v15, v14
	v_fma_f32 v17, -v13, v16, v15
	v_fmac_f32_e32 v16, v17, v14
	v_fma_f32 v13, -v13, v16, v15
	v_div_fmas_f32 v13, v13, v14, v16
	v_div_fixup_f32 v6, v13, v6, 2.0
	v_sub_f32_e32 v6, 1.0, v6
	v_add_f32_e32 v6, 1.0, v6
	v_mul_f32_e32 v13, v2, v6
	v_lshlrev_b32_e32 v2, 16, v7
	v_mul_f32_e32 v6, 0x3d372713, v2
	v_mul_f32_e32 v6, v6, v2
	v_fma_f32 v6, v6, v2, v2
	v_mul_f32_e32 v6, 0x3f4c422a, v6
	v_add_f32_e32 v6, v6, v6
	v_mul_f32_e32 v6, 0x3fb8aa3b, v6
	v_exp_f32_e32 v6, v6
	v_mul_f32_e32 v2, 0.5, v2
	v_add_f32_e32 v6, 1.0, v6
	v_div_scale_f32 v14, s[14:15], v6, v6, 2.0
	v_rcp_f32_e32 v15, v14
	s_nop 0
	v_fma_f32 v16, -v14, v15, 1.0
	v_fmac_f32_e32 v15, v16, v15
	v_div_scale_f32 v16, vcc, 2.0, v6, 2.0
	v_mul_f32_e32 v17, v16, v15
	v_fma_f32 v18, -v14, v17, v16
	v_fmac_f32_e32 v17, v18, v15
	v_fma_f32 v14, -v14, v17, v16
	v_div_fmas_f32 v14, v14, v15, v17
	v_div_fixup_f32 v6, v14, v6, 2.0
	v_sub_f32_e32 v6, 1.0, v6
	v_add_f32_e32 v6, 1.0, v6
	v_mul_f32_e32 v14, v2, v6
	v_and_b32_e32 v2, 0xffff0000, v7
	v_mul_f32_e32 v6, 0x3d372713, v2
	v_mul_f32_e32 v6, v6, v2
	v_fma_f32 v6, v6, v2, v2
	v_mul_f32_e32 v6, 0x3f4c422a, v6
	v_add_f32_e32 v6, v6, v6
	v_mul_f32_e32 v6, 0x3fb8aa3b, v6
	v_exp_f32_e32 v6, v6
	v_mul_f32_e32 v2, 0.5, v2
	v_add_f32_e32 v6, 1.0, v6
	v_div_scale_f32 v7, s[14:15], v6, v6, 2.0
	v_rcp_f32_e32 v15, v7
	s_nop 0
	v_fma_f32 v16, -v7, v15, 1.0
	v_fmac_f32_e32 v15, v16, v15
	v_div_scale_f32 v16, vcc, 2.0, v6, 2.0
	v_mul_f32_e32 v17, v16, v15
	v_fma_f32 v18, -v7, v17, v16
	v_fmac_f32_e32 v17, v18, v15
	v_fma_f32 v7, -v7, v17, v16
	v_div_fmas_f32 v7, v7, v15, v17
	v_div_fixup_f32 v6, v7, v6, 2.0
	v_sub_f32_e32 v6, 1.0, v6
	v_add_f32_e32 v6, 1.0, v6
	v_mul_f32_e32 v15, v2, v6
	v_lshlrev_b32_e32 v2, 16, v8
	v_mul_f32_e32 v6, 0x3d372713, v2
	v_mul_f32_e32 v6, v6, v2
	v_fma_f32 v6, v6, v2, v2
	v_mul_f32_e32 v6, 0x3f4c422a, v6
	v_add_f32_e32 v6, v6, v6
	v_mul_f32_e32 v6, 0x3fb8aa3b, v6
	v_exp_f32_e32 v6, v6
	v_mul_f32_e32 v2, 0.5, v2
	v_add_f32_e32 v6, 1.0, v6
	v_div_scale_f32 v7, s[14:15], v6, v6, 2.0
	v_rcp_f32_e32 v16, v7
	s_nop 0
	v_fma_f32 v17, -v7, v16, 1.0
	v_fmac_f32_e32 v16, v17, v16
	v_div_scale_f32 v17, vcc, 2.0, v6, 2.0
	v_mul_f32_e32 v18, v17, v16
	v_fma_f32 v19, -v7, v18, v17
	v_fmac_f32_e32 v18, v19, v16
	v_fma_f32 v7, -v7, v18, v17
	v_div_fmas_f32 v7, v7, v16, v18
	v_div_fixup_f32 v6, v7, v6, 2.0
	v_sub_f32_e32 v6, 1.0, v6
	v_add_f32_e32 v6, 1.0, v6
	v_mul_f32_e32 v16, v2, v6
	v_and_b32_e32 v2, 0xffff0000, v8
	v_mul_f32_e32 v6, 0x3d372713, v2
	v_mul_f32_e32 v6, v6, v2
	v_fma_f32 v6, v6, v2, v2
	v_mul_f32_e32 v6, 0x3f4c422a, v6
	v_add_f32_e32 v6, v6, v6
	v_mul_f32_e32 v6, 0x3fb8aa3b, v6
	v_exp_f32_e32 v6, v6
	v_mul_f32_e32 v2, 0.5, v2
	v_add_f32_e32 v6, 1.0, v6
	v_div_scale_f32 v7, s[14:15], v6, v6, 2.0
	v_rcp_f32_e32 v8, v7
	s_nop 0
	v_fma_f32 v17, -v7, v8, 1.0
	v_fmac_f32_e32 v8, v17, v8
	v_div_scale_f32 v17, vcc, 2.0, v6, 2.0
	v_mul_f32_e32 v18, v17, v8
	v_fma_f32 v19, -v7, v18, v17
	v_fmac_f32_e32 v18, v19, v8
	v_fma_f32 v7, -v7, v18, v17
	v_div_fmas_f32 v7, v7, v8, v18
	v_div_fixup_f32 v6, v7, v6, 2.0
	v_sub_f32_e32 v6, 1.0, v6
	v_add_f32_e32 v6, 1.0, v6
	v_mul_f32_e32 v8, v2, v6
	v_lshlrev_b32_e32 v2, 16, v9
	v_mul_f32_e32 v6, 0x3d372713, v2
	v_mul_f32_e32 v6, v6, v2
	v_fma_f32 v6, v6, v2, v2
	v_mul_f32_e32 v6, 0x3f4c422a, v6
	v_add_f32_e32 v6, v6, v6
	v_mul_f32_e32 v6, 0x3fb8aa3b, v6
	v_exp_f32_e32 v6, v6
	v_mul_f32_e32 v2, 0.5, v2
	v_add_f32_e32 v6, 1.0, v6
	v_div_scale_f32 v7, s[14:15], v6, v6, 2.0
	v_rcp_f32_e32 v17, v7
	s_nop 0
	v_fma_f32 v18, -v7, v17, 1.0
	v_fmac_f32_e32 v17, v18, v17
	v_div_scale_f32 v18, vcc, 2.0, v6, 2.0
	v_mul_f32_e32 v19, v18, v17
	v_fma_f32 v20, -v7, v19, v18
	v_fmac_f32_e32 v19, v20, v17
	v_fma_f32 v7, -v7, v19, v18
	v_div_fmas_f32 v7, v7, v17, v19
	v_div_fixup_f32 v6, v7, v6, 2.0
	v_sub_f32_e32 v6, 1.0, v6
	v_add_f32_e32 v6, 1.0, v6
	v_mul_f32_e32 v17, v2, v6
	v_and_b32_e32 v2, 0xffff0000, v9
	v_mul_f32_e32 v6, 0x3d372713, v2
	v_mul_f32_e32 v6, v6, v2
	v_fma_f32 v6, v6, v2, v2
	v_mul_f32_e32 v6, 0x3f4c422a, v6
	v_add_f32_e32 v6, v6, v6
	v_mul_f32_e32 v6, 0x3fb8aa3b, v6
	v_exp_f32_e32 v6, v6
	v_mul_f32_e32 v2, 0.5, v2
	v_add_f32_e32 v6, 1.0, v6
	v_div_scale_f32 v7, s[14:15], v6, v6, 2.0
	v_rcp_f32_e32 v9, v7
	s_nop 0
	v_fma_f32 v18, -v7, v9, 1.0
	v_fmac_f32_e32 v9, v18, v9
	v_div_scale_f32 v18, vcc, 2.0, v6, 2.0
	v_mul_f32_e32 v19, v18, v9
	v_fma_f32 v20, -v7, v19, v18
	v_fmac_f32_e32 v19, v20, v9
	v_fma_f32 v7, -v7, v19, v18
	v_div_fmas_f32 v7, v7, v9, v19
	v_div_fixup_f32 v6, v7, v6, 2.0
	v_sub_f32_e32 v6, 1.0, v6
	v_add_f32_e32 v6, 1.0, v6
	v_mul_f32_e32 v9, v2, v6
	v_and_b32_e32 v2, 0xffff0000, v3
	v_lshlrev_b32_e32 v3, 16, v3
	v_mul_f32_e32 v6, 0x3d372713, v3
	v_mul_f32_e32 v6, v6, v3
	v_mov_b32_e32 v7, v3
	v_fmac_f32_e32 v7, v6, v7
	v_mul_f32_e32 v6, 0x3f4c422a, v7
	v_add_f32_e32 v6, v6, v6
	v_mul_f32_e32 v6, 0x3fb8aa3b, v6
	v_exp_f32_e32 v7, v6
	v_mul_f32_e32 v6, 0x3d372713, v2
	v_mul_f32_e32 v6, v6, v2
	v_mov_b32_e32 v19, v2
	v_fmac_f32_e32 v19, v6, v19
	v_mul_f32_e32 v6, 0x3f4c422a, v19
	v_add_f32_e32 v6, v6, v6
	v_mul_f32_e32 v6, 0x3fb8aa3b, v6
	v_exp_f32_e32 v6, v6
	v_pk_mul_f32 v[2:3], v[2:3], 0.5 op_sel_hi:[1,0]
	v_mul_f32_e32 v18, v13, v13
	v_fmac_f32_e32 v18, v12, v12
	v_pk_add_f32 v[6:7], v[6:7], 1.0 op_sel_hi:[1,0]
	s_nop 0
	v_div_scale_f32 v19, s[14:15], v7, v7, 2.0
	v_rcp_f32_e32 v20, v19
	s_nop 0
	v_fma_f32 v21, -v19, v20, 1.0
	v_fmac_f32_e32 v20, v21, v20
	v_div_scale_f32 v21, vcc, 2.0, v7, 2.0
	v_mul_f32_e32 v22, v21, v20
	v_fma_f32 v23, -v19, v22, v21
	v_fmac_f32_e32 v22, v23, v20
	v_fma_f32 v19, -v19, v22, v21
	v_div_fmas_f32 v19, v19, v20, v22
	v_div_fixup_f32 v7, v19, v7, 2.0
	v_div_scale_f32 v19, s[14:15], v6, v6, 2.0
	v_rcp_f32_e32 v20, v19
	s_nop 0
	v_fma_f32 v21, -v19, v20, 1.0
	v_fmac_f32_e32 v20, v21, v20
	v_div_scale_f32 v21, vcc, 2.0, v6, 2.0
	v_mul_f32_e32 v22, v21, v20
	v_fma_f32 v23, -v19, v22, v21
	v_fmac_f32_e32 v22, v23, v20
	v_fma_f32 v19, -v19, v22, v21
	v_div_fmas_f32 v19, v19, v20, v22
	v_div_fixup_f32 v6, v19, v6, 2.0
	v_pk_add_f32 v[6:7], v[6:7], 1.0 op_sel_hi:[1,0] neg_lo:[1,0] neg_hi:[1,0]
	s_nop 0
	v_pk_add_f32 v[6:7], v[6:7], 1.0 op_sel_hi:[1,0]
	s_nop 0
	v_pk_mul_f32 v[2:3], v[2:3], v[6:7]
	s_nop 0
	v_pk_mul_f32 v[6:7], v[2:3], v[2:3]
	s_nop 0
	v_add_f32_e32 v7, v7, v18
	v_add_f32_e32 v20, v6, v7
	v_lshlrev_b32_e32 v7, 16, v4
	v_and_b32_e32 v6, 0xffff0000, v4
	v_mul_f32_e32 v4, 0x3d372713, v7
	v_mul_f32_e32 v4, v4, v7
	v_mov_b32_e32 v18, v7
	v_fmac_f32_e32 v18, v4, v18
	v_mul_f32_e32 v4, 0x3f4c422a, v18
	v_add_f32_e32 v4, v4, v4
	v_mul_f32_e32 v4, 0x3fb8aa3b, v4
	v_exp_f32_e32 v19, v4
	v_mul_f32_e32 v4, 0x3d372713, v6
	v_mul_f32_e32 v4, v4, v6
	v_mov_b32_e32 v18, v6
	v_fmac_f32_e32 v18, v4, v18
	v_mul_f32_e32 v4, 0x3f4c422a, v18
	v_add_f32_e32 v4, v4, v4
	v_mul_f32_e32 v4, 0x3fb8aa3b, v4
	v_exp_f32_e32 v18, v4
	v_pk_mul_f32 v[6:7], v[6:7], 0.5 op_sel_hi:[1,0]
	v_pk_add_f32 v[18:19], v[18:19], 1.0 op_sel_hi:[1,0]
	s_nop 0
	v_div_scale_f32 v4, s[14:15], v19, v19, 2.0
	v_rcp_f32_e32 v21, v4
	s_nop 0
	v_fma_f32 v22, -v4, v21, 1.0
	v_fmac_f32_e32 v21, v22, v21
	v_div_scale_f32 v22, vcc, 2.0, v19, 2.0
	v_mul_f32_e32 v23, v22, v21
	v_fma_f32 v24, -v4, v23, v22
	v_fmac_f32_e32 v23, v24, v21
	v_fma_f32 v4, -v4, v23, v22
	v_div_fmas_f32 v4, v4, v21, v23
	v_div_fixup_f32 v19, v4, v19, 2.0
	v_div_scale_f32 v4, s[14:15], v18, v18, 2.0
	v_rcp_f32_e32 v21, v4
	s_nop 0
	v_fma_f32 v22, -v4, v21, 1.0
	v_fmac_f32_e32 v21, v22, v21
	v_div_scale_f32 v22, vcc, 2.0, v18, 2.0
	v_mul_f32_e32 v23, v22, v21
	v_fma_f32 v24, -v4, v23, v22
	v_fmac_f32_e32 v23, v24, v21
	v_fma_f32 v4, -v4, v23, v22
	v_div_fmas_f32 v4, v4, v21, v23
	v_div_fixup_f32 v18, v4, v18, 2.0
	v_pk_add_f32 v[18:19], v[18:19], 1.0 op_sel_hi:[1,0] neg_lo:[1,0] neg_hi:[1,0]
	s_nop 0
	v_pk_add_f32 v[18:19], v[18:19], 1.0 op_sel_hi:[1,0]
	s_nop 0
	v_pk_mul_f32 v[6:7], v[6:7], v[18:19]
	s_nop 0
	v_pk_mul_f32 v[18:19], v[6:7], v[6:7]
	s_nop 0
	v_add_f32_e32 v4, v19, v20
	v_add_f32_e32 v20, v18, v4
	v_and_b32_e32 v4, 0xffff0000, v5
	v_lshlrev_b32_e32 v5, 16, v5
	v_mul_f32_e32 v18, 0x3d372713, v5
	v_mul_f32_e32 v18, v18, v5
	v_mov_b32_e32 v19, v5
	v_fmac_f32_e32 v19, v18, v19
	v_mul_f32_e32 v18, 0x3f4c422a, v19
	v_add_f32_e32 v18, v18, v18
	v_mul_f32_e32 v18, 0x3fb8aa3b, v18
	v_exp_f32_e32 v19, v18
	v_mul_f32_e32 v18, 0x3d372713, v4
	v_mul_f32_e32 v18, v18, v4
	v_mov_b32_e32 v21, v4
	v_fmac_f32_e32 v21, v18, v21
	v_mul_f32_e32 v18, 0x3f4c422a, v21
	v_add_f32_e32 v18, v18, v18
	v_mul_f32_e32 v18, 0x3fb8aa3b, v18
	v_exp_f32_e32 v18, v18
	v_pk_mul_f32 v[4:5], v[4:5], 0.5 op_sel_hi:[1,0]
	v_pk_add_f32 v[18:19], v[18:19], 1.0 op_sel_hi:[1,0]
	s_nop 0
	v_div_scale_f32 v21, s[14:15], v19, v19, 2.0
	v_rcp_f32_e32 v22, v21
	s_nop 0
	v_fma_f32 v23, -v21, v22, 1.0
	v_fmac_f32_e32 v22, v23, v22
	v_div_scale_f32 v23, vcc, 2.0, v19, 2.0
	v_mul_f32_e32 v24, v23, v22
	v_fma_f32 v25, -v21, v24, v23
	v_fmac_f32_e32 v24, v25, v22
	v_fma_f32 v21, -v21, v24, v23
	v_div_fmas_f32 v21, v21, v22, v24
	v_div_fixup_f32 v19, v21, v19, 2.0
	v_div_scale_f32 v21, s[14:15], v18, v18, 2.0
	v_rcp_f32_e32 v22, v21
	s_nop 0
	v_fma_f32 v23, -v21, v22, 1.0
	v_fmac_f32_e32 v22, v23, v22
	v_div_scale_f32 v23, vcc, 2.0, v18, 2.0
	v_mul_f32_e32 v24, v23, v22
	v_fma_f32 v25, -v21, v24, v23
	v_fmac_f32_e32 v24, v25, v22
	v_fma_f32 v21, -v21, v24, v23
	v_div_fmas_f32 v21, v21, v22, v24
	v_div_fixup_f32 v18, v21, v18, 2.0
	v_pk_add_f32 v[18:19], v[18:19], 1.0 op_sel_hi:[1,0] neg_lo:[1,0] neg_hi:[1,0]
	s_nop 0
	v_pk_add_f32 v[18:19], v[18:19], 1.0 op_sel_hi:[1,0]
	s_nop 0
	v_pk_mul_f32 v[18:19], v[4:5], v[18:19]
	s_nop 0
	v_pk_mul_f32 v[4:5], v[18:19], v[18:19]
	s_nop 0
	v_add_f32_e32 v5, v5, v20
	v_add_f32_e32 v4, v4, v5
	ds_bpermute_b32 v5, v106, v4
	s_waitcnt lgkmcnt(0)
	v_add_f32_e32 v4, v4, v5
	ds_bpermute_b32 v5, v107, v4
	s_waitcnt lgkmcnt(0)
	v_add_f32_e32 v4, v4, v5
	ds_bpermute_b32 v5, v108, v4
	s_waitcnt lgkmcnt(0)
	v_add_f32_e32 v4, v4, v5
	ds_bpermute_b32 v5, v109, v4
	s_waitcnt lgkmcnt(0)
	v_add_f32_e32 v4, v4, v5
	ds_bpermute_b32 v5, v110, v4
	s_waitcnt lgkmcnt(0)
	v_add_f32_e32 v4, v4, v5
	v_fmamk_f32 v4, v4, 0x3b800000, v243
	v_cmp_gt_f32_e32 vcc, s3, v4
	v_mul_f32_e32 v5, 0x4b800000, v4
	s_nop 0
	v_cndmask_b32_e32 v4, v4, v5, vcc
	v_rsq_f32_e32 v4, v4
	s_nop 0
	v_mul_f32_e32 v5, 0x45800000, v4
	v_cndmask_b32_e32 v20, v4, v5, vcc
	v_mul_f32_e32 v4, v12, v20
	v_mul_f32_e32 v5, v13, v20
	v_mul_f32_e32 v2, v2, v20
	v_mul_f32_e32 v4, v70, v4
	v_mul_f32_e32 v5, v71, v5
	v_mul_f32_e32 v3, v3, v20
	v_mul_f32_e32 v2, v73, v2
	v_cvt_pk_bf16_f32 v4, v4, v5
	v_cvt_pk_bf16_f32 v11, v14, v15
	v_mul_f32_e32 v3, v72, v3
	v_cvt_pk_bf16_f32 v5, v3, v2
	v_mul_f32_e32 v2, v7, v20
	v_mul_f32_e32 v2, v66, v2
	v_mul_f32_e32 v3, v6, v20
	v_cvt_pk_bf16_f32 v12, v16, v8
	v_mul_f32_e32 v3, v67, v3
	v_cvt_pk_bf16_f32 v6, v2, v3
	v_mul_f32_e32 v2, v19, v20
	v_mul_f32_e32 v2, v68, v2
	v_mul_f32_e32 v3, v18, v20
	v_cvt_pk_bf16_f32 v13, v17, v9
	v_mul_f32_e32 v3, v69, v3
	v_cvt_pk_bf16_f32 v7, v2, v3
	global_load_dword v204, v[74:75], off
	global_load_dword v205, v[74:75], off offset:128
	v_lshl_add_u64 v[200:201], v[98:99], 0, v[0:1]
	v_lshl_add_u64 v[202:203], v[100:101], 0, v[0:1]
	v_lshl_add_u64 v[200:201], s[4:5], 0, v[200:201]
	v_lshl_add_u64 v[202:203], s[4:5], 0, v[202:203]
	global_load_dwordx4 v[136:139], v[200:201], off
	global_load_dwordx4 v[140:143], v[202:203], off
	global_load_dwordx4 v[144:147], v[200:201], off offset:32
	global_load_dwordx4 v[148:151], v[202:203], off offset:32
	global_load_dwordx4 v[152:155], v[200:201], off offset:64
	global_load_dwordx4 v[156:159], v[202:203], off offset:64
	global_load_dwordx4 v[160:163], v[200:201], off offset:96
	global_load_dwordx4 v[164:167], v[202:203], off offset:96
	global_load_dwordx4 v[168:171], v[200:201], off offset:128
	global_load_dwordx4 v[172:175], v[202:203], off offset:128
	global_load_dwordx4 v[176:179], v[200:201], off offset:160
	global_load_dwordx4 v[180:183], v[202:203], off offset:160
	global_load_dwordx4 v[184:187], v[200:201], off offset:192
	global_load_dwordx4 v[188:191], v[202:203], off offset:192
	global_load_dwordx4 v[192:195], v[200:201], off offset:224
	global_load_dwordx4 v[196:199], v[202:203], off offset:224
	v_mov_b32_e32 v2, 0
	ds_write_b128 v111, v[10:13] offset:60928
	ds_write_b128 v112, v[4:7] offset:60928
	v_mov_b32_e32 v3, v2
	v_mov_b32_e32 v4, v2
	v_mov_b32_e32 v5, v2
	v_mov_b32_e32 v6, v2
	v_mov_b32_e32 v7, v2
	v_mov_b32_e32 v8, v2
	v_mov_b32_e32 v9, v2
	v_mov_b32_e32 v10, v2
	v_mov_b32_e32 v11, v2
	v_mov_b32_e32 v12, v2
	v_mov_b32_e32 v13, v2
	v_mov_b32_e32 v14, v2
	v_mov_b32_e32 v15, v2
	v_mov_b32_e32 v16, v2
	v_mov_b32_e32 v17, v2
	v_mov_b32_e32 v18, v2
	v_mov_b32_e32 v19, v2
	v_mov_b32_e32 v20, v2
	v_mov_b32_e32 v21, v2
	v_mov_b32_e32 v22, v2
	v_mov_b32_e32 v23, v2
	v_mov_b32_e32 v24, v2
	v_mov_b32_e32 v25, v2
	v_mov_b32_e32 v26, v2
	v_mov_b32_e32 v27, v2
	v_mov_b32_e32 v28, v2
	v_mov_b32_e32 v29, v2
	v_mov_b32_e32 v30, v2
	v_mov_b32_e32 v31, v2
	v_mov_b32_e32 v32, v2
	v_mov_b32_e32 v33, v2
	v_mov_b32_e32 v34, v2
	v_mov_b32_e32 v35, v2
	v_mov_b32_e32 v36, v2
	v_mov_b32_e32 v37, v2
	v_mov_b32_e32 v38, v2
	v_mov_b32_e32 v39, v2
	v_mov_b32_e32 v40, v2
	v_mov_b32_e32 v41, v2
	v_mov_b32_e32 v42, v2
	v_mov_b32_e32 v43, v2
	v_mov_b32_e32 v44, v2
	v_mov_b32_e32 v45, v2
	v_mov_b32_e32 v46, v2
	v_mov_b32_e32 v47, v2
	v_mov_b32_e32 v48, v2
	v_mov_b32_e32 v49, v2
	v_mov_b32_e32 v50, v2
	v_mov_b32_e32 v51, v2
	v_mov_b32_e32 v52, v2
	v_mov_b32_e32 v53, v2
	v_mov_b32_e32 v54, v2
	v_mov_b32_e32 v55, v2
	v_mov_b32_e32 v56, v2
	v_mov_b32_e32 v57, v2
	v_mov_b32_e32 v58, v2
	v_mov_b32_e32 v59, v2
	v_mov_b32_e32 v60, v2
	v_mov_b32_e32 v61, v2
	v_mov_b32_e32 v62, v2
	v_mov_b32_e32 v63, v2
	v_mov_b32_e32 v64, v2
	v_mov_b32_e32 v65, v2
	s_waitcnt lgkmcnt(0)
	s_barrier
.LBB0_278:
	s_waitcnt vmcnt(0)
	s_nop 0
	v_add_u32_e32 v115, s5, v114
	v_add_u32_e32 v124, 0x11000, v115
	v_add_u32_e32 v126, 0x11880, v115
	v_add_u32_e32 v128, 0x11040, v115
	v_add_u32_e32 v130, 0x118c0, v115
	ds_read_b64_tr_b16 v[124:125], v124
	ds_read_b64_tr_b16 v[126:127], v126
	ds_read_b64_tr_b16 v[128:129], v128
	ds_read_b64_tr_b16 v[130:131], v130
	s_addk_i32 s5, 0x4400
	s_waitcnt lgkmcnt(2)
	v_mfma_f32_32x32x16_bf16 v[50:65], v[124:127], v[136:139], v[50:65]
	s_waitcnt lgkmcnt(0)
	v_mfma_f32_32x32x16_bf16 v[34:49], v[128:131], v[136:139], v[34:49]
	v_mfma_f32_32x32x16_bf16 v[18:33], v[124:127], v[140:143], v[18:33]
	v_add_u32_e32 v124, 0x13200, v115
	v_add_u32_e32 v126, 0x13a80, v115
	v_mfma_f32_32x32x16_bf16 v[2:17], v[128:131], v[140:143], v[2:17]
	v_add_u32_e32 v128, 0x13240, v115
	ds_read_b64_tr_b16 v[124:125], v124
	ds_read_b64_tr_b16 v[126:127], v126
	v_add_u32_e32 v115, 0x13ac0, v115
	ds_read_b64_tr_b16 v[128:129], v128
	ds_read_b64_tr_b16 v[130:131], v115
	s_waitcnt lgkmcnt(2)
	v_mfma_f32_32x32x16_bf16 v[50:65], v[124:127], v[144:147], v[50:65]
	s_waitcnt lgkmcnt(0)
	v_mfma_f32_32x32x16_bf16 v[34:49], v[128:131], v[144:147], v[34:49]
	v_mfma_f32_32x32x16_bf16 v[18:33], v[124:127], v[148:151], v[18:33]
	v_mfma_f32_32x32x16_bf16 v[2:17], v[128:131], v[148:151], v[2:17]
	s_nop 0
	v_add_u32_e32 v115, s5, v114
	v_add_u32_e32 v124, 0x11000, v115
	v_add_u32_e32 v126, 0x11880, v115
	v_add_u32_e32 v128, 0x11040, v115
	v_add_u32_e32 v130, 0x118c0, v115
	ds_read_b64_tr_b16 v[124:125], v124
	ds_read_b64_tr_b16 v[126:127], v126
	ds_read_b64_tr_b16 v[128:129], v128
	ds_read_b64_tr_b16 v[130:131], v130
	s_addk_i32 s5, 0x4400
	s_waitcnt lgkmcnt(2)
	v_mfma_f32_32x32x16_bf16 v[50:65], v[124:127], v[152:155], v[50:65]
	s_waitcnt lgkmcnt(0)
	v_mfma_f32_32x32x16_bf16 v[34:49], v[128:131], v[152:155], v[34:49]
	v_mfma_f32_32x32x16_bf16 v[18:33], v[124:127], v[156:159], v[18:33]
	v_add_u32_e32 v124, 0x13200, v115
	v_add_u32_e32 v126, 0x13a80, v115
	v_mfma_f32_32x32x16_bf16 v[2:17], v[128:131], v[156:159], v[2:17]
	v_add_u32_e32 v128, 0x13240, v115
	ds_read_b64_tr_b16 v[124:125], v124
	ds_read_b64_tr_b16 v[126:127], v126
	v_add_u32_e32 v115, 0x13ac0, v115
	ds_read_b64_tr_b16 v[128:129], v128
	ds_read_b64_tr_b16 v[130:131], v115
	s_waitcnt lgkmcnt(2)
	v_mfma_f32_32x32x16_bf16 v[50:65], v[124:127], v[160:163], v[50:65]
	s_waitcnt lgkmcnt(0)
	v_mfma_f32_32x32x16_bf16 v[34:49], v[128:131], v[160:163], v[34:49]
	v_mfma_f32_32x32x16_bf16 v[18:33], v[124:127], v[164:167], v[18:33]
	v_mfma_f32_32x32x16_bf16 v[2:17], v[128:131], v[164:167], v[2:17]
	s_nop 0
	v_add_u32_e32 v115, s5, v114
	v_add_u32_e32 v124, 0x11000, v115
	v_add_u32_e32 v126, 0x11880, v115
	v_add_u32_e32 v128, 0x11040, v115
	v_add_u32_e32 v130, 0x118c0, v115
	ds_read_b64_tr_b16 v[124:125], v124
	ds_read_b64_tr_b16 v[126:127], v126
	ds_read_b64_tr_b16 v[128:129], v128
	ds_read_b64_tr_b16 v[130:131], v130
	s_addk_i32 s5, 0x4400
	s_waitcnt lgkmcnt(2)
	v_mfma_f32_32x32x16_bf16 v[50:65], v[124:127], v[168:171], v[50:65]
	s_waitcnt lgkmcnt(0)
	v_mfma_f32_32x32x16_bf16 v[34:49], v[128:131], v[168:171], v[34:49]
	v_mfma_f32_32x32x16_bf16 v[18:33], v[124:127], v[172:175], v[18:33]
	v_add_u32_e32 v124, 0x13200, v115
	v_add_u32_e32 v126, 0x13a80, v115
	v_mfma_f32_32x32x16_bf16 v[2:17], v[128:131], v[172:175], v[2:17]
	v_add_u32_e32 v128, 0x13240, v115
	ds_read_b64_tr_b16 v[124:125], v124
	ds_read_b64_tr_b16 v[126:127], v126
	v_add_u32_e32 v115, 0x13ac0, v115
	ds_read_b64_tr_b16 v[128:129], v128
	ds_read_b64_tr_b16 v[130:131], v115
	s_waitcnt lgkmcnt(2)
	v_mfma_f32_32x32x16_bf16 v[50:65], v[124:127], v[176:179], v[50:65]
	s_waitcnt lgkmcnt(0)
	v_mfma_f32_32x32x16_bf16 v[34:49], v[128:131], v[176:179], v[34:49]
	v_mfma_f32_32x32x16_bf16 v[18:33], v[124:127], v[180:183], v[18:33]
	v_mfma_f32_32x32x16_bf16 v[2:17], v[128:131], v[180:183], v[2:17]
	s_nop 0
	v_add_u32_e32 v115, s5, v114
	v_add_u32_e32 v124, 0x11000, v115
	v_add_u32_e32 v126, 0x11880, v115
	v_add_u32_e32 v128, 0x11040, v115
	v_add_u32_e32 v130, 0x118c0, v115
	ds_read_b64_tr_b16 v[124:125], v124
	ds_read_b64_tr_b16 v[126:127], v126
	ds_read_b64_tr_b16 v[128:129], v128
	ds_read_b64_tr_b16 v[130:131], v130
	s_addk_i32 s5, 0x4400
	s_waitcnt lgkmcnt(2)
	v_mfma_f32_32x32x16_bf16 v[50:65], v[124:127], v[184:187], v[50:65]
	s_waitcnt lgkmcnt(0)
	v_mfma_f32_32x32x16_bf16 v[34:49], v[128:131], v[184:187], v[34:49]
	v_mfma_f32_32x32x16_bf16 v[18:33], v[124:127], v[188:191], v[18:33]
	v_add_u32_e32 v124, 0x13200, v115
	v_add_u32_e32 v126, 0x13a80, v115
	v_mfma_f32_32x32x16_bf16 v[2:17], v[128:131], v[188:191], v[2:17]
	v_add_u32_e32 v128, 0x13240, v115
	ds_read_b64_tr_b16 v[124:125], v124
	ds_read_b64_tr_b16 v[126:127], v126
	v_add_u32_e32 v115, 0x13ac0, v115
	ds_read_b64_tr_b16 v[128:129], v128
	ds_read_b64_tr_b16 v[130:131], v115
	s_waitcnt lgkmcnt(2)
	v_mfma_f32_32x32x16_bf16 v[50:65], v[124:127], v[192:195], v[50:65]
	s_waitcnt lgkmcnt(0)
	v_mfma_f32_32x32x16_bf16 v[34:49], v[128:131], v[192:195], v[34:49]
	v_mfma_f32_32x32x16_bf16 v[18:33], v[124:127], v[196:199], v[18:33]
	v_mfma_f32_32x32x16_bf16 v[2:17], v[128:131], v[196:199], v[2:17]
	ds_read_b64 v[116:117], v113
	v_or_b32_e32 v98, s11, v103
	v_ashrrev_i32_e32 v99, 31, v98
	v_lshlrev_b64 v[98:99], 11, v[98:99]
	v_lshl_add_u64 v[98:99], s[28:29], 0, v[98:99]
	s_waitcnt lgkmcnt(0)
	v_lshlrev_b32_e32 v101, 16, v116
	s_mov_b64 s[14:15], 0xcb00200
	v_lshl_add_u64 v[98:99], v[98:99], 0, s[14:15]
	s_mov_b32 s5, s54
	s_waitcnt vmcnt(0)
	v_add_f32_e32 v50, v50, v204
	v_mul_f32_e32 v50, v50, v101
	v_add_f32_e32 v51, v51, v204
	v_and_b32_e32 v101, 0xffff0000, v116
	v_mul_f32_e32 v51, v51, v101
	v_cvt_pk_bf16_f32 v50, v50, v51
	v_add_f32_e32 v51, v52, v204
	v_lshlrev_b32_e32 v52, 16, v117
	v_mul_f32_e32 v51, v51, v52
	v_add_f32_e32 v52, v53, v204
	v_and_b32_e32 v53, 0xffff0000, v117
	v_mul_f32_e32 v52, v52, v53
	v_cvt_pk_bf16_f32 v51, v51, v52
	v_lshl_add_u64 v[52:53], v[98:99], 0, v[82:83]
	global_store_dwordx2 v[52:53], v[50:51], off
	ds_read_b64 v[50:51], v113 offset:16
	v_add_f32_e32 v52, v54, v204
	v_add_f32_e32 v34, v34, v204
	v_add_f32_e32 v35, v35, v204
	s_waitcnt lgkmcnt(0)
	v_lshlrev_b32_e32 v53, 16, v50
	v_mul_f32_e32 v52, v52, v53
	v_add_f32_e32 v53, v55, v204
	v_and_b32_e32 v50, 0xffff0000, v50
	v_mul_f32_e32 v50, v53, v50
	v_cvt_pk_bf16_f32 v50, v52, v50
	v_add_f32_e32 v52, v56, v204
	v_lshlrev_b32_e32 v53, 16, v51
	v_mul_f32_e32 v52, v52, v53
	v_add_f32_e32 v53, v57, v204
	v_and_b32_e32 v51, 0xffff0000, v51
	v_mul_f32_e32 v51, v53, v51
	v_cvt_pk_bf16_f32 v51, v52, v51
	v_lshl_add_u64 v[52:53], v[98:99], 0, v[84:85]
	global_store_dwordx2 v[52:53], v[50:51], off
	ds_read_b64 v[50:51], v113 offset:32
	v_add_f32_e32 v52, v58, v204
	s_waitcnt lgkmcnt(0)
	v_lshlrev_b32_e32 v53, 16, v50
	v_mul_f32_e32 v52, v52, v53
	v_add_f32_e32 v53, v59, v204
	v_and_b32_e32 v50, 0xffff0000, v50
	v_mul_f32_e32 v50, v53, v50
	v_cvt_pk_bf16_f32 v50, v52, v50
	v_add_f32_e32 v52, v60, v204
	v_lshlrev_b32_e32 v53, 16, v51
	v_mul_f32_e32 v52, v52, v53
	v_add_f32_e32 v53, v61, v204
	v_and_b32_e32 v51, 0xffff0000, v51
	v_mul_f32_e32 v51, v53, v51
	v_cvt_pk_bf16_f32 v51, v52, v51
	v_lshl_add_u64 v[52:53], v[98:99], 0, v[86:87]
	global_store_dwordx2 v[52:53], v[50:51], off
	ds_read_b64 v[50:51], v113 offset:48
	v_add_f32_e32 v52, v62, v204
	s_waitcnt lgkmcnt(0)
	v_lshlrev_b32_e32 v53, 16, v50
	v_mul_f32_e32 v52, v52, v53
	v_add_f32_e32 v53, v63, v204
	v_and_b32_e32 v50, 0xffff0000, v50
	v_mul_f32_e32 v50, v53, v50
	v_cvt_pk_bf16_f32 v50, v52, v50
	v_add_f32_e32 v52, v64, v204
	v_lshlrev_b32_e32 v53, 16, v51
	v_mul_f32_e32 v52, v52, v53
	v_add_f32_e32 v53, v65, v204
	v_and_b32_e32 v51, 0xffff0000, v51
	v_mul_f32_e32 v51, v53, v51
	v_cvt_pk_bf16_f32 v51, v52, v51
	v_lshl_add_u64 v[52:53], v[98:99], 0, v[88:89]
	global_store_dwordx2 v[52:53], v[50:51], off
	ds_read_b64 v[50:51], v113 offset:64
	s_waitcnt lgkmcnt(0)
	v_lshlrev_b32_e32 v52, 16, v50
	v_and_b32_e32 v50, 0xffff0000, v50
	v_mul_f32_e32 v34, v34, v52
	v_mul_f32_e32 v35, v35, v50
	v_cvt_pk_bf16_f32 v34, v34, v35
	v_add_f32_e32 v35, v36, v204
	v_lshlrev_b32_e32 v36, 16, v51
	v_mul_f32_e32 v35, v35, v36
	v_add_f32_e32 v36, v37, v204
	v_and_b32_e32 v37, 0xffff0000, v51
	v_mul_f32_e32 v36, v36, v37
	v_cvt_pk_bf16_f32 v35, v35, v36
	v_lshl_add_u64 v[36:37], v[98:99], 0, v[90:91]
	global_store_dwordx2 v[36:37], v[34:35], off
	ds_read_b64 v[34:35], v113 offset:80
	v_add_f32_e32 v36, v38, v204
	s_waitcnt lgkmcnt(0)
	v_lshlrev_b32_e32 v37, 16, v34
	v_mul_f32_e32 v36, v36, v37
	v_add_f32_e32 v37, v39, v204
	v_and_b32_e32 v34, 0xffff0000, v34
	v_mul_f32_e32 v34, v37, v34
	v_cvt_pk_bf16_f32 v34, v36, v34
	v_add_f32_e32 v36, v40, v204
	v_lshlrev_b32_e32 v37, 16, v35
	v_mul_f32_e32 v36, v36, v37
	v_add_f32_e32 v37, v41, v204
	v_and_b32_e32 v35, 0xffff0000, v35
	v_mul_f32_e32 v35, v37, v35
	v_cvt_pk_bf16_f32 v35, v36, v35
	v_lshl_add_u64 v[36:37], v[98:99], 0, v[92:93]
	global_store_dwordx2 v[36:37], v[34:35], off
	ds_read_b64 v[34:35], v113 offset:96
	v_add_f32_e32 v36, v42, v204
	s_waitcnt lgkmcnt(0)
	v_lshlrev_b32_e32 v37, 16, v34
	v_mul_f32_e32 v36, v36, v37
	v_add_f32_e32 v37, v43, v204
	v_and_b32_e32 v34, 0xffff0000, v34
	v_mul_f32_e32 v34, v37, v34
	v_cvt_pk_bf16_f32 v34, v36, v34
	v_add_f32_e32 v36, v44, v204
	v_lshlrev_b32_e32 v37, 16, v35
	v_mul_f32_e32 v36, v36, v37
	v_add_f32_e32 v37, v45, v204
	v_and_b32_e32 v35, 0xffff0000, v35
	v_mul_f32_e32 v35, v37, v35
	v_cvt_pk_bf16_f32 v35, v36, v35
	v_lshl_add_u64 v[36:37], v[98:99], 0, v[94:95]
	global_store_dwordx2 v[36:37], v[34:35], off
	ds_read_b64 v[34:35], v113 offset:112
	v_add_f32_e32 v36, v46, v204
	s_waitcnt lgkmcnt(0)
	v_lshlrev_b32_e32 v37, 16, v34
	v_mul_f32_e32 v36, v36, v37
	v_add_f32_e32 v37, v47, v204
	v_and_b32_e32 v34, 0xffff0000, v34
	v_mul_f32_e32 v34, v37, v34
	v_cvt_pk_bf16_f32 v34, v36, v34
	v_add_f32_e32 v36, v48, v204
	v_lshlrev_b32_e32 v37, 16, v35
	v_mul_f32_e32 v36, v36, v37
	v_add_f32_e32 v37, v49, v204
	v_and_b32_e32 v35, 0xffff0000, v35
	v_mul_f32_e32 v35, v37, v35
	v_cvt_pk_bf16_f32 v35, v36, v35
	v_lshl_add_u64 v[36:37], v[98:99], 0, v[96:97]
	global_store_dwordx2 v[36:37], v[34:35], off
	ds_read_b64 v[38:39], v105
	v_or_b32_e32 v34, s11, v104
	v_ashrrev_i32_e32 v35, 31, v34
	v_lshlrev_b64 v[34:35], 11, v[34:35]
	v_lshl_add_u64 v[34:35], s[28:29], 0, v[34:35]
	s_waitcnt lgkmcnt(0)
	v_lshlrev_b32_e32 v37, 16, v38
	v_lshl_add_u64 v[34:35], v[34:35], 0, s[14:15]
	v_add_f32_e32 v18, v18, v205
	v_mul_f32_e32 v18, v18, v37
	v_add_f32_e32 v19, v19, v205
	v_and_b32_e32 v37, 0xffff0000, v38
	v_mul_f32_e32 v19, v19, v37
	v_cvt_pk_bf16_f32 v18, v18, v19
	v_add_f32_e32 v19, v20, v205
	v_lshlrev_b32_e32 v20, 16, v39
	v_mul_f32_e32 v19, v19, v20
	v_add_f32_e32 v20, v21, v205
	v_and_b32_e32 v21, 0xffff0000, v39
	v_mul_f32_e32 v20, v20, v21
	v_cvt_pk_bf16_f32 v19, v19, v20
	v_lshl_add_u64 v[20:21], v[34:35], 0, v[82:83]
	global_store_dwordx2 v[20:21], v[18:19], off
	ds_read_b64 v[18:19], v105 offset:16
	v_add_f32_e32 v20, v22, v205
	v_add_f32_e32 v2, v2, v205
	v_add_f32_e32 v3, v3, v205
	s_waitcnt lgkmcnt(0)
	v_lshlrev_b32_e32 v21, 16, v18
	v_mul_f32_e32 v20, v20, v21
	v_add_f32_e32 v21, v23, v205
	v_and_b32_e32 v18, 0xffff0000, v18
	v_mul_f32_e32 v18, v21, v18
	v_cvt_pk_bf16_f32 v18, v20, v18
	v_add_f32_e32 v20, v24, v205
	v_lshlrev_b32_e32 v21, 16, v19
	v_mul_f32_e32 v20, v20, v21
	v_add_f32_e32 v21, v25, v205
	v_and_b32_e32 v19, 0xffff0000, v19
	v_mul_f32_e32 v19, v21, v19
	v_cvt_pk_bf16_f32 v19, v20, v19
	v_lshl_add_u64 v[20:21], v[34:35], 0, v[84:85]
	global_store_dwordx2 v[20:21], v[18:19], off
	ds_read_b64 v[18:19], v105 offset:32
	v_add_f32_e32 v20, v26, v205
	s_waitcnt lgkmcnt(0)
	v_lshlrev_b32_e32 v21, 16, v18
	v_mul_f32_e32 v20, v20, v21
	v_add_f32_e32 v21, v27, v205
	v_and_b32_e32 v18, 0xffff0000, v18
	v_mul_f32_e32 v18, v21, v18
	v_cvt_pk_bf16_f32 v18, v20, v18
	v_add_f32_e32 v20, v28, v205
	v_lshlrev_b32_e32 v21, 16, v19
	v_mul_f32_e32 v20, v20, v21
	v_add_f32_e32 v21, v29, v205
	v_and_b32_e32 v19, 0xffff0000, v19
	v_mul_f32_e32 v19, v21, v19
	v_cvt_pk_bf16_f32 v19, v20, v19
	v_lshl_add_u64 v[20:21], v[34:35], 0, v[86:87]
	global_store_dwordx2 v[20:21], v[18:19], off
	ds_read_b64 v[18:19], v105 offset:48
	v_add_f32_e32 v20, v30, v205
	s_waitcnt lgkmcnt(0)
	v_lshlrev_b32_e32 v21, 16, v18
	v_mul_f32_e32 v20, v20, v21
	v_add_f32_e32 v21, v31, v205
	v_and_b32_e32 v18, 0xffff0000, v18
	v_mul_f32_e32 v18, v21, v18
	v_cvt_pk_bf16_f32 v18, v20, v18
	v_add_f32_e32 v20, v32, v205
	v_lshlrev_b32_e32 v21, 16, v19
	v_mul_f32_e32 v20, v20, v21
	v_add_f32_e32 v21, v33, v205
	v_and_b32_e32 v19, 0xffff0000, v19
	v_mul_f32_e32 v19, v21, v19
	v_cvt_pk_bf16_f32 v19, v20, v19
	v_lshl_add_u64 v[20:21], v[34:35], 0, v[88:89]
	global_store_dwordx2 v[20:21], v[18:19], off
	ds_read_b64 v[18:19], v105 offset:64
	s_waitcnt lgkmcnt(0)
	v_lshlrev_b32_e32 v20, 16, v18
	v_and_b32_e32 v18, 0xffff0000, v18
	v_mul_f32_e32 v2, v2, v20
	v_mul_f32_e32 v3, v3, v18
	v_cvt_pk_bf16_f32 v2, v2, v3
	v_add_f32_e32 v3, v4, v205
	v_lshlrev_b32_e32 v4, 16, v19
	v_mul_f32_e32 v3, v3, v4
	v_add_f32_e32 v4, v5, v205
	v_and_b32_e32 v5, 0xffff0000, v19
	v_mul_f32_e32 v4, v4, v5
	v_cvt_pk_bf16_f32 v3, v3, v4
	v_lshl_add_u64 v[4:5], v[34:35], 0, v[90:91]
	global_store_dwordx2 v[4:5], v[2:3], off
	ds_read_b64 v[2:3], v105 offset:80
	v_add_f32_e32 v4, v6, v205
	s_waitcnt lgkmcnt(0)
	v_lshlrev_b32_e32 v5, 16, v2
	v_mul_f32_e32 v4, v4, v5
	v_add_f32_e32 v5, v7, v205
	v_and_b32_e32 v2, 0xffff0000, v2
	v_mul_f32_e32 v2, v5, v2
	v_cvt_pk_bf16_f32 v2, v4, v2
	v_add_f32_e32 v4, v8, v205
	v_lshlrev_b32_e32 v5, 16, v3
	v_mul_f32_e32 v4, v4, v5
	v_add_f32_e32 v5, v9, v205
	v_and_b32_e32 v3, 0xffff0000, v3
	v_mul_f32_e32 v3, v5, v3
	v_cvt_pk_bf16_f32 v3, v4, v3
	v_lshl_add_u64 v[4:5], v[34:35], 0, v[92:93]
	global_store_dwordx2 v[4:5], v[2:3], off
	ds_read_b64 v[2:3], v105 offset:96
	v_add_f32_e32 v4, v10, v205
	s_waitcnt lgkmcnt(0)
	v_lshlrev_b32_e32 v5, 16, v2
	v_mul_f32_e32 v4, v4, v5
	v_add_f32_e32 v5, v11, v205
	v_and_b32_e32 v2, 0xffff0000, v2
	v_mul_f32_e32 v2, v5, v2
	v_cvt_pk_bf16_f32 v2, v4, v2
	v_add_f32_e32 v4, v12, v205
	v_lshlrev_b32_e32 v5, 16, v3
	v_mul_f32_e32 v4, v4, v5
	v_add_f32_e32 v5, v13, v205
	v_and_b32_e32 v3, 0xffff0000, v3
	v_mul_f32_e32 v3, v5, v3
	v_cvt_pk_bf16_f32 v3, v4, v3
	v_lshl_add_u64 v[4:5], v[34:35], 0, v[94:95]
	global_store_dwordx2 v[4:5], v[2:3], off
	ds_read_b64 v[2:3], v105 offset:112
	v_add_f32_e32 v4, v14, v205
	s_waitcnt lgkmcnt(0)
	v_lshlrev_b32_e32 v5, 16, v2
	v_mul_f32_e32 v4, v4, v5
	v_add_f32_e32 v5, v15, v205
	v_and_b32_e32 v2, 0xffff0000, v2
	v_mul_f32_e32 v2, v5, v2
	v_cvt_pk_bf16_f32 v2, v4, v2
	v_add_f32_e32 v4, v16, v205
	v_lshlrev_b32_e32 v5, 16, v3
	v_mul_f32_e32 v4, v4, v5
	v_add_f32_e32 v5, v17, v205
	v_and_b32_e32 v3, 0xffff0000, v3
	v_mul_f32_e32 v3, v5, v3
	v_cvt_pk_bf16_f32 v3, v4, v3
	v_lshl_add_u64 v[4:5], v[34:35], 0, v[96:97]
	global_store_dwordx2 v[4:5], v[2:3], off
	s_barrier
	s_add_i32 s10, s5, s10
	s_cmpk_lt_i32 s10, 0xc0
	s_cbranch_scc1 .LBB0_277

.LBB0_498:
	s_or_b64 exec, exec, s[10:11]
	s_nop 0
	s_waitcnt lgkmcnt(10)
	v_mfma_f32_32x32x16_bf16 v[34:49], v[148:151], v[74:77], v[218:233]
	v_mfma_f32_32x32x16_bf16 v[50:65], v[152:155], v[74:77], v[218:233]
	s_waitcnt lgkmcnt(8)
	v_mfma_f32_32x32x16_bf16 v[34:49], v[156:159], v[66:69], v[34:49]
	v_mfma_f32_32x32x16_bf16 v[50:65], v[160:163], v[66:69], v[50:65]
	s_waitcnt lgkmcnt(6)
	v_mfma_f32_32x32x16_bf16 v[34:49], v[164:167], v[82:85], v[34:49]
	v_mfma_f32_32x32x16_bf16 v[50:65], v[168:171], v[82:85], v[50:65]
	s_waitcnt lgkmcnt(4)
	v_mfma_f32_32x32x16_bf16 v[34:49], v[172:175], v[70:73], v[34:49]
	v_mfma_f32_32x32x16_bf16 v[50:65], v[176:179], v[70:73], v[50:65]
	s_waitcnt lgkmcnt(2)
	v_mfma_f32_32x32x16_bf16 v[34:49], v[180:183], v[86:89], v[34:49]
	v_mfma_f32_32x32x16_bf16 v[50:65], v[184:187], v[86:89], v[50:65]
	s_waitcnt lgkmcnt(0)
	v_mfma_f32_32x32x16_bf16 v[34:49], v[188:191], v[78:81], v[34:49]
	v_mfma_f32_32x32x16_bf16 v[50:65], v[192:195], v[78:81], v[50:65]
	ds_read_b64_tr_b16 v[196:197], v234 offset:13312
	ds_read_b64_tr_b16 v[198:199], v234 offset:14848
	ds_read_b64_tr_b16 v[200:201], v234 offset:16384
	ds_read_b64_tr_b16 v[202:203], v234 offset:17920
	ds_read_b64_tr_b16 v[204:205], v234 offset:19456
	ds_read_b64_tr_b16 v[206:207], v234 offset:20992
	ds_read_b64_tr_b16 v[214:215], v234 offset:22528
	ds_read_b64_tr_b16 v[216:217], v234 offset:24064
	s_nop 4
	v_max_f32_e32 v126, v35, v35
	v_max_f32_e32 v132, v34, v34
	v_max_f32_e32 v126, v132, v126
	v_max3_f32 v128, v36, v37, v51
	v_max3_f32 v126, v126, v50, v52
	v_max3_f32 v126, v126, v53, v38
	v_max3_f32 v128, v128, v40, v41
	v_max3_f32 v126, v126, v39, v54
	v_max3_f32 v128, v128, v56, v57
	v_max3_f32 v126, v126, v55, v42
	v_max3_f32 v128, v128, v44, v45
	v_max3_f32 v126, v126, v43, v58
	v_max3_f32 v128, v128, v60, v61
	v_max3_f32 v126, v126, v59, v46
	v_max3_f32 v128, v128, v48, v49
	v_max3_f32 v126, v126, v47, v62
	v_max3_f32 v128, v128, v64, v65
	v_max3_f32 v126, v126, v63, v128
	ds_bpermute_b32 v128, v113, v126
	s_waitcnt lgkmcnt(0)
	ds_read_b64_tr_b16 v[148:149], v234 offset:13376
	ds_read_b64_tr_b16 v[150:151], v234 offset:14912
	ds_read_b64_tr_b16 v[152:153], v234 offset:16448
	ds_read_b64_tr_b16 v[154:155], v234 offset:17984
	ds_read_b64_tr_b16 v[156:157], v234 offset:19520
	ds_read_b64_tr_b16 v[158:159], v234 offset:21056
	ds_read_b64_tr_b16 v[160:161], v234 offset:22592
	ds_read_b64_tr_b16 v[162:163], v234 offset:24128
	v_max_f32_e32 v128, v128, v128
	v_max_f32_e32 v126, v126, v128
	v_cmp_lt_f32_e32 vcc, s7, v126
	s_cbranch_vccz .LBB0_502
	v_max_f32_e32 v126, v126, v126
	v_max_f32_e32 v126, 0, v126
	v_add_f32_e32 v126, v127, v126
	v_cvt_pk_bf16_f32 v126, v126, v1
	s_nop 0
	v_lshlrev_b32_e32 v126, 16, v126
	s_and_saveexec_b64 s[10:11], s[36:37]
	s_cbranch_execz .LBB0_501
	v_xor_b32_e32 v128, 0x80000000, v126
	v_cvt_pk_bf16_f32 v128, v128, v1
	s_nop 0
	v_bfi_b32 v98, s2, v128, v98
